# phase0 prep de-serialised (16 tile loads / 9 row loads issued together) + UP epilogue counted waits
# speedup vs baseline: 1.1268x; 1.0268x over previous
.LBB0_23:
	s_or_b64 exec, exec, s[8:9]
	v_lshl_add_u32 v2, s12, 2, v26
	v_lshlrev_b64 v[24:25], 12, v[2:3]
	v_lshl_add_u64 v[68:69], v[18:19], 0, v[24:25]
	global_load_dwordx4 v[80:83], v[10:11], off
	global_load_dwordx4 v[84:87], v[68:69], off
	global_load_dwordx4 v[88:91], v[68:69], off offset:1024
	global_load_dwordx4 v[92:95], v[10:11], off offset:1024
	global_load_dwordx4 v[96:99], v[68:69], off offset:2048
	global_load_dwordx4 v[100:103], v[10:11], off offset:2048
	global_load_dwordx4 v[104:107], v[68:69], off offset:3072
	global_load_dwordx4 v[108:111], v[10:11], off offset:3072
	v_lshl_add_u64 v[112:113], v[2:3], 2, s[62:63]
	global_load_dword v114, v[112:113], off
	s_waitcnt vmcnt(0)
	v_mov_b64_e32 v[52:53], v[80:81]
	v_mov_b64_e32 v[54:55], v[82:83]
	v_mov_b64_e32 v[56:57], v[84:85]
	v_mov_b64_e32 v[58:59], v[86:87]
	v_lshlrev_b64 v[24:25], 11, v[2:3]
	v_lshl_add_u64 v[24:25], v[20:21], 0, v[24:25]
	v_cmp_lt_i32_e32 vcc, v39, v38
	v_pk_mul_f32 v[54:55], v[58:59], v[54:55]
	v_pk_mul_f32 v[52:53], v[56:57], v[52:53]
	v_and_b32_sdwa v60, v55, v47 dst_sel:DWORD dst_unused:UNUSED_PAD src0_sel:WORD_1 src1_sel:DWORD
	v_and_b32_sdwa v51, v52, v47 dst_sel:DWORD dst_unused:UNUSED_PAD src0_sel:WORD_1 src1_sel:DWORD
	v_and_b32_sdwa v61, v53, v47 dst_sel:DWORD dst_unused:UNUSED_PAD src0_sel:WORD_1 src1_sel:DWORD
	v_and_b32_sdwa v23, v54, v47 dst_sel:DWORD dst_unused:UNUSED_PAD src0_sel:WORD_1 src1_sel:DWORD
	v_add3_u32 v51, v52, v51, s3
	v_add3_u32 v52, v55, v60, s3
	v_add3_u32 v53, v53, v61, s3
	v_add3_u32 v23, v54, v23, s3
	v_and_b32_e32 v52, 0xffff0000, v52
	v_and_b32_e32 v54, 0xffff0000, v53
	v_or_b32_sdwa v53, v52, v23 dst_sel:DWORD dst_unused:UNUSED_PAD src0_sel:DWORD src1_sel:WORD_1
	v_or_b32_sdwa v52, v54, v51 dst_sel:DWORD dst_unused:UNUSED_PAD src0_sel:DWORD src1_sel:WORD_1
	global_store_dwordx2 v[24:25], v[52:53], off
	v_mov_b64_e32 v[52:53], v[88:89]
	v_mov_b64_e32 v[54:55], v[90:91]
	s_nop 0
	v_mov_b64_e32 v[60:61], v[92:93]
	v_mov_b64_e32 v[62:63], v[94:95]
	v_pk_mul_f32 v[56:57], v[56:57], v[56:57]
	v_pk_mul_f32 v[58:59], v[58:59], v[58:59]
	v_add_f32_e32 v56, v56, v57
	v_add_f32_e32 v56, v56, v58
	v_add_f32_e32 v56, v56, v59
	v_pk_mul_f32 v[62:63], v[54:55], v[62:63]
	v_pk_mul_f32 v[60:61], v[52:53], v[60:61]
	v_and_b32_sdwa v64, v63, v47 dst_sel:DWORD dst_unused:UNUSED_PAD src0_sel:WORD_1 src1_sel:DWORD
	v_and_b32_sdwa v51, v60, v47 dst_sel:DWORD dst_unused:UNUSED_PAD src0_sel:WORD_1 src1_sel:DWORD
	v_and_b32_sdwa v65, v61, v47 dst_sel:DWORD dst_unused:UNUSED_PAD src0_sel:WORD_1 src1_sel:DWORD
	v_and_b32_sdwa v23, v62, v47 dst_sel:DWORD dst_unused:UNUSED_PAD src0_sel:WORD_1 src1_sel:DWORD
	v_add3_u32 v51, v60, v51, s3
	v_add3_u32 v60, v63, v64, s3
	v_add3_u32 v61, v61, v65, s3
	v_add3_u32 v23, v62, v23, s3
	v_and_b32_e32 v60, 0xffff0000, v60
	v_and_b32_e32 v62, 0xffff0000, v61
	v_or_b32_sdwa v61, v60, v23 dst_sel:DWORD dst_unused:UNUSED_PAD src0_sel:DWORD src1_sel:WORD_1
	v_or_b32_sdwa v60, v62, v51 dst_sel:DWORD dst_unused:UNUSED_PAD src0_sel:DWORD src1_sel:WORD_1
	global_store_dwordx2 v[24:25], v[60:61], off offset:512
	v_mov_b64_e32 v[60:61], v[96:97]
	v_mov_b64_e32 v[62:63], v[98:99]
	s_nop 0
	v_mov_b64_e32 v[64:65], v[100:101]
	v_mov_b64_e32 v[66:67], v[102:103]
	v_pk_mul_f32 v[52:53], v[52:53], v[52:53]
	v_pk_mul_f32 v[54:55], v[54:55], v[54:55]
	v_add_f32_e32 v52, v52, v53
	v_add_f32_e32 v52, v52, v54
	v_add_f32_e32 v52, v52, v55
	v_add_f32_e32 v56, v56, v52
	v_pk_mul_f32 v[54:55], v[60:61], v[60:61]
	v_pk_mul_f32 v[66:67], v[62:63], v[66:67]
	v_pk_mul_f32 v[64:65], v[60:61], v[64:65]
	v_and_b32_sdwa v70, v67, v47 dst_sel:DWORD dst_unused:UNUSED_PAD src0_sel:WORD_1 src1_sel:DWORD
	v_and_b32_sdwa v51, v64, v47 dst_sel:DWORD dst_unused:UNUSED_PAD src0_sel:WORD_1 src1_sel:DWORD
	v_and_b32_sdwa v71, v65, v47 dst_sel:DWORD dst_unused:UNUSED_PAD src0_sel:WORD_1 src1_sel:DWORD
	v_and_b32_sdwa v23, v66, v47 dst_sel:DWORD dst_unused:UNUSED_PAD src0_sel:WORD_1 src1_sel:DWORD
	v_add3_u32 v51, v64, v51, s3
	v_add3_u32 v64, v67, v70, s3
	v_add3_u32 v65, v65, v71, s3
	v_add3_u32 v23, v66, v23, s3
	v_and_b32_e32 v64, 0xffff0000, v64
	v_and_b32_e32 v66, 0xffff0000, v65
	v_or_b32_sdwa v65, v64, v23 dst_sel:DWORD dst_unused:UNUSED_PAD src0_sel:DWORD src1_sel:WORD_1
	v_or_b32_sdwa v64, v66, v51 dst_sel:DWORD dst_unused:UNUSED_PAD src0_sel:DWORD src1_sel:WORD_1
	global_store_dwordx2 v[24:25], v[64:65], off offset:1024
	v_mov_b64_e32 v[64:65], v[104:105]
	v_mov_b64_e32 v[66:67], v[106:107]
	s_nop 0
	v_mov_b64_e32 v[68:69], v[108:109]
	v_mov_b64_e32 v[70:71], v[110:111]
	v_pk_mul_f32 v[52:53], v[62:63], v[62:63]
	v_add_f32_e32 v54, v54, v55
	v_add_f32_e32 v52, v54, v52
	v_add_f32_e32 v52, v52, v53
	v_add_f32_e32 v56, v56, v52
	v_cndmask_b32_e32 v23, v37, v39, vcc
	v_lshlrev_b32_e32 v23, 2, v23
	v_cmp_lt_i32_e32 vcc, v40, v38
	v_pk_mul_f32 v[54:55], v[64:65], v[64:65]
	v_pk_mul_f32 v[52:53], v[66:67], v[66:67]
	v_add_f32_e32 v54, v54, v55
	v_add_f32_e32 v52, v54, v52
	v_add_f32_e32 v52, v52, v53
	v_add_f32_e32 v52, v56, v52
	ds_bpermute_b32 v23, v23, v52
	v_cndmask_b32_e32 v51, v37, v40, vcc
	v_lshlrev_b32_e32 v51, 2, v51
	v_cmp_lt_i32_e32 vcc, v41, v38
	s_waitcnt lgkmcnt(0)
	v_add_f32_e32 v23, v52, v23
	ds_bpermute_b32 v51, v51, v23
	v_cndmask_b32_e32 v72, v37, v41, vcc
	v_lshlrev_b32_e32 v52, 2, v72
	v_cmp_lt_i32_e32 vcc, v42, v38
	s_waitcnt lgkmcnt(0)
	v_add_f32_e32 v23, v23, v51
	ds_bpermute_b32 v51, v52, v23
	v_cndmask_b32_e32 v53, v37, v42, vcc
	v_lshlrev_b32_e32 v57, 2, v53
	v_cmp_lt_i32_e32 vcc, v43, v38
	v_pk_mul_f32 v[52:53], v[66:67], v[70:71]
	s_waitcnt lgkmcnt(0)
	v_add_f32_e32 v23, v23, v51
	ds_bpermute_b32 v51, v57, v23
	v_cndmask_b32_e32 v54, v37, v43, vcc
	v_lshlrev_b32_e32 v58, 2, v54
	v_cmp_lt_i32_e32 vcc, v44, v38
	v_pk_mul_f32 v[54:55], v[64:65], v[68:69]
	s_waitcnt lgkmcnt(0)
	v_add_f32_e32 v23, v23, v51
	ds_bpermute_b32 v51, v58, v23
	v_cndmask_b32_e32 v56, v37, v44, vcc
	v_and_b32_sdwa v60, v53, v47 dst_sel:DWORD dst_unused:UNUSED_PAD src0_sel:WORD_1 src1_sel:DWORD
	v_and_b32_sdwa v61, v55, v47 dst_sel:DWORD dst_unused:UNUSED_PAD src0_sel:WORD_1 src1_sel:DWORD
	v_and_b32_sdwa v59, v52, v47 dst_sel:DWORD dst_unused:UNUSED_PAD src0_sel:WORD_1 src1_sel:DWORD
	s_waitcnt lgkmcnt(0)
	v_add_f32_e32 v23, v23, v51
	v_lshlrev_b32_e32 v51, 2, v56
	ds_bpermute_b32 v51, v51, v23
	v_and_b32_sdwa v57, v54, v47 dst_sel:DWORD dst_unused:UNUSED_PAD src0_sel:WORD_1 src1_sel:DWORD
	v_add3_u32 v53, v53, v60, s3
	v_add3_u32 v55, v55, v61, s3
	v_add3_u32 v54, v54, v57, s3
	v_add3_u32 v52, v52, v59, s3
	v_and_b32_e32 v53, 0xffff0000, v53
	v_and_b32_e32 v55, 0xffff0000, v55
	v_or_b32_sdwa v53, v53, v52 dst_sel:DWORD dst_unused:UNUSED_PAD src0_sel:DWORD src1_sel:WORD_1
	v_or_b32_sdwa v52, v55, v54 dst_sel:DWORD dst_unused:UNUSED_PAD src0_sel:DWORD src1_sel:WORD_1
	global_store_dwordx2 v[24:25], v[52:53], off offset:1536
	s_and_saveexec_b64 s[8:9], s[4:5]
	s_cbranch_execz .LBB0_25
	v_lshl_add_u64 v[24:25], v[2:3], 2, s[16:17]
	v_add_co_u32_e32 v52, vcc, 0x20000, v24
	s_waitcnt lgkmcnt(0)
	v_add_f32_e32 v23, v23, v51
	v_addc_co_u32_e32 v53, vcc, 0, v25, vcc
	global_store_dword v[52:53], v3, off
	v_add_co_u32_e32 v52, vcc, 0x40000, v24
	global_store_dword v[24:25], v23, off
	s_nop 0
	v_addc_co_u32_e32 v53, vcc, 0, v25, vcc
	v_add_co_u32_e32 v24, vcc, 0x60000, v24
	global_store_dword v[52:53], v3, off
	s_nop 0
	v_addc_co_u32_e32 v25, vcc, 0, v25, vcc
	global_store_dword v[24:25], v3, off
.LBB0_25:
	s_or_b64 exec, exec, s[8:9]
	s_and_saveexec_b64 s[22:23], s[6:7]
	s_cbranch_execz .LBB0_31
	v_lshl_add_u64 v[24:25], v[2:3], 2, s[62:63]
	v_mov_b32_e32 v23, v114
	s_brev_b32 s8, 18
	v_cvt_f32_i32_e32 v23, v23
	v_mul_f32_e32 v23, v27, v23
	v_and_b32_e32 v24, 0x7fffffff, v23
	v_cmp_nlt_f32_e64 s[8:9], |v23|, s8
	s_and_saveexec_b64 s[12:13], s[8:9]
	s_xor_b64 s[24:25], exec, s[12:13]
	s_cbranch_execz .LBB0_28
	v_lshrrev_b32_e32 v25, 23, v24
	v_add_u32_e32 v25, 0xffffff88, v25
	v_cmp_lt_u32_e32 vcc, 63, v25
	s_mov_b32 s14, 0xfe5163ab
	v_mov_b32_e32 v55, v3
	s_waitcnt lgkmcnt(0)
	v_cndmask_b32_e32 v51, 0, v48, vcc
	v_add_u32_e32 v25, v51, v25
	v_cmp_lt_u32_e64 s[8:9], 31, v25
	v_mov_b32_e32 v57, v3
	v_mov_b32_e32 v59, v3
	v_cndmask_b32_e64 v51, 0, v49, s[8:9]
	v_add_u32_e32 v25, v51, v25
	v_cmp_lt_u32_e64 s[12:13], 31, v25
	v_mov_b32_e32 v61, v3
	v_mov_b32_e32 v63, v3
	v_cndmask_b32_e64 v51, 0, v49, s[12:13]
	v_add_u32_e32 v25, v51, v25
	v_and_b32_e32 v51, 0x7fffff, v24
	v_or_b32_e32 v51, 0x800000, v51
	v_mad_u64_u32 v[52:53], s[14:15], v51, s14, 0
	v_mov_b32_e32 v54, v53
	s_mov_b32 s14, 0x3c439041
	v_mad_u64_u32 v[54:55], s[14:15], v51, s14, v[54:55]
	v_mov_b32_e32 v56, v55
	s_mov_b32 s14, 0xdb629599
	v_mad_u64_u32 v[56:57], s[14:15], v51, s14, v[56:57]
	v_mov_b32_e32 v58, v57
	s_mov_b32 s14, 0xf534ddc0
	v_mad_u64_u32 v[58:59], s[14:15], v51, s14, v[58:59]
	v_mov_b32_e32 v60, v59
	s_mov_b32 s14, 0xfc2757d1
	v_mad_u64_u32 v[60:61], s[14:15], v51, s14, v[60:61]
	v_mov_b32_e32 v62, v61
	s_mov_b32 s14, 0x4e441529
	v_mad_u64_u32 v[62:63], s[14:15], v51, s14, v[62:63]
	v_mov_b32_e32 v64, v63
	v_mov_b32_e32 v65, v3
	s_mov_b32 s14, 0xa2f9836e
	v_mad_u64_u32 v[64:65], s[14:15], v51, s14, v[64:65]
	v_cndmask_b32_e32 v53, v62, v58, vcc
	v_cndmask_b32_e32 v51, v64, v60, vcc
	v_cndmask_b32_e32 v57, v65, v62, vcc
	v_cndmask_b32_e64 v55, v51, v53, s[8:9]
	v_cndmask_b32_e64 v51, v57, v51, s[8:9]
	v_cndmask_b32_e32 v57, v60, v56, vcc
	v_cndmask_b32_e64 v53, v53, v57, s[8:9]
	v_sub_u32_e32 v59, 32, v25
	v_cmp_eq_u32_e64 s[14:15], 0, v25
	v_cndmask_b32_e32 v25, v58, v54, vcc
	v_cndmask_b32_e64 v51, v51, v55, s[12:13]
	v_cndmask_b32_e64 v55, v55, v53, s[12:13]
	v_cndmask_b32_e64 v54, v57, v25, s[8:9]
	v_alignbit_b32 v60, v51, v55, v59
	v_cndmask_b32_e64 v53, v53, v54, s[12:13]
	v_cndmask_b32_e64 v51, v60, v51, s[14:15]
	v_alignbit_b32 v57, v55, v53, v59
	v_cndmask_b32_e32 v52, v56, v52, vcc
	v_cndmask_b32_e64 v55, v57, v55, s[14:15]
	v_bfe_u32 v60, v51, 29, 1
	v_cndmask_b32_e64 v25, v25, v52, s[8:9]
	v_alignbit_b32 v57, v51, v55, 30
	v_sub_u32_e32 v61, 0, v60
	v_cndmask_b32_e64 v25, v54, v25, s[12:13]
	v_xor_b32_e32 v57, v57, v61
	v_alignbit_b32 v52, v53, v25, v59
	v_cndmask_b32_e64 v52, v52, v53, s[14:15]
	v_ffbh_u32_e32 v54, v57
	v_alignbit_b32 v53, v55, v52, 30
	v_min_u32_e32 v54, 32, v54
	v_alignbit_b32 v25, v52, v25, 30
	v_xor_b32_e32 v53, v53, v61
	v_sub_u32_e32 v55, 31, v54
	v_xor_b32_e32 v25, v25, v61
	v_alignbit_b32 v56, v57, v53, v55
	v_alignbit_b32 v25, v53, v25, v55
	v_alignbit_b32 v52, v56, v25, 9
	v_ffbh_u32_e32 v53, v52
	v_min_u32_e32 v53, 32, v53
	v_lshrrev_b32_e32 v58, 29, v51
	v_not_b32_e32 v55, v53
	v_alignbit_b32 v25, v52, v25, v55
	v_lshlrev_b32_e32 v52, 31, v58
	v_or_b32_e32 v55, 0x33000000, v52
	v_add_lshl_u32 v53, v53, v54, 23
	v_lshrrev_b32_e32 v25, 9, v25
	v_sub_u32_e32 v53, v55, v53
	v_or_b32_e32 v52, 0.5, v52
	v_lshlrev_b32_e32 v54, 23, v54
	v_or_b32_e32 v25, v53, v25
	v_lshrrev_b32_e32 v53, 9, v56
	v_sub_u32_e32 v52, v52, v54
	v_or_b32_e32 v52, v53, v52
	v_mul_f32_e32 v53, 0x3fc90fda, v52
	s_mov_b32 s8, 0x3fc90fda
	v_fma_f32 v54, v52, s8, -v53
	v_fmac_f32_e32 v54, 0x33a22168, v52
	v_fmac_f32_e32 v54, 0x3fc90fda, v25
	v_lshrrev_b32_e32 v51, 30, v51
	v_add_f32_e32 v25, v53, v54
	v_add_u32_e32 v51, v60, v51

.LBB0_47:
	v_mov_b32_e32 v80, 0
	v_mov_b32_e32 v81, 0
	v_mov_b32_e32 v82, 0
	v_mov_b32_e32 v83, 0
	v_mov_b32_e32 v84, 0
	v_mov_b32_e32 v85, 0
	v_mov_b32_e32 v86, 0
	v_mov_b32_e32 v87, 0
	v_mov_b32_e32 v88, 0
	v_mov_b32_e32 v89, 0
	v_mov_b32_e32 v90, 0
	v_mov_b32_e32 v91, 0
	v_mov_b32_e32 v92, 0
	v_mov_b32_e32 v93, 0
	v_mov_b32_e32 v94, 0
	v_mov_b32_e32 v95, 0
	s_and_saveexec_b64 s[8:9], vcc
	s_cbranch_execz .Lp0_tr_skip
	v_mad_i64_i32 v[96:97], s[30:31], s12, v2, 0
	v_lshl_add_u64 v[96:97], v[96:97], 2, v[24:25]
	s_lshl_b32 s30, s12, 4
	s_mov_b32 s31, 0
	global_load_dword v80, v[96:97], off
	v_lshl_add_u64 v[96:97], v[96:97], 0, s[30:31]
	global_load_dword v81, v[96:97], off
	v_lshl_add_u64 v[96:97], v[96:97], 0, s[30:31]
	global_load_dword v82, v[96:97], off
	v_lshl_add_u64 v[96:97], v[96:97], 0, s[30:31]
	global_load_dword v83, v[96:97], off
	v_lshl_add_u64 v[96:97], v[96:97], 0, s[30:31]
	global_load_dword v84, v[96:97], off
	v_lshl_add_u64 v[96:97], v[96:97], 0, s[30:31]
	global_load_dword v85, v[96:97], off
	v_lshl_add_u64 v[96:97], v[96:97], 0, s[30:31]
	global_load_dword v86, v[96:97], off
	v_lshl_add_u64 v[96:97], v[96:97], 0, s[30:31]
	global_load_dword v87, v[96:97], off
	v_lshl_add_u64 v[96:97], v[96:97], 0, s[30:31]
	global_load_dword v88, v[96:97], off
	v_lshl_add_u64 v[96:97], v[96:97], 0, s[30:31]
	global_load_dword v89, v[96:97], off
	v_lshl_add_u64 v[96:97], v[96:97], 0, s[30:31]
	global_load_dword v90, v[96:97], off
	v_lshl_add_u64 v[96:97], v[96:97], 0, s[30:31]
	global_load_dword v91, v[96:97], off
	v_lshl_add_u64 v[96:97], v[96:97], 0, s[30:31]
	global_load_dword v92, v[96:97], off
	v_lshl_add_u64 v[96:97], v[96:97], 0, s[30:31]
	global_load_dword v93, v[96:97], off
	v_lshl_add_u64 v[96:97], v[96:97], 0, s[30:31]
	global_load_dword v94, v[96:97], off
	v_lshl_add_u64 v[96:97], v[96:97], 0, s[30:31]
	global_load_dword v95, v[96:97], off
.Lp0_tr_skip:
	s_or_b64 exec, exec, s[8:9]
	s_waitcnt vmcnt(0)
	ds_write_b32 v23, v80
	ds_write_b32 v23, v81 offset:1040
	ds_write_b32 v23, v82 offset:2080
	ds_write_b32 v23, v83 offset:3120
	ds_write_b32 v23, v84 offset:4160
	ds_write_b32 v23, v85 offset:5200
	ds_write_b32 v23, v86 offset:6240
	ds_write_b32 v23, v87 offset:7280
	ds_write_b32 v23, v88 offset:8320
	ds_write_b32 v23, v89 offset:9360
	ds_write_b32 v23, v90 offset:10400
	ds_write_b32 v23, v91 offset:11440
	ds_write_b32 v23, v92 offset:12480
	ds_write_b32 v23, v93 offset:13520
	ds_write_b32 v23, v94 offset:14560
	ds_write_b32 v23, v95 offset:15600
	s_branch .LBB0_17

.LBB0_338:
	s_lshr_b32 s8, s13, 2
	s_and_b32 s10, s16, 56
	s_and_b32 s8, s8, 0x1ffffc0
	s_or_b32 s10, s10, s3
	s_or_b32 s8, s10, s8
	s_lshl_b32 s8, s8, 7
	s_lshl_b64 s[24:25], s[8:9], 11
	v_lshl_add_u64 v[78:79], v[68:69], 0, s[24:25]
	v_add_co_u32_e32 v80, vcc, s18, v78
	s_and_b32 s10, s14, 0xf80
	s_nop 0
	v_addc_co_u32_e32 v81, vcc, 0, v79, vcc
	s_lshl_b32 s26, s10, 11
	s_mov_b32 s27, s9
	v_add_co_u32_e32 v82, vcc, s19, v78
	v_lshl_add_u64 v[76:77], v[70:71], 0, s[26:27]
	s_nop 0
	v_addc_co_u32_e32 v83, vcc, 0, v79, vcc
	v_add_co_u32_e32 v84, vcc, s18, v76
	global_load_dwordx4 v[2:5], v[78:79], off
	global_load_dwordx4 v[6:9], v[80:81], off
	v_addc_co_u32_e32 v85, vcc, 0, v77, vcc
	v_add_co_u32_e32 v86, vcc, s19, v76
	global_load_dwordx4 v[10:13], v[82:83], off
	global_load_dwordx4 v[14:17], v[76:77], off
	v_addc_co_u32_e32 v87, vcc, 0, v77, vcc
	global_load_dwordx4 v[18:21], v[84:85], off
	global_load_dwordx4 v[22:25], v[86:87], off
	v_add_co_u32_e32 v88, vcc, s20, v76
	s_nop 1
	v_addc_co_u32_e32 v89, vcc, 0, v77, vcc
	global_load_dwordx4 v[26:29], v[88:89], off
	v_add_co_u32_e32 v90, vcc, s20, v78
	s_nop 1
	v_addc_co_u32_e32 v91, vcc, 0, v79, vcc
	global_load_dwordx4 v[30:33], v[90:91], off
	global_load_dwordx4 v[148:151], v[76:77], off offset:128
	global_load_dwordx4 v[152:155], v[84:85], off offset:128
	global_load_dwordx4 v[156:159], v[86:87], off offset:128
	global_load_dwordx4 v[160:163], v[88:89], off offset:128
	global_load_dwordx4 v[164:167], v[78:79], off offset:128
	global_load_dwordx4 v[168:171], v[80:81], off offset:128
	global_load_dwordx4 v[172:175], v[82:83], off offset:128
	global_load_dwordx4 v[176:179], v[90:91], off offset:128
	s_waitcnt vmcnt(12)
	ds_write_b128 v1, v[14:17] offset:36864
	s_waitcnt vmcnt(11)
	ds_write_b128 v1, v[18:21] offset:41472
	s_waitcnt vmcnt(10)
	ds_write_b128 v1, v[22:25] offset:46080
	s_waitcnt vmcnt(9)
	ds_write_b128 v1, v[26:29] offset:50688
	ds_write_b128 v1, v[2:5]
	ds_write_b128 v1, v[6:9] offset:4608
	ds_write_b128 v1, v[10:13] offset:9216
	s_waitcnt vmcnt(8)
	ds_write_b128 v1, v[30:33] offset:13824
	s_waitcnt lgkmcnt(0)
	s_barrier
	global_load_dwordx4 v[180:183], v[80:81], off offset:256
	global_load_dwordx4 v[184:187], v[82:83], off offset:256
	global_load_dwordx4 v[188:191], v[78:79], off offset:256
	global_load_dwordx4 v[192:195], v[76:77], off offset:256
	global_load_dwordx4 v[196:199], v[90:91], off offset:256
	global_load_dwordx4 v[200:203], v[84:85], off offset:256
	global_load_dwordx4 v[204:207], v[86:87], off offset:256
	global_load_dwordx4 v[208:211], v[88:89], off offset:256
	ds_read_b128 v[18:21], v72
	ds_read_b128 v[34:37], v73 offset:36864
	ds_read_b128 v[212:215], v72 offset:32
	ds_read_b128 v[216:219], v73 offset:36896
	ds_read_b128 v[50:53], v73 offset:41472
	ds_read_b128 v[220:223], v73 offset:41504
	ds_read_b128 v[54:57], v72 offset:4608
	ds_read_b128 v[224:227], v72 offset:4640
	s_waitcnt lgkmcnt(6)
	v_mfma_f32_32x32x16_bf16 v[2:17], v[18:21], v[34:37], 0
	s_waitcnt lgkmcnt(3)
	v_mfma_f32_32x32x16_bf16 v[18:33], v[18:21], v[50:53], 0
	s_waitcnt lgkmcnt(1)
	v_mfma_f32_32x32x16_bf16 v[34:49], v[54:57], v[34:37], 0
	v_mfma_f32_32x32x16_bf16 v[50:65], v[54:57], v[50:53], 0
	v_mfma_f32_32x32x16_bf16 v[2:17], v[212:215], v[216:219], v[2:17]
	v_mfma_f32_32x32x16_bf16 v[18:33], v[212:215], v[220:223], v[18:33]
	s_waitcnt lgkmcnt(0)
	v_mfma_f32_32x32x16_bf16 v[34:49], v[224:227], v[216:219], v[34:49]
	v_mfma_f32_32x32x16_bf16 v[50:65], v[224:227], v[220:223], v[50:65]
	ds_read_b128 v[212:215], v72 offset:64
	ds_read_b128 v[216:219], v73 offset:36928
	ds_read_b128 v[220:223], v72 offset:96
	ds_read_b128 v[224:227], v73 offset:36960
	ds_read_b128 v[228:231], v73 offset:41536
	ds_read_b128 v[232:235], v73 offset:41568
	s_waitcnt lgkmcnt(4)
	v_mfma_f32_32x32x16_bf16 v[2:17], v[212:215], v[216:219], v[2:17]
	s_waitcnt lgkmcnt(1)
	v_mfma_f32_32x32x16_bf16 v[18:33], v[212:215], v[228:231], v[18:33]
	ds_read_b128 v[212:215], v72 offset:4672
	ds_read_b128 v[236:239], v72 offset:4704
	s_waitcnt vmcnt(11)
	ds_write_b128 v1, v[164:167] offset:18432
	s_waitcnt vmcnt(10)
	ds_write_b128 v1, v[168:171] offset:23040
	s_waitcnt vmcnt(9)
	ds_write_b128 v1, v[172:175] offset:27648
	s_waitcnt vmcnt(8)
	ds_write_b128 v1, v[176:179] offset:32256
	ds_write_b128 v1, v[148:151] offset:55296
	ds_write_b128 v1, v[152:155] offset:59904
	ds_write_b128 v1, v[156:159] offset:64512
	ds_write_b128 v92, v[160:163] offset:32256
	s_waitcnt lgkmcnt(0)
	s_barrier
	global_load_dwordx4 v[148:151], v[80:81], off offset:384
	global_load_dwordx4 v[152:155], v[82:83], off offset:384
	global_load_dwordx4 v[156:159], v[78:79], off offset:384
	global_load_dwordx4 v[160:163], v[76:77], off offset:384
	global_load_dwordx4 v[164:167], v[90:91], off offset:384
	global_load_dwordx4 v[168:171], v[84:85], off offset:384
	global_load_dwordx4 v[172:175], v[86:87], off offset:384
	global_load_dwordx4 v[176:179], v[88:89], off offset:384
	v_mfma_f32_32x32x16_bf16 v[34:49], v[212:215], v[216:219], v[34:49]
	v_mfma_f32_32x32x16_bf16 v[50:65], v[212:215], v[228:231], v[50:65]
	v_mfma_f32_32x32x16_bf16 v[2:17], v[220:223], v[224:227], v[2:17]
	v_mfma_f32_32x32x16_bf16 v[18:33], v[220:223], v[232:235], v[18:33]
	v_mfma_f32_32x32x16_bf16 v[34:49], v[236:239], v[224:227], v[34:49]
	v_mfma_f32_32x32x16_bf16 v[50:65], v[236:239], v[232:235], v[50:65]
	ds_read_b128 v[212:215], v72 offset:18432
	ds_read_b128 v[216:219], v73 offset:55296
	ds_read_b128 v[220:223], v72 offset:18464
	ds_read_b128 v[224:227], v73 offset:55328
	ds_read_b128 v[228:231], v73 offset:59904
	ds_read_b128 v[232:235], v73 offset:59936
	s_waitcnt lgkmcnt(4)
	v_mfma_f32_32x32x16_bf16 v[2:17], v[212:215], v[216:219], v[2:17]
	s_waitcnt lgkmcnt(1)
	v_mfma_f32_32x32x16_bf16 v[18:33], v[212:215], v[228:231], v[18:33]
	ds_read_b128 v[212:215], v72 offset:23040
	ds_read_b128 v[236:239], v72 offset:23072
	s_waitcnt lgkmcnt(1)
	v_mfma_f32_32x32x16_bf16 v[34:49], v[212:215], v[216:219], v[34:49]
	v_mfma_f32_32x32x16_bf16 v[50:65], v[212:215], v[228:231], v[50:65]
	v_mfma_f32_32x32x16_bf16 v[2:17], v[220:223], v[224:227], v[2:17]
	v_mfma_f32_32x32x16_bf16 v[18:33], v[220:223], v[232:235], v[18:33]
	s_waitcnt lgkmcnt(0)
	v_mfma_f32_32x32x16_bf16 v[34:49], v[236:239], v[224:227], v[34:49]
	ds_read_b128 v[212:215], v72 offset:18496
	ds_read_b128 v[216:219], v73 offset:55360
	ds_read_b128 v[220:223], v72 offset:18528
	ds_read_b128 v[224:227], v73 offset:55392
	v_mfma_f32_32x32x16_bf16 v[50:65], v[236:239], v[232:235], v[50:65]
	ds_read_b128 v[228:231], v73 offset:59968
	ds_read_b128 v[232:235], v73 offset:60000
	s_waitcnt lgkmcnt(4)
	v_mfma_f32_32x32x16_bf16 v[2:17], v[212:215], v[216:219], v[2:17]
	s_waitcnt lgkmcnt(1)
	v_mfma_f32_32x32x16_bf16 v[18:33], v[212:215], v[228:231], v[18:33]
	ds_read_b128 v[212:215], v72 offset:23104
	ds_read_b128 v[236:239], v72 offset:23136
	s_waitcnt vmcnt(13)
	ds_write_b128 v1, v[188:191]
	ds_write_b128 v1, v[180:183] offset:4608
	ds_write_b128 v1, v[184:187] offset:9216
	s_waitcnt vmcnt(11)
	ds_write_b128 v1, v[196:199] offset:13824
	ds_write_b128 v1, v[192:195] offset:36864
	s_waitcnt vmcnt(10)
	ds_write_b128 v1, v[200:203] offset:41472
	s_waitcnt vmcnt(9)
	ds_write_b128 v1, v[204:207] offset:46080
	s_waitcnt vmcnt(8)
	ds_write_b128 v1, v[208:211] offset:50688
	s_waitcnt lgkmcnt(0)
	s_barrier
	global_load_dwordx4 v[180:183], v[80:81], off offset:512
	global_load_dwordx4 v[184:187], v[82:83], off offset:512
	global_load_dwordx4 v[188:191], v[78:79], off offset:512
	global_load_dwordx4 v[192:195], v[76:77], off offset:512
	global_load_dwordx4 v[196:199], v[90:91], off offset:512
	global_load_dwordx4 v[200:203], v[84:85], off offset:512
	global_load_dwordx4 v[204:207], v[86:87], off offset:512
	global_load_dwordx4 v[208:211], v[88:89], off offset:512
	v_mfma_f32_32x32x16_bf16 v[34:49], v[212:215], v[216:219], v[34:49]
	v_mfma_f32_32x32x16_bf16 v[50:65], v[212:215], v[228:231], v[50:65]
	v_mfma_f32_32x32x16_bf16 v[2:17], v[220:223], v[224:227], v[2:17]
	v_mfma_f32_32x32x16_bf16 v[18:33], v[220:223], v[232:235], v[18:33]
	v_mfma_f32_32x32x16_bf16 v[34:49], v[236:239], v[224:227], v[34:49]
	v_mfma_f32_32x32x16_bf16 v[50:65], v[236:239], v[232:235], v[50:65]
	ds_read_b128 v[212:215], v72
	ds_read_b128 v[216:219], v73 offset:36864
	ds_read_b128 v[220:223], v72 offset:32
	ds_read_b128 v[224:227], v73 offset:36896
	ds_read_b128 v[228:231], v73 offset:41472
	ds_read_b128 v[232:235], v73 offset:41504
	s_waitcnt lgkmcnt(4)
	v_mfma_f32_32x32x16_bf16 v[2:17], v[212:215], v[216:219], v[2:17]
	s_waitcnt lgkmcnt(1)
	v_mfma_f32_32x32x16_bf16 v[18:33], v[212:215], v[228:231], v[18:33]
	ds_read_b128 v[212:215], v72 offset:4608
	ds_read_b128 v[236:239], v72 offset:4640
	s_waitcnt lgkmcnt(1)
	v_mfma_f32_32x32x16_bf16 v[34:49], v[212:215], v[216:219], v[34:49]
	v_mfma_f32_32x32x16_bf16 v[50:65], v[212:215], v[228:231], v[50:65]
	v_mfma_f32_32x32x16_bf16 v[2:17], v[220:223], v[224:227], v[2:17]
	v_mfma_f32_32x32x16_bf16 v[18:33], v[220:223], v[232:235], v[18:33]
	s_waitcnt lgkmcnt(0)
	v_mfma_f32_32x32x16_bf16 v[34:49], v[236:239], v[224:227], v[34:49]
	ds_read_b128 v[212:215], v72 offset:64
	ds_read_b128 v[216:219], v73 offset:36928
	ds_read_b128 v[220:223], v72 offset:96
	ds_read_b128 v[224:227], v73 offset:36960
	v_mfma_f32_32x32x16_bf16 v[50:65], v[236:239], v[232:235], v[50:65]
	ds_read_b128 v[228:231], v73 offset:41536
	ds_read_b128 v[232:235], v73 offset:41568
	s_waitcnt lgkmcnt(4)
	v_mfma_f32_32x32x16_bf16 v[2:17], v[212:215], v[216:219], v[2:17]
	s_waitcnt lgkmcnt(1)
	v_mfma_f32_32x32x16_bf16 v[18:33], v[212:215], v[228:231], v[18:33]
	ds_read_b128 v[212:215], v72 offset:4672
	ds_read_b128 v[236:239], v72 offset:4704
	s_waitcnt vmcnt(13)
	ds_write_b128 v1, v[156:159] offset:18432
	ds_write_b128 v1, v[148:151] offset:23040
	ds_write_b128 v1, v[152:155] offset:27648
	s_waitcnt vmcnt(11)
	ds_write_b128 v1, v[164:167] offset:32256
	ds_write_b128 v1, v[160:163] offset:55296
	s_waitcnt vmcnt(10)
	ds_write_b128 v1, v[168:171] offset:59904
	s_waitcnt vmcnt(9)
	ds_write_b128 v1, v[172:175] offset:64512
	s_waitcnt vmcnt(8)
	ds_write_b128 v92, v[176:179] offset:32256
	s_waitcnt lgkmcnt(0)
	s_barrier
	global_load_dwordx4 v[148:151], v[80:81], off offset:640
	global_load_dwordx4 v[152:155], v[82:83], off offset:640
	global_load_dwordx4 v[156:159], v[78:79], off offset:640
	global_load_dwordx4 v[160:163], v[76:77], off offset:640
	global_load_dwordx4 v[164:167], v[90:91], off offset:640
	global_load_dwordx4 v[168:171], v[84:85], off offset:640
	global_load_dwordx4 v[172:175], v[86:87], off offset:640
	global_load_dwordx4 v[176:179], v[88:89], off offset:640
	v_mfma_f32_32x32x16_bf16 v[34:49], v[212:215], v[216:219], v[34:49]
	v_mfma_f32_32x32x16_bf16 v[50:65], v[212:215], v[228:231], v[50:65]
	v_mfma_f32_32x32x16_bf16 v[2:17], v[220:223], v[224:227], v[2:17]
	v_mfma_f32_32x32x16_bf16 v[18:33], v[220:223], v[232:235], v[18:33]
	v_mfma_f32_32x32x16_bf16 v[34:49], v[236:239], v[224:227], v[34:49]
	v_mfma_f32_32x32x16_bf16 v[50:65], v[236:239], v[232:235], v[50:65]
	ds_read_b128 v[212:215], v72 offset:18432
	ds_read_b128 v[216:219], v73 offset:55296
	ds_read_b128 v[220:223], v72 offset:18464
	ds_read_b128 v[224:227], v73 offset:55328
	ds_read_b128 v[228:231], v73 offset:59904
	ds_read_b128 v[232:235], v73 offset:59936
	s_waitcnt lgkmcnt(4)
	v_mfma_f32_32x32x16_bf16 v[2:17], v[212:215], v[216:219], v[2:17]
	s_waitcnt lgkmcnt(1)
	v_mfma_f32_32x32x16_bf16 v[18:33], v[212:215], v[228:231], v[18:33]
	ds_read_b128 v[212:215], v72 offset:23040
	ds_read_b128 v[236:239], v72 offset:23072
	s_waitcnt lgkmcnt(1)
	v_mfma_f32_32x32x16_bf16 v[34:49], v[212:215], v[216:219], v[34:49]
	v_mfma_f32_32x32x16_bf16 v[50:65], v[212:215], v[228:231], v[50:65]
	v_mfma_f32_32x32x16_bf16 v[2:17], v[220:223], v[224:227], v[2:17]
	v_mfma_f32_32x32x16_bf16 v[18:33], v[220:223], v[232:235], v[18:33]
	s_waitcnt lgkmcnt(0)
	v_mfma_f32_32x32x16_bf16 v[34:49], v[236:239], v[224:227], v[34:49]
	ds_read_b128 v[212:215], v72 offset:18496
	ds_read_b128 v[216:219], v73 offset:55360
	ds_read_b128 v[220:223], v72 offset:18528
	ds_read_b128 v[224:227], v73 offset:55392
	v_mfma_f32_32x32x16_bf16 v[50:65], v[236:239], v[232:235], v[50:65]
	ds_read_b128 v[228:231], v73 offset:59968
	ds_read_b128 v[232:235], v73 offset:60000
	s_waitcnt lgkmcnt(4)
	v_mfma_f32_32x32x16_bf16 v[2:17], v[212:215], v[216:219], v[2:17]
	s_waitcnt lgkmcnt(1)
	v_mfma_f32_32x32x16_bf16 v[18:33], v[212:215], v[228:231], v[18:33]
	ds_read_b128 v[212:215], v72 offset:23104
	ds_read_b128 v[236:239], v72 offset:23136
	s_waitcnt vmcnt(13)
	ds_write_b128 v1, v[188:191]
	ds_write_b128 v1, v[180:183] offset:4608
	ds_write_b128 v1, v[184:187] offset:9216
	s_waitcnt vmcnt(11)
	ds_write_b128 v1, v[196:199] offset:13824
	ds_write_b128 v1, v[192:195] offset:36864
	s_waitcnt vmcnt(10)
	ds_write_b128 v1, v[200:203] offset:41472
	s_waitcnt vmcnt(9)
	ds_write_b128 v1, v[204:207] offset:46080
	s_waitcnt vmcnt(8)
	ds_write_b128 v1, v[208:211] offset:50688
	s_waitcnt lgkmcnt(0)
	s_barrier
	global_load_dwordx4 v[180:183], v[80:81], off offset:768
	global_load_dwordx4 v[184:187], v[82:83], off offset:768
	global_load_dwordx4 v[188:191], v[78:79], off offset:768
	global_load_dwordx4 v[192:195], v[76:77], off offset:768
	global_load_dwordx4 v[196:199], v[90:91], off offset:768
	global_load_dwordx4 v[200:203], v[84:85], off offset:768
	global_load_dwordx4 v[204:207], v[86:87], off offset:768
	global_load_dwordx4 v[208:211], v[88:89], off offset:768
	v_mfma_f32_32x32x16_bf16 v[34:49], v[212:215], v[216:219], v[34:49]
	v_mfma_f32_32x32x16_bf16 v[50:65], v[212:215], v[228:231], v[50:65]
	v_mfma_f32_32x32x16_bf16 v[2:17], v[220:223], v[224:227], v[2:17]
	v_mfma_f32_32x32x16_bf16 v[18:33], v[220:223], v[232:235], v[18:33]
	v_mfma_f32_32x32x16_bf16 v[34:49], v[236:239], v[224:227], v[34:49]
	v_mfma_f32_32x32x16_bf16 v[50:65], v[236:239], v[232:235], v[50:65]
	ds_read_b128 v[212:215], v72
	ds_read_b128 v[216:219], v73 offset:36864
	ds_read_b128 v[220:223], v72 offset:32
	ds_read_b128 v[224:227], v73 offset:36896
	ds_read_b128 v[228:231], v73 offset:41472
	ds_read_b128 v[232:235], v73 offset:41504
	s_waitcnt lgkmcnt(4)
	v_mfma_f32_32x32x16_bf16 v[2:17], v[212:215], v[216:219], v[2:17]
	s_waitcnt lgkmcnt(1)
	v_mfma_f32_32x32x16_bf16 v[18:33], v[212:215], v[228:231], v[18:33]
	ds_read_b128 v[212:215], v72 offset:4608
	ds_read_b128 v[236:239], v72 offset:4640
	s_waitcnt lgkmcnt(1)
	v_mfma_f32_32x32x16_bf16 v[34:49], v[212:215], v[216:219], v[34:49]
	v_mfma_f32_32x32x16_bf16 v[50:65], v[212:215], v[228:231], v[50:65]
	v_mfma_f32_32x32x16_bf16 v[2:17], v[220:223], v[224:227], v[2:17]
	v_mfma_f32_32x32x16_bf16 v[18:33], v[220:223], v[232:235], v[18:33]
	s_waitcnt lgkmcnt(0)
	v_mfma_f32_32x32x16_bf16 v[34:49], v[236:239], v[224:227], v[34:49]
	ds_read_b128 v[212:215], v72 offset:64
	ds_read_b128 v[216:219], v73 offset:36928
	ds_read_b128 v[220:223], v72 offset:96
	ds_read_b128 v[224:227], v73 offset:36960
	v_mfma_f32_32x32x16_bf16 v[50:65], v[236:239], v[232:235], v[50:65]
	ds_read_b128 v[228:231], v73 offset:41536
	ds_read_b128 v[232:235], v73 offset:41568
	s_waitcnt lgkmcnt(4)
	v_mfma_f32_32x32x16_bf16 v[2:17], v[212:215], v[216:219], v[2:17]
	s_waitcnt lgkmcnt(1)
	v_mfma_f32_32x32x16_bf16 v[18:33], v[212:215], v[228:231], v[18:33]
	ds_read_b128 v[212:215], v72 offset:4672
	ds_read_b128 v[236:239], v72 offset:4704
	s_waitcnt vmcnt(13)
	ds_write_b128 v1, v[156:159] offset:18432
	ds_write_b128 v1, v[148:151] offset:23040
	ds_write_b128 v1, v[152:155] offset:27648
	s_waitcnt vmcnt(11)
	ds_write_b128 v1, v[164:167] offset:32256
	ds_write_b128 v1, v[160:163] offset:55296
	s_waitcnt vmcnt(10)
	ds_write_b128 v1, v[168:171] offset:59904
	s_waitcnt vmcnt(9)
	ds_write_b128 v1, v[172:175] offset:64512
	s_waitcnt vmcnt(8)
	ds_write_b128 v92, v[176:179] offset:32256
	s_waitcnt lgkmcnt(0)
	s_barrier
	global_load_dwordx4 v[148:151], v[80:81], off offset:896
	global_load_dwordx4 v[152:155], v[82:83], off offset:896
	global_load_dwordx4 v[156:159], v[78:79], off offset:896
	global_load_dwordx4 v[160:163], v[76:77], off offset:896
	global_load_dwordx4 v[164:167], v[90:91], off offset:896
	global_load_dwordx4 v[168:171], v[84:85], off offset:896
	global_load_dwordx4 v[172:175], v[86:87], off offset:896
	global_load_dwordx4 v[176:179], v[88:89], off offset:896
	v_mfma_f32_32x32x16_bf16 v[34:49], v[212:215], v[216:219], v[34:49]
	v_mfma_f32_32x32x16_bf16 v[50:65], v[212:215], v[228:231], v[50:65]
	v_mfma_f32_32x32x16_bf16 v[2:17], v[220:223], v[224:227], v[2:17]
	v_mfma_f32_32x32x16_bf16 v[18:33], v[220:223], v[232:235], v[18:33]
	v_mfma_f32_32x32x16_bf16 v[34:49], v[236:239], v[224:227], v[34:49]
	v_mfma_f32_32x32x16_bf16 v[50:65], v[236:239], v[232:235], v[50:65]
	ds_read_b128 v[212:215], v72 offset:18432
	ds_read_b128 v[216:219], v73 offset:55296
	ds_read_b128 v[220:223], v72 offset:18464
	ds_read_b128 v[224:227], v73 offset:55328
	ds_read_b128 v[228:231], v73 offset:59904
	ds_read_b128 v[232:235], v73 offset:59936
	s_waitcnt lgkmcnt(4)
	v_mfma_f32_32x32x16_bf16 v[2:17], v[212:215], v[216:219], v[2:17]
	s_waitcnt lgkmcnt(1)
	v_mfma_f32_32x32x16_bf16 v[18:33], v[212:215], v[228:231], v[18:33]
	ds_read_b128 v[212:215], v72 offset:23040
	ds_read_b128 v[236:239], v72 offset:23072
	s_waitcnt lgkmcnt(1)
	v_mfma_f32_32x32x16_bf16 v[34:49], v[212:215], v[216:219], v[34:49]
	v_mfma_f32_32x32x16_bf16 v[50:65], v[212:215], v[228:231], v[50:65]
	v_mfma_f32_32x32x16_bf16 v[2:17], v[220:223], v[224:227], v[2:17]
	v_mfma_f32_32x32x16_bf16 v[18:33], v[220:223], v[232:235], v[18:33]
	s_waitcnt lgkmcnt(0)
	v_mfma_f32_32x32x16_bf16 v[34:49], v[236:239], v[224:227], v[34:49]
	ds_read_b128 v[212:215], v72 offset:18496
	ds_read_b128 v[216:219], v73 offset:55360
	ds_read_b128 v[220:223], v72 offset:18528
	ds_read_b128 v[224:227], v73 offset:55392
	v_mfma_f32_32x32x16_bf16 v[50:65], v[236:239], v[232:235], v[50:65]
	ds_read_b128 v[228:231], v73 offset:59968
	ds_read_b128 v[232:235], v73 offset:60000
	s_waitcnt lgkmcnt(4)
	v_mfma_f32_32x32x16_bf16 v[2:17], v[212:215], v[216:219], v[2:17]
	s_waitcnt lgkmcnt(1)
	v_mfma_f32_32x32x16_bf16 v[18:33], v[212:215], v[228:231], v[18:33]
	ds_read_b128 v[212:215], v72 offset:23104
	ds_read_b128 v[236:239], v72 offset:23136
	s_waitcnt vmcnt(13)
	ds_write_b128 v1, v[188:191]
	ds_write_b128 v1, v[180:183] offset:4608
	ds_write_b128 v1, v[184:187] offset:9216
	s_waitcnt vmcnt(11)
	ds_write_b128 v1, v[196:199] offset:13824
	ds_write_b128 v1, v[192:195] offset:36864
	s_waitcnt vmcnt(10)
	ds_write_b128 v1, v[200:203] offset:41472
	s_waitcnt vmcnt(9)
	ds_write_b128 v1, v[204:207] offset:46080
	s_waitcnt vmcnt(8)
	ds_write_b128 v1, v[208:211] offset:50688
	s_waitcnt lgkmcnt(0)
	s_barrier
	global_load_dwordx4 v[180:183], v[80:81], off offset:1024
	global_load_dwordx4 v[184:187], v[82:83], off offset:1024
	global_load_dwordx4 v[188:191], v[78:79], off offset:1024
	global_load_dwordx4 v[192:195], v[76:77], off offset:1024
	global_load_dwordx4 v[196:199], v[90:91], off offset:1024
	global_load_dwordx4 v[200:203], v[84:85], off offset:1024
	global_load_dwordx4 v[204:207], v[86:87], off offset:1024
	global_load_dwordx4 v[208:211], v[88:89], off offset:1024
	v_mfma_f32_32x32x16_bf16 v[34:49], v[212:215], v[216:219], v[34:49]
	v_mfma_f32_32x32x16_bf16 v[50:65], v[212:215], v[228:231], v[50:65]
	v_mfma_f32_32x32x16_bf16 v[2:17], v[220:223], v[224:227], v[2:17]
	v_mfma_f32_32x32x16_bf16 v[18:33], v[220:223], v[232:235], v[18:33]
	v_mfma_f32_32x32x16_bf16 v[34:49], v[236:239], v[224:227], v[34:49]
	v_mfma_f32_32x32x16_bf16 v[50:65], v[236:239], v[232:235], v[50:65]
	ds_read_b128 v[212:215], v72
	ds_read_b128 v[216:219], v73 offset:36864
	ds_read_b128 v[220:223], v72 offset:32
	ds_read_b128 v[224:227], v73 offset:36896
	ds_read_b128 v[228:231], v73 offset:41472
	ds_read_b128 v[232:235], v73 offset:41504
	s_waitcnt lgkmcnt(4)
	v_mfma_f32_32x32x16_bf16 v[2:17], v[212:215], v[216:219], v[2:17]
	s_waitcnt lgkmcnt(1)
	v_mfma_f32_32x32x16_bf16 v[18:33], v[212:215], v[228:231], v[18:33]
	ds_read_b128 v[212:215], v72 offset:4608
	ds_read_b128 v[236:239], v72 offset:4640
	s_waitcnt lgkmcnt(1)
	v_mfma_f32_32x32x16_bf16 v[34:49], v[212:215], v[216:219], v[34:49]
	v_mfma_f32_32x32x16_bf16 v[50:65], v[212:215], v[228:231], v[50:65]
	v_mfma_f32_32x32x16_bf16 v[2:17], v[220:223], v[224:227], v[2:17]
	v_mfma_f32_32x32x16_bf16 v[18:33], v[220:223], v[232:235], v[18:33]
	s_waitcnt lgkmcnt(0)
	v_mfma_f32_32x32x16_bf16 v[34:49], v[236:239], v[224:227], v[34:49]
	ds_read_b128 v[212:215], v72 offset:64
	ds_read_b128 v[216:219], v73 offset:36928
	ds_read_b128 v[220:223], v72 offset:96
	ds_read_b128 v[224:227], v73 offset:36960
	v_mfma_f32_32x32x16_bf16 v[50:65], v[236:239], v[232:235], v[50:65]
	ds_read_b128 v[228:231], v73 offset:41536
	ds_read_b128 v[232:235], v73 offset:41568
	s_waitcnt lgkmcnt(4)
	v_mfma_f32_32x32x16_bf16 v[2:17], v[212:215], v[216:219], v[2:17]
	s_waitcnt lgkmcnt(1)
	v_mfma_f32_32x32x16_bf16 v[18:33], v[212:215], v[228:231], v[18:33]
	ds_read_b128 v[212:215], v72 offset:4672
	ds_read_b128 v[236:239], v72 offset:4704
	s_waitcnt vmcnt(13)
	ds_write_b128 v1, v[156:159] offset:18432
	ds_write_b128 v1, v[148:151] offset:23040
	ds_write_b128 v1, v[152:155] offset:27648
	s_waitcnt vmcnt(11)
	ds_write_b128 v1, v[164:167] offset:32256
	ds_write_b128 v1, v[160:163] offset:55296
	s_waitcnt vmcnt(10)
	ds_write_b128 v1, v[168:171] offset:59904
	s_waitcnt vmcnt(9)
	ds_write_b128 v1, v[172:175] offset:64512
	s_waitcnt vmcnt(8)
	ds_write_b128 v92, v[176:179] offset:32256
	s_waitcnt lgkmcnt(0)
	s_barrier
	global_load_dwordx4 v[148:151], v[80:81], off offset:1152
	global_load_dwordx4 v[152:155], v[82:83], off offset:1152
	global_load_dwordx4 v[156:159], v[78:79], off offset:1152
	global_load_dwordx4 v[160:163], v[76:77], off offset:1152
	global_load_dwordx4 v[164:167], v[90:91], off offset:1152
	global_load_dwordx4 v[168:171], v[84:85], off offset:1152
	global_load_dwordx4 v[172:175], v[86:87], off offset:1152
	global_load_dwordx4 v[176:179], v[88:89], off offset:1152
	v_mfma_f32_32x32x16_bf16 v[34:49], v[212:215], v[216:219], v[34:49]
	v_mfma_f32_32x32x16_bf16 v[50:65], v[212:215], v[228:231], v[50:65]
	v_mfma_f32_32x32x16_bf16 v[2:17], v[220:223], v[224:227], v[2:17]
	v_mfma_f32_32x32x16_bf16 v[18:33], v[220:223], v[232:235], v[18:33]
	v_mfma_f32_32x32x16_bf16 v[34:49], v[236:239], v[224:227], v[34:49]
	v_mfma_f32_32x32x16_bf16 v[50:65], v[236:239], v[232:235], v[50:65]
	ds_read_b128 v[212:215], v72 offset:18432
	ds_read_b128 v[216:219], v73 offset:55296
	ds_read_b128 v[220:223], v72 offset:18464
	ds_read_b128 v[224:227], v73 offset:55328
	ds_read_b128 v[228:231], v73 offset:59904
	ds_read_b128 v[232:235], v73 offset:59936
	s_waitcnt lgkmcnt(4)
	v_mfma_f32_32x32x16_bf16 v[2:17], v[212:215], v[216:219], v[2:17]
	s_waitcnt lgkmcnt(1)
	v_mfma_f32_32x32x16_bf16 v[18:33], v[212:215], v[228:231], v[18:33]
	ds_read_b128 v[212:215], v72 offset:23040
	ds_read_b128 v[236:239], v72 offset:23072
	s_waitcnt lgkmcnt(1)
	v_mfma_f32_32x32x16_bf16 v[34:49], v[212:215], v[216:219], v[34:49]
	v_mfma_f32_32x32x16_bf16 v[50:65], v[212:215], v[228:231], v[50:65]
	v_mfma_f32_32x32x16_bf16 v[2:17], v[220:223], v[224:227], v[2:17]
	v_mfma_f32_32x32x16_bf16 v[18:33], v[220:223], v[232:235], v[18:33]
	s_waitcnt lgkmcnt(0)
	v_mfma_f32_32x32x16_bf16 v[34:49], v[236:239], v[224:227], v[34:49]
	ds_read_b128 v[212:215], v72 offset:18496
	ds_read_b128 v[216:219], v73 offset:55360
	ds_read_b128 v[220:223], v72 offset:18528
	ds_read_b128 v[224:227], v73 offset:55392
	v_mfma_f32_32x32x16_bf16 v[50:65], v[236:239], v[232:235], v[50:65]
	ds_read_b128 v[228:231], v73 offset:59968
	ds_read_b128 v[232:235], v73 offset:60000
	s_waitcnt lgkmcnt(4)
	v_mfma_f32_32x32x16_bf16 v[2:17], v[212:215], v[216:219], v[2:17]
	s_waitcnt lgkmcnt(1)
	v_mfma_f32_32x32x16_bf16 v[18:33], v[212:215], v[228:231], v[18:33]
	ds_read_b128 v[212:215], v72 offset:23104
	ds_read_b128 v[236:239], v72 offset:23136
	s_waitcnt vmcnt(13)
	ds_write_b128 v1, v[188:191]
	ds_write_b128 v1, v[180:183] offset:4608
	ds_write_b128 v1, v[184:187] offset:9216
	s_waitcnt vmcnt(11)
	ds_write_b128 v1, v[196:199] offset:13824
	ds_write_b128 v1, v[192:195] offset:36864
	s_waitcnt vmcnt(10)
	ds_write_b128 v1, v[200:203] offset:41472
	s_waitcnt vmcnt(9)
	ds_write_b128 v1, v[204:207] offset:46080
	s_waitcnt vmcnt(8)
	ds_write_b128 v1, v[208:211] offset:50688
	s_waitcnt lgkmcnt(0)
	s_barrier
	global_load_dwordx4 v[180:183], v[80:81], off offset:1280
	global_load_dwordx4 v[184:187], v[82:83], off offset:1280
	global_load_dwordx4 v[188:191], v[78:79], off offset:1280
	global_load_dwordx4 v[192:195], v[76:77], off offset:1280
	global_load_dwordx4 v[196:199], v[90:91], off offset:1280
	global_load_dwordx4 v[200:203], v[84:85], off offset:1280
	global_load_dwordx4 v[204:207], v[86:87], off offset:1280
	global_load_dwordx4 v[208:211], v[88:89], off offset:1280
	v_mfma_f32_32x32x16_bf16 v[34:49], v[212:215], v[216:219], v[34:49]
	v_mfma_f32_32x32x16_bf16 v[50:65], v[212:215], v[228:231], v[50:65]
	v_mfma_f32_32x32x16_bf16 v[2:17], v[220:223], v[224:227], v[2:17]
	v_mfma_f32_32x32x16_bf16 v[18:33], v[220:223], v[232:235], v[18:33]
	v_mfma_f32_32x32x16_bf16 v[34:49], v[236:239], v[224:227], v[34:49]
	v_mfma_f32_32x32x16_bf16 v[50:65], v[236:239], v[232:235], v[50:65]
	ds_read_b128 v[212:215], v72
	ds_read_b128 v[216:219], v73 offset:36864
	ds_read_b128 v[220:223], v72 offset:32
	ds_read_b128 v[224:227], v73 offset:36896
	ds_read_b128 v[228:231], v73 offset:41472
	ds_read_b128 v[232:235], v73 offset:41504
	s_waitcnt lgkmcnt(4)
	v_mfma_f32_32x32x16_bf16 v[2:17], v[212:215], v[216:219], v[2:17]
	s_waitcnt lgkmcnt(1)
	v_mfma_f32_32x32x16_bf16 v[18:33], v[212:215], v[228:231], v[18:33]
	ds_read_b128 v[212:215], v72 offset:4608
	ds_read_b128 v[236:239], v72 offset:4640
	s_waitcnt lgkmcnt(1)
	v_mfma_f32_32x32x16_bf16 v[34:49], v[212:215], v[216:219], v[34:49]
	v_mfma_f32_32x32x16_bf16 v[50:65], v[212:215], v[228:231], v[50:65]
	v_mfma_f32_32x32x16_bf16 v[2:17], v[220:223], v[224:227], v[2:17]
	v_mfma_f32_32x32x16_bf16 v[18:33], v[220:223], v[232:235], v[18:33]
	s_waitcnt lgkmcnt(0)
	v_mfma_f32_32x32x16_bf16 v[34:49], v[236:239], v[224:227], v[34:49]
	ds_read_b128 v[212:215], v72 offset:64
	ds_read_b128 v[216:219], v73 offset:36928
	ds_read_b128 v[220:223], v72 offset:96
	ds_read_b128 v[224:227], v73 offset:36960
	v_mfma_f32_32x32x16_bf16 v[50:65], v[236:239], v[232:235], v[50:65]
	ds_read_b128 v[228:231], v73 offset:41536
	ds_read_b128 v[232:235], v73 offset:41568
	s_waitcnt lgkmcnt(4)
	v_mfma_f32_32x32x16_bf16 v[2:17], v[212:215], v[216:219], v[2:17]
	s_waitcnt lgkmcnt(1)
	v_mfma_f32_32x32x16_bf16 v[18:33], v[212:215], v[228:231], v[18:33]
	ds_read_b128 v[212:215], v72 offset:4672
	ds_read_b128 v[236:239], v72 offset:4704
	s_waitcnt vmcnt(13)
	ds_write_b128 v1, v[156:159] offset:18432
	ds_write_b128 v1, v[148:151] offset:23040
	ds_write_b128 v1, v[152:155] offset:27648
	s_waitcnt vmcnt(11)
	ds_write_b128 v1, v[164:167] offset:32256
	ds_write_b128 v1, v[160:163] offset:55296
	s_waitcnt vmcnt(10)
	ds_write_b128 v1, v[168:171] offset:59904
	s_waitcnt vmcnt(9)
	ds_write_b128 v1, v[172:175] offset:64512
	s_waitcnt vmcnt(8)
	ds_write_b128 v92, v[176:179] offset:32256
	s_waitcnt lgkmcnt(0)
	s_barrier
	global_load_dwordx4 v[148:151], v[80:81], off offset:1408
	global_load_dwordx4 v[152:155], v[82:83], off offset:1408
	global_load_dwordx4 v[156:159], v[78:79], off offset:1408
	global_load_dwordx4 v[160:163], v[76:77], off offset:1408
	global_load_dwordx4 v[164:167], v[90:91], off offset:1408
	global_load_dwordx4 v[168:171], v[84:85], off offset:1408
	global_load_dwordx4 v[172:175], v[86:87], off offset:1408
	global_load_dwordx4 v[176:179], v[88:89], off offset:1408
	v_mfma_f32_32x32x16_bf16 v[34:49], v[212:215], v[216:219], v[34:49]
	v_mfma_f32_32x32x16_bf16 v[50:65], v[212:215], v[228:231], v[50:65]
	v_mfma_f32_32x32x16_bf16 v[2:17], v[220:223], v[224:227], v[2:17]
	v_mfma_f32_32x32x16_bf16 v[18:33], v[220:223], v[232:235], v[18:33]
	v_mfma_f32_32x32x16_bf16 v[34:49], v[236:239], v[224:227], v[34:49]
	v_mfma_f32_32x32x16_bf16 v[50:65], v[236:239], v[232:235], v[50:65]
	ds_read_b128 v[212:215], v72 offset:18432
	ds_read_b128 v[216:219], v73 offset:55296
	ds_read_b128 v[220:223], v72 offset:18464
	ds_read_b128 v[224:227], v73 offset:55328
	ds_read_b128 v[228:231], v73 offset:59904
	ds_read_b128 v[232:235], v73 offset:59936
	s_waitcnt lgkmcnt(4)
	v_mfma_f32_32x32x16_bf16 v[2:17], v[212:215], v[216:219], v[2:17]
	s_waitcnt lgkmcnt(1)
	v_mfma_f32_32x32x16_bf16 v[18:33], v[212:215], v[228:231], v[18:33]
	ds_read_b128 v[212:215], v72 offset:23040
	ds_read_b128 v[236:239], v72 offset:23072
	s_waitcnt lgkmcnt(1)
	v_mfma_f32_32x32x16_bf16 v[34:49], v[212:215], v[216:219], v[34:49]
	v_mfma_f32_32x32x16_bf16 v[50:65], v[212:215], v[228:231], v[50:65]
	v_mfma_f32_32x32x16_bf16 v[2:17], v[220:223], v[224:227], v[2:17]
	v_mfma_f32_32x32x16_bf16 v[18:33], v[220:223], v[232:235], v[18:33]
	s_waitcnt lgkmcnt(0)
	v_mfma_f32_32x32x16_bf16 v[34:49], v[236:239], v[224:227], v[34:49]
	ds_read_b128 v[212:215], v72 offset:18496
	ds_read_b128 v[216:219], v73 offset:55360
	ds_read_b128 v[220:223], v72 offset:18528
	ds_read_b128 v[224:227], v73 offset:55392
	v_mfma_f32_32x32x16_bf16 v[50:65], v[236:239], v[232:235], v[50:65]
	ds_read_b128 v[228:231], v73 offset:59968
	ds_read_b128 v[232:235], v73 offset:60000
	s_waitcnt lgkmcnt(4)
	v_mfma_f32_32x32x16_bf16 v[2:17], v[212:215], v[216:219], v[2:17]
	s_waitcnt lgkmcnt(1)
	v_mfma_f32_32x32x16_bf16 v[18:33], v[212:215], v[228:231], v[18:33]
	ds_read_b128 v[212:215], v72 offset:23104
	ds_read_b128 v[236:239], v72 offset:23136
	s_waitcnt vmcnt(13)
	ds_write_b128 v1, v[188:191]
	ds_write_b128 v1, v[180:183] offset:4608
	ds_write_b128 v1, v[184:187] offset:9216
	s_waitcnt vmcnt(11)
	ds_write_b128 v1, v[196:199] offset:13824
	ds_write_b128 v1, v[192:195] offset:36864
	s_waitcnt vmcnt(10)
	ds_write_b128 v1, v[200:203] offset:41472
	s_waitcnt vmcnt(9)
	ds_write_b128 v1, v[204:207] offset:46080
	s_waitcnt vmcnt(8)
	ds_write_b128 v1, v[208:211] offset:50688
	s_waitcnt lgkmcnt(0)
	s_barrier
	global_load_dwordx4 v[180:183], v[80:81], off offset:1536
	global_load_dwordx4 v[184:187], v[82:83], off offset:1536
	global_load_dwordx4 v[188:191], v[78:79], off offset:1536
	global_load_dwordx4 v[192:195], v[76:77], off offset:1536
	global_load_dwordx4 v[196:199], v[90:91], off offset:1536
	global_load_dwordx4 v[200:203], v[84:85], off offset:1536
	global_load_dwordx4 v[204:207], v[86:87], off offset:1536
	global_load_dwordx4 v[208:211], v[88:89], off offset:1536
	v_mfma_f32_32x32x16_bf16 v[34:49], v[212:215], v[216:219], v[34:49]
	v_mfma_f32_32x32x16_bf16 v[50:65], v[212:215], v[228:231], v[50:65]
	v_mfma_f32_32x32x16_bf16 v[2:17], v[220:223], v[224:227], v[2:17]
	v_mfma_f32_32x32x16_bf16 v[18:33], v[220:223], v[232:235], v[18:33]
	v_mfma_f32_32x32x16_bf16 v[34:49], v[236:239], v[224:227], v[34:49]
	v_mfma_f32_32x32x16_bf16 v[50:65], v[236:239], v[232:235], v[50:65]
	ds_read_b128 v[212:215], v72
	ds_read_b128 v[216:219], v73 offset:36864
	ds_read_b128 v[220:223], v72 offset:32
	ds_read_b128 v[224:227], v73 offset:36896
	ds_read_b128 v[228:231], v73 offset:41472
	ds_read_b128 v[232:235], v73 offset:41504
	s_waitcnt lgkmcnt(4)
	v_mfma_f32_32x32x16_bf16 v[2:17], v[212:215], v[216:219], v[2:17]
	s_waitcnt lgkmcnt(1)
	v_mfma_f32_32x32x16_bf16 v[18:33], v[212:215], v[228:231], v[18:33]
	ds_read_b128 v[212:215], v72 offset:4608
	ds_read_b128 v[236:239], v72 offset:4640
	s_waitcnt lgkmcnt(1)
	v_mfma_f32_32x32x16_bf16 v[34:49], v[212:215], v[216:219], v[34:49]
	v_mfma_f32_32x32x16_bf16 v[50:65], v[212:215], v[228:231], v[50:65]
	v_mfma_f32_32x32x16_bf16 v[2:17], v[220:223], v[224:227], v[2:17]
	v_mfma_f32_32x32x16_bf16 v[18:33], v[220:223], v[232:235], v[18:33]
	s_waitcnt lgkmcnt(0)
	v_mfma_f32_32x32x16_bf16 v[34:49], v[236:239], v[224:227], v[34:49]
	ds_read_b128 v[212:215], v72 offset:64
	ds_read_b128 v[216:219], v73 offset:36928
	ds_read_b128 v[220:223], v72 offset:96
	ds_read_b128 v[224:227], v73 offset:36960
	v_mfma_f32_32x32x16_bf16 v[50:65], v[236:239], v[232:235], v[50:65]
	ds_read_b128 v[228:231], v73 offset:41536
	ds_read_b128 v[232:235], v73 offset:41568
	s_waitcnt lgkmcnt(4)
	v_mfma_f32_32x32x16_bf16 v[2:17], v[212:215], v[216:219], v[2:17]
	s_waitcnt lgkmcnt(1)
	v_mfma_f32_32x32x16_bf16 v[18:33], v[212:215], v[228:231], v[18:33]
	ds_read_b128 v[212:215], v72 offset:4672
	ds_read_b128 v[236:239], v72 offset:4704
	s_waitcnt vmcnt(13)
	ds_write_b128 v1, v[156:159] offset:18432
	ds_write_b128 v1, v[148:151] offset:23040
	ds_write_b128 v1, v[152:155] offset:27648
	s_waitcnt vmcnt(11)
	ds_write_b128 v1, v[164:167] offset:32256
	ds_write_b128 v1, v[160:163] offset:55296
	s_waitcnt vmcnt(10)
	ds_write_b128 v1, v[168:171] offset:59904
	s_waitcnt vmcnt(9)
	ds_write_b128 v1, v[172:175] offset:64512
	s_waitcnt vmcnt(8)
	ds_write_b128 v92, v[176:179] offset:32256
	s_waitcnt lgkmcnt(0)
	s_barrier
	global_load_dwordx4 v[148:151], v[80:81], off offset:1664
	global_load_dwordx4 v[152:155], v[82:83], off offset:1664
	global_load_dwordx4 v[156:159], v[78:79], off offset:1664
	global_load_dwordx4 v[160:163], v[76:77], off offset:1664
	global_load_dwordx4 v[164:167], v[90:91], off offset:1664
	global_load_dwordx4 v[168:171], v[84:85], off offset:1664
	global_load_dwordx4 v[172:175], v[86:87], off offset:1664
	global_load_dwordx4 v[176:179], v[88:89], off offset:1664
	v_mfma_f32_32x32x16_bf16 v[34:49], v[212:215], v[216:219], v[34:49]
	v_mfma_f32_32x32x16_bf16 v[50:65], v[212:215], v[228:231], v[50:65]
	v_mfma_f32_32x32x16_bf16 v[2:17], v[220:223], v[224:227], v[2:17]
	v_mfma_f32_32x32x16_bf16 v[18:33], v[220:223], v[232:235], v[18:33]
	v_mfma_f32_32x32x16_bf16 v[34:49], v[236:239], v[224:227], v[34:49]
	v_mfma_f32_32x32x16_bf16 v[50:65], v[236:239], v[232:235], v[50:65]
	ds_read_b128 v[212:215], v72 offset:18432
	ds_read_b128 v[216:219], v73 offset:55296
	ds_read_b128 v[220:223], v72 offset:18464
	ds_read_b128 v[224:227], v73 offset:55328
	ds_read_b128 v[228:231], v73 offset:59904
	ds_read_b128 v[232:235], v73 offset:59936
	s_waitcnt lgkmcnt(4)
	v_mfma_f32_32x32x16_bf16 v[2:17], v[212:215], v[216:219], v[2:17]
	s_waitcnt lgkmcnt(1)
	v_mfma_f32_32x32x16_bf16 v[18:33], v[212:215], v[228:231], v[18:33]
	ds_read_b128 v[212:215], v72 offset:23040
	ds_read_b128 v[236:239], v72 offset:23072
	s_waitcnt lgkmcnt(1)
	v_mfma_f32_32x32x16_bf16 v[34:49], v[212:215], v[216:219], v[34:49]
	v_mfma_f32_32x32x16_bf16 v[50:65], v[212:215], v[228:231], v[50:65]
	v_mfma_f32_32x32x16_bf16 v[2:17], v[220:223], v[224:227], v[2:17]
	v_mfma_f32_32x32x16_bf16 v[18:33], v[220:223], v[232:235], v[18:33]
	s_waitcnt lgkmcnt(0)
	v_mfma_f32_32x32x16_bf16 v[34:49], v[236:239], v[224:227], v[34:49]
	ds_read_b128 v[212:215], v72 offset:18496
	ds_read_b128 v[216:219], v73 offset:55360
	ds_read_b128 v[220:223], v72 offset:18528
	ds_read_b128 v[224:227], v73 offset:55392
	v_mfma_f32_32x32x16_bf16 v[50:65], v[236:239], v[232:235], v[50:65]
	ds_read_b128 v[228:231], v73 offset:59968
	ds_read_b128 v[232:235], v73 offset:60000
	s_waitcnt lgkmcnt(4)
	v_mfma_f32_32x32x16_bf16 v[2:17], v[212:215], v[216:219], v[2:17]
	s_waitcnt lgkmcnt(1)
	v_mfma_f32_32x32x16_bf16 v[18:33], v[212:215], v[228:231], v[18:33]
	ds_read_b128 v[212:215], v72 offset:23104
	ds_read_b128 v[236:239], v72 offset:23136
	s_waitcnt vmcnt(13)
	ds_write_b128 v1, v[188:191]
	ds_write_b128 v1, v[180:183] offset:4608
	ds_write_b128 v1, v[184:187] offset:9216
	s_waitcnt vmcnt(11)
	ds_write_b128 v1, v[196:199] offset:13824
	ds_write_b128 v1, v[192:195] offset:36864
	s_waitcnt vmcnt(10)
	ds_write_b128 v1, v[200:203] offset:41472
	s_waitcnt vmcnt(9)
	ds_write_b128 v1, v[204:207] offset:46080
	s_waitcnt vmcnt(8)
	ds_write_b128 v1, v[208:211] offset:50688
	s_waitcnt lgkmcnt(0)
	s_barrier
	global_load_dwordx4 v[180:183], v[80:81], off offset:1792
	global_load_dwordx4 v[184:187], v[82:83], off offset:1792
	global_load_dwordx4 v[188:191], v[78:79], off offset:1792
	global_load_dwordx4 v[192:195], v[76:77], off offset:1792
	global_load_dwordx4 v[196:199], v[90:91], off offset:1792
	global_load_dwordx4 v[200:203], v[84:85], off offset:1792
	global_load_dwordx4 v[204:207], v[86:87], off offset:1792
	global_load_dwordx4 v[208:211], v[88:89], off offset:1792
	v_mfma_f32_32x32x16_bf16 v[34:49], v[212:215], v[216:219], v[34:49]
	v_mfma_f32_32x32x16_bf16 v[50:65], v[212:215], v[228:231], v[50:65]
	v_mfma_f32_32x32x16_bf16 v[2:17], v[220:223], v[224:227], v[2:17]
	v_mfma_f32_32x32x16_bf16 v[18:33], v[220:223], v[232:235], v[18:33]
	v_mfma_f32_32x32x16_bf16 v[34:49], v[236:239], v[224:227], v[34:49]
	v_mfma_f32_32x32x16_bf16 v[50:65], v[236:239], v[232:235], v[50:65]
	ds_read_b128 v[212:215], v72
	ds_read_b128 v[216:219], v73 offset:36864
	ds_read_b128 v[220:223], v72 offset:32
	ds_read_b128 v[224:227], v73 offset:36896
	ds_read_b128 v[228:231], v73 offset:41472
	ds_read_b128 v[232:235], v73 offset:41504
	s_waitcnt lgkmcnt(4)
	v_mfma_f32_32x32x16_bf16 v[2:17], v[212:215], v[216:219], v[2:17]
	s_waitcnt lgkmcnt(1)
	v_mfma_f32_32x32x16_bf16 v[18:33], v[212:215], v[228:231], v[18:33]
	ds_read_b128 v[212:215], v72 offset:4608
	ds_read_b128 v[236:239], v72 offset:4640
	s_waitcnt lgkmcnt(1)
	v_mfma_f32_32x32x16_bf16 v[34:49], v[212:215], v[216:219], v[34:49]
	v_mfma_f32_32x32x16_bf16 v[50:65], v[212:215], v[228:231], v[50:65]
	v_mfma_f32_32x32x16_bf16 v[2:17], v[220:223], v[224:227], v[2:17]
	v_mfma_f32_32x32x16_bf16 v[18:33], v[220:223], v[232:235], v[18:33]
	s_waitcnt lgkmcnt(0)
	v_mfma_f32_32x32x16_bf16 v[34:49], v[236:239], v[224:227], v[34:49]
	ds_read_b128 v[212:215], v72 offset:64
	ds_read_b128 v[216:219], v73 offset:36928
	ds_read_b128 v[220:223], v72 offset:96
	ds_read_b128 v[224:227], v73 offset:36960
	v_mfma_f32_32x32x16_bf16 v[50:65], v[236:239], v[232:235], v[50:65]
	ds_read_b128 v[228:231], v73 offset:41536
	ds_read_b128 v[232:235], v73 offset:41568
	s_waitcnt lgkmcnt(4)
	v_mfma_f32_32x32x16_bf16 v[2:17], v[212:215], v[216:219], v[2:17]
	s_waitcnt lgkmcnt(1)
	v_mfma_f32_32x32x16_bf16 v[18:33], v[212:215], v[228:231], v[18:33]
	ds_read_b128 v[212:215], v72 offset:4672
	ds_read_b128 v[236:239], v72 offset:4704
	s_waitcnt vmcnt(13)
	ds_write_b128 v1, v[156:159] offset:18432
	ds_write_b128 v1, v[148:151] offset:23040
	ds_write_b128 v1, v[152:155] offset:27648
	s_waitcnt vmcnt(11)
	ds_write_b128 v1, v[164:167] offset:32256
	ds_write_b128 v1, v[160:163] offset:55296
	s_waitcnt vmcnt(10)
	ds_write_b128 v1, v[168:171] offset:59904
	s_waitcnt vmcnt(9)
	ds_write_b128 v1, v[172:175] offset:64512
	s_waitcnt vmcnt(8)
	ds_write_b128 v92, v[176:179] offset:32256
	s_waitcnt lgkmcnt(0)
	s_barrier
	global_load_dwordx4 v[148:151], v[80:81], off offset:1920
	s_nop 0
	global_load_dwordx4 v[80:83], v[82:83], off offset:1920
	s_nop 0
	global_load_dwordx4 v[152:155], v[78:79], off offset:1920
	s_nop 0
	global_load_dwordx4 v[76:79], v[76:77], off offset:1920
	s_nop 0
	global_load_dwordx4 v[156:159], v[90:91], off offset:1920
	global_load_dwordx4 v[160:163], v[84:85], off offset:1920
	s_nop 0
	global_load_dwordx4 v[84:87], v[86:87], off offset:1920
	s_nop 0
	global_load_dwordx4 v[88:91], v[88:89], off offset:1920
	v_mfma_f32_32x32x16_bf16 v[34:49], v[212:215], v[216:219], v[34:49]
	v_mfma_f32_32x32x16_bf16 v[50:65], v[212:215], v[228:231], v[50:65]
	v_mfma_f32_32x32x16_bf16 v[2:17], v[220:223], v[224:227], v[2:17]
	v_mfma_f32_32x32x16_bf16 v[18:33], v[220:223], v[232:235], v[18:33]
	v_mfma_f32_32x32x16_bf16 v[34:49], v[236:239], v[224:227], v[34:49]
	v_mfma_f32_32x32x16_bf16 v[50:65], v[236:239], v[232:235], v[50:65]
	ds_read_b128 v[164:167], v72 offset:18432
	ds_read_b128 v[168:171], v73 offset:55296
	ds_read_b128 v[172:175], v72 offset:18464
	ds_read_b128 v[176:179], v73 offset:55328
	ds_read_b128 v[212:215], v73 offset:59904
	ds_read_b128 v[216:219], v73 offset:59936
	s_waitcnt lgkmcnt(4)
	v_mfma_f32_32x32x16_bf16 v[2:17], v[164:167], v[168:171], v[2:17]
	s_waitcnt lgkmcnt(1)
	v_mfma_f32_32x32x16_bf16 v[18:33], v[164:167], v[212:215], v[18:33]
	ds_read_b128 v[164:167], v72 offset:23040
	ds_read_b128 v[220:223], v72 offset:23072
	s_waitcnt lgkmcnt(1)
	v_mfma_f32_32x32x16_bf16 v[34:49], v[164:167], v[168:171], v[34:49]
	v_mfma_f32_32x32x16_bf16 v[50:65], v[164:167], v[212:215], v[50:65]
	v_mfma_f32_32x32x16_bf16 v[2:17], v[172:175], v[176:179], v[2:17]
	v_mfma_f32_32x32x16_bf16 v[18:33], v[172:175], v[216:219], v[18:33]
	s_waitcnt lgkmcnt(0)
	v_mfma_f32_32x32x16_bf16 v[34:49], v[220:223], v[176:179], v[34:49]
	ds_read_b128 v[164:167], v72 offset:18496
	ds_read_b128 v[168:171], v73 offset:55360
	ds_read_b128 v[172:175], v72 offset:18528
	ds_read_b128 v[176:179], v73 offset:55392
	v_mfma_f32_32x32x16_bf16 v[50:65], v[220:223], v[216:219], v[50:65]
	ds_read_b128 v[212:215], v73 offset:59968
	ds_read_b128 v[216:219], v73 offset:60000
	s_waitcnt lgkmcnt(4)
	v_mfma_f32_32x32x16_bf16 v[2:17], v[164:167], v[168:171], v[2:17]
	s_waitcnt lgkmcnt(1)
	v_mfma_f32_32x32x16_bf16 v[18:33], v[164:167], v[212:215], v[18:33]
	ds_read_b128 v[164:167], v72 offset:23104
	ds_read_b128 v[220:223], v72 offset:23136
	s_waitcnt vmcnt(13)
	ds_write_b128 v1, v[188:191]
	ds_write_b128 v1, v[180:183] offset:4608
	ds_write_b128 v1, v[184:187] offset:9216
	s_waitcnt vmcnt(11)
	ds_write_b128 v1, v[196:199] offset:13824
	ds_write_b128 v1, v[192:195] offset:36864
	s_waitcnt vmcnt(10)
	ds_write_b128 v1, v[200:203] offset:41472
	s_waitcnt vmcnt(9)
	ds_write_b128 v1, v[204:207] offset:46080
	s_waitcnt vmcnt(8)
	ds_write_b128 v1, v[208:211] offset:50688
	s_waitcnt lgkmcnt(0)
	s_barrier
	v_mfma_f32_32x32x16_bf16 v[34:49], v[164:167], v[168:171], v[34:49]
	v_mfma_f32_32x32x16_bf16 v[50:65], v[164:167], v[212:215], v[50:65]
	v_mfma_f32_32x32x16_bf16 v[2:17], v[172:175], v[176:179], v[2:17]
	v_mfma_f32_32x32x16_bf16 v[18:33], v[172:175], v[216:219], v[18:33]
	v_mfma_f32_32x32x16_bf16 v[34:49], v[220:223], v[176:179], v[34:49]
	v_mfma_f32_32x32x16_bf16 v[50:65], v[220:223], v[216:219], v[50:65]
	ds_read_b128 v[164:167], v72
	ds_read_b128 v[168:171], v73 offset:36864
	ds_read_b128 v[172:175], v72 offset:32
	ds_read_b128 v[176:179], v73 offset:36896
	ds_read_b128 v[180:183], v73 offset:41472
	ds_read_b128 v[184:187], v73 offset:41504
	s_waitcnt lgkmcnt(4)
	v_mfma_f32_32x32x16_bf16 v[2:17], v[164:167], v[168:171], v[2:17]
	s_waitcnt lgkmcnt(1)
	v_mfma_f32_32x32x16_bf16 v[18:33], v[164:167], v[180:183], v[18:33]
	ds_read_b128 v[164:167], v72 offset:4608
	ds_read_b128 v[188:191], v72 offset:4640
	s_waitcnt lgkmcnt(1)
	v_mfma_f32_32x32x16_bf16 v[34:49], v[164:167], v[168:171], v[34:49]
	v_mfma_f32_32x32x16_bf16 v[50:65], v[164:167], v[180:183], v[50:65]
	v_mfma_f32_32x32x16_bf16 v[2:17], v[172:175], v[176:179], v[2:17]
	v_mfma_f32_32x32x16_bf16 v[18:33], v[172:175], v[184:187], v[18:33]
	s_waitcnt lgkmcnt(0)
	v_mfma_f32_32x32x16_bf16 v[34:49], v[188:191], v[176:179], v[34:49]
	ds_read_b128 v[164:167], v72 offset:64
	ds_read_b128 v[168:171], v73 offset:36928
	ds_read_b128 v[172:175], v72 offset:96
	ds_read_b128 v[176:179], v73 offset:36960
	v_mfma_f32_32x32x16_bf16 v[50:65], v[188:191], v[184:187], v[50:65]
	ds_read_b128 v[180:183], v73 offset:41536
	ds_read_b128 v[184:187], v73 offset:41568
	s_waitcnt lgkmcnt(4)
	v_mfma_f32_32x32x16_bf16 v[2:17], v[164:167], v[168:171], v[2:17]
	s_waitcnt lgkmcnt(1)
	v_mfma_f32_32x32x16_bf16 v[18:33], v[164:167], v[180:183], v[18:33]
	ds_read_b128 v[164:167], v72 offset:4672
	ds_read_b128 v[188:191], v72 offset:4704
	s_waitcnt vmcnt(5)
	ds_write_b128 v1, v[152:155] offset:18432
	ds_write_b128 v1, v[148:151] offset:23040
	ds_write_b128 v1, v[80:83] offset:27648
	s_waitcnt vmcnt(3)
	ds_write_b128 v1, v[156:159] offset:32256
	ds_write_b128 v1, v[76:79] offset:55296
	s_waitcnt vmcnt(2)
	ds_write_b128 v1, v[160:163] offset:59904
	s_waitcnt vmcnt(1)
	ds_write_b128 v1, v[84:87] offset:64512
	s_waitcnt vmcnt(0)
	ds_write_b128 v92, v[88:91] offset:32256
	s_waitcnt lgkmcnt(0)
	s_barrier
	v_mfma_f32_32x32x16_bf16 v[34:49], v[164:167], v[168:171], v[34:49]
	v_mfma_f32_32x32x16_bf16 v[50:65], v[164:167], v[180:183], v[50:65]
	v_mfma_f32_32x32x16_bf16 v[2:17], v[172:175], v[176:179], v[2:17]
	v_mfma_f32_32x32x16_bf16 v[18:33], v[172:175], v[184:187], v[18:33]
	v_mfma_f32_32x32x16_bf16 v[34:49], v[188:191], v[176:179], v[34:49]
	v_mfma_f32_32x32x16_bf16 v[50:65], v[188:191], v[184:187], v[50:65]
	ds_read_b128 v[76:79], v72 offset:18432
	ds_read_b128 v[80:83], v73 offset:55296
	ds_read_b128 v[84:87], v72 offset:18464
	ds_read_b128 v[88:91], v73 offset:55328
	ds_read_b128 v[148:151], v73 offset:59904
	ds_read_b128 v[152:155], v73 offset:59936
	v_or_b32_e32 v66, s8, v93
	s_waitcnt lgkmcnt(4)
	v_mfma_f32_32x32x16_bf16 v[2:17], v[76:79], v[80:83], v[2:17]
	s_lshl_b32 s10, s10, 1
	s_mov_b32 s11, s9
	s_add_i32 s13, s13, s12
	s_add_i32 s14, s14, s15
	s_add_i32 s16, s16, s17
	s_cmpk_lt_u32 s13, 0x400
	s_waitcnt lgkmcnt(1)
	v_mfma_f32_32x32x16_bf16 v[18:33], v[76:79], v[148:151], v[18:33]
	ds_read_b128 v[76:79], v72 offset:23040
	ds_read_b128 v[156:159], v72 offset:23072
	s_waitcnt lgkmcnt(1)
	v_mfma_f32_32x32x16_bf16 v[34:49], v[76:79], v[80:83], v[34:49]
	v_mfma_f32_32x32x16_bf16 v[50:65], v[76:79], v[148:151], v[50:65]
	v_mfma_f32_32x32x16_bf16 v[2:17], v[84:87], v[88:91], v[2:17]
	v_mfma_f32_32x32x16_bf16 v[18:33], v[84:87], v[152:155], v[18:33]
	s_waitcnt lgkmcnt(0)
	v_mfma_f32_32x32x16_bf16 v[34:49], v[156:159], v[88:91], v[34:49]
	ds_read_b128 v[76:79], v72 offset:18496
	ds_read_b128 v[80:83], v73 offset:55360
	ds_read_b128 v[84:87], v72 offset:18528
	ds_read_b128 v[88:91], v73 offset:55392
	v_mfma_f32_32x32x16_bf16 v[50:65], v[156:159], v[152:155], v[50:65]
	ds_read_b128 v[148:151], v73 offset:59968
	ds_read_b128 v[152:155], v73 offset:60000
	s_waitcnt lgkmcnt(4)
	v_mfma_f32_32x32x16_bf16 v[2:17], v[76:79], v[80:83], v[2:17]
	s_waitcnt lgkmcnt(1)
	v_mfma_f32_32x32x16_bf16 v[18:33], v[76:79], v[148:151], v[18:33]
	ds_read_b128 v[76:79], v72 offset:23104
	ds_read_b128 v[156:159], v72 offset:23136
	s_waitcnt lgkmcnt(0)
	s_barrier
	v_mfma_f32_32x32x16_bf16 v[34:49], v[76:79], v[80:83], v[34:49]
	v_mfma_f32_32x32x16_bf16 v[50:65], v[76:79], v[148:151], v[50:65]
	v_mfma_f32_32x32x16_bf16 v[2:17], v[84:87], v[88:91], v[2:17]
	v_mfma_f32_32x32x16_bf16 v[18:33], v[84:87], v[152:155], v[18:33]
	v_mfma_f32_32x32x16_bf16 v[34:49], v[156:159], v[88:91], v[34:49]
	s_nop 10
	ds_write2_b32 v101, v2, v18 offset1:32
	v_mfma_f32_32x32x16_bf16 v[50:65], v[156:159], v[152:155], v[50:65]
	s_nop 11
	ds_write2_b32 v132, v34, v50 offset0:32 offset1:64
	ds_write2_b32 v101, v3, v19 offset0:129 offset1:161
	ds_write2_b32 v132, v35, v51 offset0:161 offset1:193
	ds_write2_b32 v133, v4, v20 offset0:2 offset1:34
	ds_write2_b32 v134, v36, v52 offset0:34 offset1:66
	ds_write2_b32 v133, v5, v21 offset0:131 offset1:163
	ds_write2_b32 v134, v37, v53 offset0:163 offset1:195
	ds_write2_b32 v135, v6, v22 offset0:8 offset1:40
	ds_write2_b32 v136, v38, v54 offset0:40 offset1:72
	ds_write2_b32 v135, v7, v23 offset0:137 offset1:169
	ds_write2_b32 v136, v39, v55 offset0:169 offset1:201
	ds_write2_b32 v137, v8, v24 offset0:10 offset1:42
	ds_write2_b32 v138, v40, v56 offset0:42 offset1:74
	ds_write2_b32 v137, v9, v25 offset0:139 offset1:171
	ds_write2_b32 v138, v41, v57 offset0:171 offset1:203
	ds_write2_b32 v139, v10, v26 offset0:16 offset1:48
	ds_write2_b32 v140, v42, v58 offset0:48 offset1:80
	ds_write2_b32 v139, v11, v27 offset0:145 offset1:177
	ds_write2_b32 v140, v43, v59 offset0:177 offset1:209
	ds_write2_b32 v141, v12, v28 offset0:18 offset1:50
	ds_write2_b32 v142, v44, v60 offset0:50 offset1:82
	ds_write2_b32 v141, v13, v29 offset0:147 offset1:179
	ds_write2_b32 v142, v45, v61 offset0:179 offset1:211
	ds_write2_b32 v143, v14, v30 offset0:24 offset1:56
	ds_write2_b32 v144, v46, v62 offset0:56 offset1:88
	ds_write2_b32 v143, v15, v31 offset0:153 offset1:185
	ds_write2_b32 v144, v47, v63 offset0:185 offset1:217
	ds_write2_b32 v145, v16, v32 offset0:26 offset1:58
	ds_write2_b32 v146, v48, v64 offset0:58 offset1:90
	ds_write2_b32 v145, v17, v33 offset0:155 offset1:187
	ds_write2_b32 v146, v49, v65 offset0:187 offset1:219
	v_lshl_add_u64 v[2:3], v[66:67], 2, s[6:7]
	s_waitcnt lgkmcnt(0)
	s_barrier
	v_mov_b32_e32 v2, v66
	v_lshlrev_b32_e32 v3, 2, v2
	global_load_dword v5, v3, s[6:7]
	global_load_dword v6, v3, s[6:7] offset:64
	global_load_dword v7, v3, s[6:7] offset:128
	global_load_dword v8, v3, s[6:7] offset:192
	global_load_dword v9, v3, s[6:7] offset:256
	global_load_dword v10, v3, s[6:7] offset:320
	global_load_dword v11, v3, s[6:7] offset:384
	global_load_dword v12, v3, s[6:7] offset:448
	v_lshlrev_b32_e32 v4, 13, v2
	v_add3_u32 v4, v4, v74, s10
	s_movk_i32 s24, 0x7fff
	v_mov_b32_e32 v59, 1
	v_mov_b32_e32 v13, 0x358637bd
	ds_read2_b32 v[14:15], v103 offset0:0 offset1:1
	ds_read2_b32 v[16:17], v103 offset0:2 offset1:3
	ds_read2_b32 v[18:19], v103 offset0:4 offset1:5
	ds_read2_b32 v[20:21], v103 offset0:6 offset1:7
	v_add_u32_e32 v56, 0x2040, v103
	ds_read2_b32 v[22:23], v56 offset0:0 offset1:1
	ds_read2_b32 v[24:25], v56 offset0:2 offset1:3
	ds_read2_b32 v[26:27], v56 offset0:4 offset1:5
	ds_read2_b32 v[28:29], v56 offset0:6 offset1:7
	s_waitcnt vmcnt(7) lgkmcnt(4)
	v_fmamk_f32 v54, v5, 0x3a800000, v13
	v_rsq_f32_e32 v54, v54
	s_nop 0
	v_mul_f32_e32 v14, v14, v54
	v_mul_f32_e32 v15, v15, v54
	v_mul_f32_e32 v16, v16, v54
	v_mul_f32_e32 v17, v17, v54
	v_mul_f32_e32 v18, v18, v54
	v_mul_f32_e32 v19, v19, v54
	v_mul_f32_e32 v20, v20, v54
	v_mul_f32_e32 v21, v21, v54
	v_max_f32_e32 v14, 0, v14
	v_max_f32_e32 v15, 0, v15
	v_max_f32_e32 v16, 0, v16
	v_max_f32_e32 v17, 0, v17
	v_max_f32_e32 v18, 0, v18
	v_max_f32_e32 v19, 0, v19
	v_max_f32_e32 v20, 0, v20
	v_max_f32_e32 v21, 0, v21
	v_pk_mul_f32 v[14:15], v[14:15], v[14:15]
	v_pk_mul_f32 v[16:17], v[16:17], v[16:17]
	v_pk_mul_f32 v[18:19], v[18:19], v[18:19]
	v_pk_mul_f32 v[20:21], v[20:21], v[20:21]
	v_and_b32_sdwa v46, v14, v59 dst_sel:DWORD dst_unused:UNUSED_PAD src0_sel:WORD_1 src1_sel:DWORD
	v_and_b32_sdwa v47, v15, v59 dst_sel:DWORD dst_unused:UNUSED_PAD src0_sel:WORD_1 src1_sel:DWORD
	v_and_b32_sdwa v48, v16, v59 dst_sel:DWORD dst_unused:UNUSED_PAD src0_sel:WORD_1 src1_sel:DWORD
	v_and_b32_sdwa v49, v17, v59 dst_sel:DWORD dst_unused:UNUSED_PAD src0_sel:WORD_1 src1_sel:DWORD
	v_and_b32_sdwa v50, v18, v59 dst_sel:DWORD dst_unused:UNUSED_PAD src0_sel:WORD_1 src1_sel:DWORD
	v_and_b32_sdwa v51, v19, v59 dst_sel:DWORD dst_unused:UNUSED_PAD src0_sel:WORD_1 src1_sel:DWORD
	v_and_b32_sdwa v52, v20, v59 dst_sel:DWORD dst_unused:UNUSED_PAD src0_sel:WORD_1 src1_sel:DWORD
	v_and_b32_sdwa v53, v21, v59 dst_sel:DWORD dst_unused:UNUSED_PAD src0_sel:WORD_1 src1_sel:DWORD
	v_add3_u32 v14, v14, v46, s24
	v_add3_u32 v15, v15, v47, s24
	v_add3_u32 v16, v16, v48, s24
	v_add3_u32 v17, v17, v49, s24
	v_add3_u32 v18, v18, v50, s24
	v_add3_u32 v19, v19, v51, s24
	v_add3_u32 v20, v20, v52, s24
	v_add3_u32 v21, v21, v53, s24
	v_and_b32_e32 v15, 0xffff0000, v15
	v_and_b32_e32 v17, 0xffff0000, v17
	v_and_b32_e32 v19, 0xffff0000, v19
	v_and_b32_e32 v21, 0xffff0000, v21
	v_or_b32_sdwa v60, v15, v14 dst_sel:DWORD dst_unused:UNUSED_PAD src0_sel:DWORD src1_sel:WORD_1
	v_or_b32_sdwa v61, v17, v16 dst_sel:DWORD dst_unused:UNUSED_PAD src0_sel:DWORD src1_sel:WORD_1
	v_or_b32_sdwa v62, v19, v18 dst_sel:DWORD dst_unused:UNUSED_PAD src0_sel:DWORD src1_sel:WORD_1
	v_or_b32_sdwa v63, v21, v20 dst_sel:DWORD dst_unused:UNUSED_PAD src0_sel:DWORD src1_sel:WORD_1
	global_store_dwordx4 v4, v[60:63], s[56:57]
	v_add_u32_e32 v55, 0x4080, v103
	ds_read2_b32 v[30:31], v55 offset0:0 offset1:1
	ds_read2_b32 v[32:33], v55 offset0:2 offset1:3
	ds_read2_b32 v[34:35], v55 offset0:4 offset1:5
	ds_read2_b32 v[36:37], v55 offset0:6 offset1:7
	v_add_u32_e32 v56, 0x60c0, v103
	ds_read2_b32 v[38:39], v56 offset0:0 offset1:1
	ds_read2_b32 v[40:41], v56 offset0:2 offset1:3
	ds_read2_b32 v[42:43], v56 offset0:4 offset1:5
	ds_read2_b32 v[44:45], v56 offset0:6 offset1:7
	s_waitcnt vmcnt(7) lgkmcnt(8)
	v_fmamk_f32 v54, v6, 0x3a800000, v13
	v_rsq_f32_e32 v54, v54
	v_add_u32_e32 v58, 0x20000, v4
	v_mul_f32_e32 v22, v22, v54
	v_mul_f32_e32 v23, v23, v54
	v_mul_f32_e32 v24, v24, v54
	v_mul_f32_e32 v25, v25, v54
	v_mul_f32_e32 v26, v26, v54
	v_mul_f32_e32 v27, v27, v54
	v_mul_f32_e32 v28, v28, v54
	v_mul_f32_e32 v29, v29, v54
	v_max_f32_e32 v22, 0, v22
	v_max_f32_e32 v23, 0, v23
	v_max_f32_e32 v24, 0, v24
	v_max_f32_e32 v25, 0, v25
	v_max_f32_e32 v26, 0, v26
	v_max_f32_e32 v27, 0, v27
	v_max_f32_e32 v28, 0, v28
	v_max_f32_e32 v29, 0, v29
	v_pk_mul_f32 v[22:23], v[22:23], v[22:23]
	v_pk_mul_f32 v[24:25], v[24:25], v[24:25]
	v_pk_mul_f32 v[26:27], v[26:27], v[26:27]
	v_pk_mul_f32 v[28:29], v[28:29], v[28:29]
	v_and_b32_sdwa v46, v22, v59 dst_sel:DWORD dst_unused:UNUSED_PAD src0_sel:WORD_1 src1_sel:DWORD
	v_and_b32_sdwa v47, v23, v59 dst_sel:DWORD dst_unused:UNUSED_PAD src0_sel:WORD_1 src1_sel:DWORD
	v_and_b32_sdwa v48, v24, v59 dst_sel:DWORD dst_unused:UNUSED_PAD src0_sel:WORD_1 src1_sel:DWORD
	v_and_b32_sdwa v49, v25, v59 dst_sel:DWORD dst_unused:UNUSED_PAD src0_sel:WORD_1 src1_sel:DWORD
	v_and_b32_sdwa v50, v26, v59 dst_sel:DWORD dst_unused:UNUSED_PAD src0_sel:WORD_1 src1_sel:DWORD
	v_and_b32_sdwa v51, v27, v59 dst_sel:DWORD dst_unused:UNUSED_PAD src0_sel:WORD_1 src1_sel:DWORD
	v_and_b32_sdwa v52, v28, v59 dst_sel:DWORD dst_unused:UNUSED_PAD src0_sel:WORD_1 src1_sel:DWORD
	v_and_b32_sdwa v53, v29, v59 dst_sel:DWORD dst_unused:UNUSED_PAD src0_sel:WORD_1 src1_sel:DWORD
	v_add3_u32 v22, v22, v46, s24
	v_add3_u32 v23, v23, v47, s24
	v_add3_u32 v24, v24, v48, s24
	v_add3_u32 v25, v25, v49, s24
	v_add3_u32 v26, v26, v50, s24
	v_add3_u32 v27, v27, v51, s24
	v_add3_u32 v28, v28, v52, s24
	v_add3_u32 v29, v29, v53, s24
	v_and_b32_e32 v23, 0xffff0000, v23
	v_and_b32_e32 v25, 0xffff0000, v25
	v_and_b32_e32 v27, 0xffff0000, v27
	v_and_b32_e32 v29, 0xffff0000, v29
	v_or_b32_sdwa v76, v23, v22 dst_sel:DWORD dst_unused:UNUSED_PAD src0_sel:DWORD src1_sel:WORD_1
	v_or_b32_sdwa v77, v25, v24 dst_sel:DWORD dst_unused:UNUSED_PAD src0_sel:DWORD src1_sel:WORD_1
	v_or_b32_sdwa v78, v27, v26 dst_sel:DWORD dst_unused:UNUSED_PAD src0_sel:DWORD src1_sel:WORD_1
	v_or_b32_sdwa v79, v29, v28 dst_sel:DWORD dst_unused:UNUSED_PAD src0_sel:DWORD src1_sel:WORD_1
	global_store_dwordx4 v58, v[76:79], s[56:57]
	s_waitcnt vmcnt(7) lgkmcnt(4)
	v_fmamk_f32 v54, v7, 0x3a800000, v13
	v_rsq_f32_e32 v54, v54
	v_add_u32_e32 v57, 0x40000, v4
	v_mul_f32_e32 v30, v30, v54
	v_mul_f32_e32 v31, v31, v54
	v_mul_f32_e32 v32, v32, v54
	v_mul_f32_e32 v33, v33, v54
	v_mul_f32_e32 v34, v34, v54
	v_mul_f32_e32 v35, v35, v54
	v_mul_f32_e32 v36, v36, v54
	v_mul_f32_e32 v37, v37, v54
	v_max_f32_e32 v30, 0, v30
	v_max_f32_e32 v31, 0, v31
	v_max_f32_e32 v32, 0, v32
	v_max_f32_e32 v33, 0, v33
	v_max_f32_e32 v34, 0, v34
	v_max_f32_e32 v35, 0, v35
	v_max_f32_e32 v36, 0, v36
	v_max_f32_e32 v37, 0, v37
	v_pk_mul_f32 v[30:31], v[30:31], v[30:31]
	v_pk_mul_f32 v[32:33], v[32:33], v[32:33]
	v_pk_mul_f32 v[34:35], v[34:35], v[34:35]
	v_pk_mul_f32 v[36:37], v[36:37], v[36:37]
	v_and_b32_sdwa v46, v30, v59 dst_sel:DWORD dst_unused:UNUSED_PAD src0_sel:WORD_1 src1_sel:DWORD
	v_and_b32_sdwa v47, v31, v59 dst_sel:DWORD dst_unused:UNUSED_PAD src0_sel:WORD_1 src1_sel:DWORD
	v_and_b32_sdwa v48, v32, v59 dst_sel:DWORD dst_unused:UNUSED_PAD src0_sel:WORD_1 src1_sel:DWORD
	v_and_b32_sdwa v49, v33, v59 dst_sel:DWORD dst_unused:UNUSED_PAD src0_sel:WORD_1 src1_sel:DWORD
	v_and_b32_sdwa v50, v34, v59 dst_sel:DWORD dst_unused:UNUSED_PAD src0_sel:WORD_1 src1_sel:DWORD
	v_and_b32_sdwa v51, v35, v59 dst_sel:DWORD dst_unused:UNUSED_PAD src0_sel:WORD_1 src1_sel:DWORD
	v_and_b32_sdwa v52, v36, v59 dst_sel:DWORD dst_unused:UNUSED_PAD src0_sel:WORD_1 src1_sel:DWORD
	v_and_b32_sdwa v53, v37, v59 dst_sel:DWORD dst_unused:UNUSED_PAD src0_sel:WORD_1 src1_sel:DWORD
	v_add3_u32 v30, v30, v46, s24
	v_add3_u32 v31, v31, v47, s24
	v_add3_u32 v32, v32, v48, s24
	v_add3_u32 v33, v33, v49, s24
	v_add3_u32 v34, v34, v50, s24
	v_add3_u32 v35, v35, v51, s24
	v_add3_u32 v36, v36, v52, s24
	v_add3_u32 v37, v37, v53, s24
	v_and_b32_e32 v31, 0xffff0000, v31
	v_and_b32_e32 v33, 0xffff0000, v33
	v_and_b32_e32 v35, 0xffff0000, v35
	v_and_b32_e32 v37, 0xffff0000, v37
	v_or_b32_sdwa v60, v31, v30 dst_sel:DWORD dst_unused:UNUSED_PAD src0_sel:DWORD src1_sel:WORD_1
	v_or_b32_sdwa v61, v33, v32 dst_sel:DWORD dst_unused:UNUSED_PAD src0_sel:DWORD src1_sel:WORD_1
	v_or_b32_sdwa v62, v35, v34 dst_sel:DWORD dst_unused:UNUSED_PAD src0_sel:DWORD src1_sel:WORD_1
	v_or_b32_sdwa v63, v37, v36 dst_sel:DWORD dst_unused:UNUSED_PAD src0_sel:DWORD src1_sel:WORD_1
	global_store_dwordx4 v57, v[60:63], s[56:57]
	v_add_u32_e32 v55, 0x8100, v103
	ds_read2_b32 v[14:15], v55 offset0:0 offset1:1
	ds_read2_b32 v[16:17], v55 offset0:2 offset1:3
	ds_read2_b32 v[18:19], v55 offset0:4 offset1:5
	ds_read2_b32 v[20:21], v55 offset0:6 offset1:7
	v_add_u32_e32 v56, 0xa140, v103
	ds_read2_b32 v[22:23], v56 offset0:0 offset1:1
	ds_read2_b32 v[24:25], v56 offset0:2 offset1:3
	ds_read2_b32 v[26:27], v56 offset0:4 offset1:5
	ds_read2_b32 v[28:29], v56 offset0:6 offset1:7
	s_waitcnt vmcnt(7) lgkmcnt(8)
	v_fmamk_f32 v54, v8, 0x3a800000, v13
	v_rsq_f32_e32 v54, v54
	v_add_u32_e32 v58, 0x60000, v4
	v_mul_f32_e32 v38, v38, v54
	v_mul_f32_e32 v39, v39, v54
	v_mul_f32_e32 v40, v40, v54
	v_mul_f32_e32 v41, v41, v54
	v_mul_f32_e32 v42, v42, v54
	v_mul_f32_e32 v43, v43, v54
	v_mul_f32_e32 v44, v44, v54
	v_mul_f32_e32 v45, v45, v54
	v_max_f32_e32 v38, 0, v38
	v_max_f32_e32 v39, 0, v39
	v_max_f32_e32 v40, 0, v40
	v_max_f32_e32 v41, 0, v41
	v_max_f32_e32 v42, 0, v42
	v_max_f32_e32 v43, 0, v43
	v_max_f32_e32 v44, 0, v44
	v_max_f32_e32 v45, 0, v45
	v_pk_mul_f32 v[38:39], v[38:39], v[38:39]
	v_pk_mul_f32 v[40:41], v[40:41], v[40:41]
	v_pk_mul_f32 v[42:43], v[42:43], v[42:43]
	v_pk_mul_f32 v[44:45], v[44:45], v[44:45]
	v_and_b32_sdwa v46, v38, v59 dst_sel:DWORD dst_unused:UNUSED_PAD src0_sel:WORD_1 src1_sel:DWORD
	v_and_b32_sdwa v47, v39, v59 dst_sel:DWORD dst_unused:UNUSED_PAD src0_sel:WORD_1 src1_sel:DWORD
	v_and_b32_sdwa v48, v40, v59 dst_sel:DWORD dst_unused:UNUSED_PAD src0_sel:WORD_1 src1_sel:DWORD
	v_and_b32_sdwa v49, v41, v59 dst_sel:DWORD dst_unused:UNUSED_PAD src0_sel:WORD_1 src1_sel:DWORD
	v_and_b32_sdwa v50, v42, v59 dst_sel:DWORD dst_unused:UNUSED_PAD src0_sel:WORD_1 src1_sel:DWORD
	v_and_b32_sdwa v51, v43, v59 dst_sel:DWORD dst_unused:UNUSED_PAD src0_sel:WORD_1 src1_sel:DWORD
	v_and_b32_sdwa v52, v44, v59 dst_sel:DWORD dst_unused:UNUSED_PAD src0_sel:WORD_1 src1_sel:DWORD
	v_and_b32_sdwa v53, v45, v59 dst_sel:DWORD dst_unused:UNUSED_PAD src0_sel:WORD_1 src1_sel:DWORD
	v_add3_u32 v38, v38, v46, s24
	v_add3_u32 v39, v39, v47, s24
	v_add3_u32 v40, v40, v48, s24
	v_add3_u32 v41, v41, v49, s24
	v_add3_u32 v42, v42, v50, s24
	v_add3_u32 v43, v43, v51, s24
	v_add3_u32 v44, v44, v52, s24
	v_add3_u32 v45, v45, v53, s24
	v_and_b32_e32 v39, 0xffff0000, v39
	v_and_b32_e32 v41, 0xffff0000, v41
	v_and_b32_e32 v43, 0xffff0000, v43
	v_and_b32_e32 v45, 0xffff0000, v45
	v_or_b32_sdwa v76, v39, v38 dst_sel:DWORD dst_unused:UNUSED_PAD src0_sel:DWORD src1_sel:WORD_1
	v_or_b32_sdwa v77, v41, v40 dst_sel:DWORD dst_unused:UNUSED_PAD src0_sel:DWORD src1_sel:WORD_1
	v_or_b32_sdwa v78, v43, v42 dst_sel:DWORD dst_unused:UNUSED_PAD src0_sel:DWORD src1_sel:WORD_1
	v_or_b32_sdwa v79, v45, v44 dst_sel:DWORD dst_unused:UNUSED_PAD src0_sel:DWORD src1_sel:WORD_1
	global_store_dwordx4 v58, v[76:79], s[56:57]
	s_waitcnt vmcnt(7) lgkmcnt(4)
	v_fmamk_f32 v54, v9, 0x3a800000, v13
	v_rsq_f32_e32 v54, v54
	v_add_u32_e32 v57, 0x80000, v4
	v_mul_f32_e32 v14, v14, v54
	v_mul_f32_e32 v15, v15, v54
	v_mul_f32_e32 v16, v16, v54
	v_mul_f32_e32 v17, v17, v54
	v_mul_f32_e32 v18, v18, v54
	v_mul_f32_e32 v19, v19, v54
	v_mul_f32_e32 v20, v20, v54
	v_mul_f32_e32 v21, v21, v54
	v_max_f32_e32 v14, 0, v14
	v_max_f32_e32 v15, 0, v15
	v_max_f32_e32 v16, 0, v16
	v_max_f32_e32 v17, 0, v17
	v_max_f32_e32 v18, 0, v18
	v_max_f32_e32 v19, 0, v19
	v_max_f32_e32 v20, 0, v20
	v_max_f32_e32 v21, 0, v21
	v_pk_mul_f32 v[14:15], v[14:15], v[14:15]
	v_pk_mul_f32 v[16:17], v[16:17], v[16:17]
	v_pk_mul_f32 v[18:19], v[18:19], v[18:19]
	v_pk_mul_f32 v[20:21], v[20:21], v[20:21]
	v_and_b32_sdwa v46, v14, v59 dst_sel:DWORD dst_unused:UNUSED_PAD src0_sel:WORD_1 src1_sel:DWORD
	v_and_b32_sdwa v47, v15, v59 dst_sel:DWORD dst_unused:UNUSED_PAD src0_sel:WORD_1 src1_sel:DWORD
	v_and_b32_sdwa v48, v16, v59 dst_sel:DWORD dst_unused:UNUSED_PAD src0_sel:WORD_1 src1_sel:DWORD
	v_and_b32_sdwa v49, v17, v59 dst_sel:DWORD dst_unused:UNUSED_PAD src0_sel:WORD_1 src1_sel:DWORD
	v_and_b32_sdwa v50, v18, v59 dst_sel:DWORD dst_unused:UNUSED_PAD src0_sel:WORD_1 src1_sel:DWORD
	v_and_b32_sdwa v51, v19, v59 dst_sel:DWORD dst_unused:UNUSED_PAD src0_sel:WORD_1 src1_sel:DWORD
	v_and_b32_sdwa v52, v20, v59 dst_sel:DWORD dst_unused:UNUSED_PAD src0_sel:WORD_1 src1_sel:DWORD
	v_and_b32_sdwa v53, v21, v59 dst_sel:DWORD dst_unused:UNUSED_PAD src0_sel:WORD_1 src1_sel:DWORD
	v_add3_u32 v14, v14, v46, s24
	v_add3_u32 v15, v15, v47, s24
	v_add3_u32 v16, v16, v48, s24
	v_add3_u32 v17, v17, v49, s24
	v_add3_u32 v18, v18, v50, s24
	v_add3_u32 v19, v19, v51, s24
	v_add3_u32 v20, v20, v52, s24
	v_add3_u32 v21, v21, v53, s24
	v_and_b32_e32 v15, 0xffff0000, v15
	v_and_b32_e32 v17, 0xffff0000, v17
	v_and_b32_e32 v19, 0xffff0000, v19
	v_and_b32_e32 v21, 0xffff0000, v21
	v_or_b32_sdwa v60, v15, v14 dst_sel:DWORD dst_unused:UNUSED_PAD src0_sel:DWORD src1_sel:WORD_1
	v_or_b32_sdwa v61, v17, v16 dst_sel:DWORD dst_unused:UNUSED_PAD src0_sel:DWORD src1_sel:WORD_1
	v_or_b32_sdwa v62, v19, v18 dst_sel:DWORD dst_unused:UNUSED_PAD src0_sel:DWORD src1_sel:WORD_1
	v_or_b32_sdwa v63, v21, v20 dst_sel:DWORD dst_unused:UNUSED_PAD src0_sel:DWORD src1_sel:WORD_1
	global_store_dwordx4 v57, v[60:63], s[56:57]
	v_add_u32_e32 v55, 0xc180, v103
	ds_read2_b32 v[30:31], v55 offset0:0 offset1:1
	ds_read2_b32 v[32:33], v55 offset0:2 offset1:3
	ds_read2_b32 v[34:35], v55 offset0:4 offset1:5
	ds_read2_b32 v[36:37], v55 offset0:6 offset1:7
	v_add_u32_e32 v56, 0xe1c0, v103
	ds_read2_b32 v[38:39], v56 offset0:0 offset1:1
	ds_read2_b32 v[40:41], v56 offset0:2 offset1:3
	ds_read2_b32 v[42:43], v56 offset0:4 offset1:5
	ds_read2_b32 v[44:45], v56 offset0:6 offset1:7
	s_waitcnt vmcnt(7) lgkmcnt(8)
	v_fmamk_f32 v54, v10, 0x3a800000, v13
	v_rsq_f32_e32 v54, v54
	v_add_u32_e32 v58, 0xa0000, v4
	v_mul_f32_e32 v22, v22, v54
	v_mul_f32_e32 v23, v23, v54
	v_mul_f32_e32 v24, v24, v54
	v_mul_f32_e32 v25, v25, v54
	v_mul_f32_e32 v26, v26, v54
	v_mul_f32_e32 v27, v27, v54
	v_mul_f32_e32 v28, v28, v54
	v_mul_f32_e32 v29, v29, v54
	v_max_f32_e32 v22, 0, v22
	v_max_f32_e32 v23, 0, v23
	v_max_f32_e32 v24, 0, v24
	v_max_f32_e32 v25, 0, v25
	v_max_f32_e32 v26, 0, v26
	v_max_f32_e32 v27, 0, v27
	v_max_f32_e32 v28, 0, v28
	v_max_f32_e32 v29, 0, v29
	v_pk_mul_f32 v[22:23], v[22:23], v[22:23]
	v_pk_mul_f32 v[24:25], v[24:25], v[24:25]
	v_pk_mul_f32 v[26:27], v[26:27], v[26:27]
	v_pk_mul_f32 v[28:29], v[28:29], v[28:29]
	v_and_b32_sdwa v46, v22, v59 dst_sel:DWORD dst_unused:UNUSED_PAD src0_sel:WORD_1 src1_sel:DWORD
	v_and_b32_sdwa v47, v23, v59 dst_sel:DWORD dst_unused:UNUSED_PAD src0_sel:WORD_1 src1_sel:DWORD
	v_and_b32_sdwa v48, v24, v59 dst_sel:DWORD dst_unused:UNUSED_PAD src0_sel:WORD_1 src1_sel:DWORD
	v_and_b32_sdwa v49, v25, v59 dst_sel:DWORD dst_unused:UNUSED_PAD src0_sel:WORD_1 src1_sel:DWORD
	v_and_b32_sdwa v50, v26, v59 dst_sel:DWORD dst_unused:UNUSED_PAD src0_sel:WORD_1 src1_sel:DWORD
	v_and_b32_sdwa v51, v27, v59 dst_sel:DWORD dst_unused:UNUSED_PAD src0_sel:WORD_1 src1_sel:DWORD
	v_and_b32_sdwa v52, v28, v59 dst_sel:DWORD dst_unused:UNUSED_PAD src0_sel:WORD_1 src1_sel:DWORD
	v_and_b32_sdwa v53, v29, v59 dst_sel:DWORD dst_unused:UNUSED_PAD src0_sel:WORD_1 src1_sel:DWORD
	v_add3_u32 v22, v22, v46, s24
	v_add3_u32 v23, v23, v47, s24
	v_add3_u32 v24, v24, v48, s24
	v_add3_u32 v25, v25, v49, s24
	v_add3_u32 v26, v26, v50, s24
	v_add3_u32 v27, v27, v51, s24
	v_add3_u32 v28, v28, v52, s24
	v_add3_u32 v29, v29, v53, s24
	v_and_b32_e32 v23, 0xffff0000, v23
	v_and_b32_e32 v25, 0xffff0000, v25
	v_and_b32_e32 v27, 0xffff0000, v27
	v_and_b32_e32 v29, 0xffff0000, v29
	v_or_b32_sdwa v76, v23, v22 dst_sel:DWORD dst_unused:UNUSED_PAD src0_sel:DWORD src1_sel:WORD_1
	v_or_b32_sdwa v77, v25, v24 dst_sel:DWORD dst_unused:UNUSED_PAD src0_sel:DWORD src1_sel:WORD_1
	v_or_b32_sdwa v78, v27, v26 dst_sel:DWORD dst_unused:UNUSED_PAD src0_sel:DWORD src1_sel:WORD_1
	v_or_b32_sdwa v79, v29, v28 dst_sel:DWORD dst_unused:UNUSED_PAD src0_sel:DWORD src1_sel:WORD_1
	global_store_dwordx4 v58, v[76:79], s[56:57]
	s_waitcnt vmcnt(7) lgkmcnt(4)
	v_fmamk_f32 v54, v11, 0x3a800000, v13
	v_rsq_f32_e32 v54, v54
	v_add_u32_e32 v57, 0xc0000, v4
	v_mul_f32_e32 v30, v30, v54
	v_mul_f32_e32 v31, v31, v54
	v_mul_f32_e32 v32, v32, v54
	v_mul_f32_e32 v33, v33, v54
	v_mul_f32_e32 v34, v34, v54
	v_mul_f32_e32 v35, v35, v54
	v_mul_f32_e32 v36, v36, v54
	v_mul_f32_e32 v37, v37, v54
	v_max_f32_e32 v30, 0, v30
	v_max_f32_e32 v31, 0, v31
	v_max_f32_e32 v32, 0, v32
	v_max_f32_e32 v33, 0, v33
	v_max_f32_e32 v34, 0, v34
	v_max_f32_e32 v35, 0, v35
	v_max_f32_e32 v36, 0, v36
	v_max_f32_e32 v37, 0, v37
	v_pk_mul_f32 v[30:31], v[30:31], v[30:31]
	v_pk_mul_f32 v[32:33], v[32:33], v[32:33]
	v_pk_mul_f32 v[34:35], v[34:35], v[34:35]
	v_pk_mul_f32 v[36:37], v[36:37], v[36:37]
	v_and_b32_sdwa v46, v30, v59 dst_sel:DWORD dst_unused:UNUSED_PAD src0_sel:WORD_1 src1_sel:DWORD
	v_and_b32_sdwa v47, v31, v59 dst_sel:DWORD dst_unused:UNUSED_PAD src0_sel:WORD_1 src1_sel:DWORD
	v_and_b32_sdwa v48, v32, v59 dst_sel:DWORD dst_unused:UNUSED_PAD src0_sel:WORD_1 src1_sel:DWORD
	v_and_b32_sdwa v49, v33, v59 dst_sel:DWORD dst_unused:UNUSED_PAD src0_sel:WORD_1 src1_sel:DWORD
	v_and_b32_sdwa v50, v34, v59 dst_sel:DWORD dst_unused:UNUSED_PAD src0_sel:WORD_1 src1_sel:DWORD
	v_and_b32_sdwa v51, v35, v59 dst_sel:DWORD dst_unused:UNUSED_PAD src0_sel:WORD_1 src1_sel:DWORD
	v_and_b32_sdwa v52, v36, v59 dst_sel:DWORD dst_unused:UNUSED_PAD src0_sel:WORD_1 src1_sel:DWORD
	v_and_b32_sdwa v53, v37, v59 dst_sel:DWORD dst_unused:UNUSED_PAD src0_sel:WORD_1 src1_sel:DWORD
	v_add3_u32 v30, v30, v46, s24
	v_add3_u32 v31, v31, v47, s24
	v_add3_u32 v32, v32, v48, s24
	v_add3_u32 v33, v33, v49, s24
	v_add3_u32 v34, v34, v50, s24
	v_add3_u32 v35, v35, v51, s24
	v_add3_u32 v36, v36, v52, s24
	v_add3_u32 v37, v37, v53, s24
	v_and_b32_e32 v31, 0xffff0000, v31
	v_and_b32_e32 v33, 0xffff0000, v33
	v_and_b32_e32 v35, 0xffff0000, v35
	v_and_b32_e32 v37, 0xffff0000, v37
	v_or_b32_sdwa v60, v31, v30 dst_sel:DWORD dst_unused:UNUSED_PAD src0_sel:DWORD src1_sel:WORD_1
	v_or_b32_sdwa v61, v33, v32 dst_sel:DWORD dst_unused:UNUSED_PAD src0_sel:DWORD src1_sel:WORD_1
	v_or_b32_sdwa v62, v35, v34 dst_sel:DWORD dst_unused:UNUSED_PAD src0_sel:DWORD src1_sel:WORD_1
	v_or_b32_sdwa v63, v37, v36 dst_sel:DWORD dst_unused:UNUSED_PAD src0_sel:DWORD src1_sel:WORD_1
	global_store_dwordx4 v57, v[60:63], s[56:57]
	s_waitcnt vmcnt(7) lgkmcnt(0)
	v_fmamk_f32 v54, v12, 0x3a800000, v13
	v_rsq_f32_e32 v54, v54
	v_add_u32_e32 v58, 0xe0000, v4
	v_mul_f32_e32 v38, v38, v54
	v_mul_f32_e32 v39, v39, v54
	v_mul_f32_e32 v40, v40, v54
	v_mul_f32_e32 v41, v41, v54
	v_mul_f32_e32 v42, v42, v54
	v_mul_f32_e32 v43, v43, v54
	v_mul_f32_e32 v44, v44, v54
	v_mul_f32_e32 v45, v45, v54
	v_max_f32_e32 v38, 0, v38
	v_max_f32_e32 v39, 0, v39
	v_max_f32_e32 v40, 0, v40
	v_max_f32_e32 v41, 0, v41
	v_max_f32_e32 v42, 0, v42
	v_max_f32_e32 v43, 0, v43
	v_max_f32_e32 v44, 0, v44
	v_max_f32_e32 v45, 0, v45
	v_pk_mul_f32 v[38:39], v[38:39], v[38:39]
	v_pk_mul_f32 v[40:41], v[40:41], v[40:41]
	v_pk_mul_f32 v[42:43], v[42:43], v[42:43]
	v_pk_mul_f32 v[44:45], v[44:45], v[44:45]
	v_and_b32_sdwa v46, v38, v59 dst_sel:DWORD dst_unused:UNUSED_PAD src0_sel:WORD_1 src1_sel:DWORD
	v_and_b32_sdwa v47, v39, v59 dst_sel:DWORD dst_unused:UNUSED_PAD src0_sel:WORD_1 src1_sel:DWORD
	v_and_b32_sdwa v48, v40, v59 dst_sel:DWORD dst_unused:UNUSED_PAD src0_sel:WORD_1 src1_sel:DWORD
	v_and_b32_sdwa v49, v41, v59 dst_sel:DWORD dst_unused:UNUSED_PAD src0_sel:WORD_1 src1_sel:DWORD
	v_and_b32_sdwa v50, v42, v59 dst_sel:DWORD dst_unused:UNUSED_PAD src0_sel:WORD_1 src1_sel:DWORD
	v_and_b32_sdwa v51, v43, v59 dst_sel:DWORD dst_unused:UNUSED_PAD src0_sel:WORD_1 src1_sel:DWORD
	v_and_b32_sdwa v52, v44, v59 dst_sel:DWORD dst_unused:UNUSED_PAD src0_sel:WORD_1 src1_sel:DWORD
	v_and_b32_sdwa v53, v45, v59 dst_sel:DWORD dst_unused:UNUSED_PAD src0_sel:WORD_1 src1_sel:DWORD
	v_add3_u32 v38, v38, v46, s24
	v_add3_u32 v39, v39, v47, s24
	v_add3_u32 v40, v40, v48, s24
	v_add3_u32 v41, v41, v49, s24
	v_add3_u32 v42, v42, v50, s24
	v_add3_u32 v43, v43, v51, s24
	v_add3_u32 v44, v44, v52, s24
	v_add3_u32 v45, v45, v53, s24
	v_and_b32_e32 v39, 0xffff0000, v39
	v_and_b32_e32 v41, 0xffff0000, v41
	v_and_b32_e32 v43, 0xffff0000, v43
	v_and_b32_e32 v45, 0xffff0000, v45
	v_or_b32_sdwa v76, v39, v38 dst_sel:DWORD dst_unused:UNUSED_PAD src0_sel:DWORD src1_sel:WORD_1
	v_or_b32_sdwa v77, v41, v40 dst_sel:DWORD dst_unused:UNUSED_PAD src0_sel:DWORD src1_sel:WORD_1
	v_or_b32_sdwa v78, v43, v42 dst_sel:DWORD dst_unused:UNUSED_PAD src0_sel:DWORD src1_sel:WORD_1
	v_or_b32_sdwa v79, v45, v44 dst_sel:DWORD dst_unused:UNUSED_PAD src0_sel:DWORD src1_sel:WORD_1
	global_store_dwordx4 v58, v[76:79], s[56:57]
	s_cmpk_lt_u32 s13, 0x400
	s_barrier
	s_cbranch_scc1 .LBB0_338

.LBB0_590:
	s_lshr_b32 s8, s12, 2
	s_and_b32 s10, s16, 56
	s_and_b32 s8, s8, 0x1ffffc0
	s_or_b32 s10, s10, s3
	s_or_b32 s8, s10, s8
	s_lshl_b32 s8, s8, 7
	s_lshl_b64 s[24:25], s[8:9], 11
	v_lshl_add_u64 v[78:79], v[70:71], 0, s[24:25]
	v_add_co_u32_e32 v80, vcc, s18, v78
	s_and_b32 s10, s14, 0xf80
	s_nop 0
	v_addc_co_u32_e32 v81, vcc, 0, v79, vcc
	s_lshl_b32 s26, s10, 11
	s_mov_b32 s27, s9
	v_add_co_u32_e32 v82, vcc, s19, v78
	v_lshl_add_u64 v[76:77], v[72:73], 0, s[26:27]
	s_nop 0
	v_addc_co_u32_e32 v83, vcc, 0, v79, vcc
	v_add_co_u32_e32 v84, vcc, s18, v76
	global_load_dwordx4 v[2:5], v[78:79], off
	global_load_dwordx4 v[6:9], v[80:81], off
	v_addc_co_u32_e32 v85, vcc, 0, v77, vcc
	v_add_co_u32_e32 v86, vcc, s19, v76
	global_load_dwordx4 v[10:13], v[82:83], off
	global_load_dwordx4 v[14:17], v[76:77], off
	v_addc_co_u32_e32 v87, vcc, 0, v77, vcc
	global_load_dwordx4 v[18:21], v[84:85], off
	global_load_dwordx4 v[22:25], v[86:87], off
	v_add_co_u32_e32 v88, vcc, s20, v76
	s_nop 1
	v_addc_co_u32_e32 v89, vcc, 0, v77, vcc
	global_load_dwordx4 v[26:29], v[88:89], off
	v_add_co_u32_e32 v90, vcc, s20, v78
	s_nop 1
	v_addc_co_u32_e32 v91, vcc, 0, v79, vcc
	global_load_dwordx4 v[30:33], v[90:91], off
	global_load_dwordx4 v[148:151], v[76:77], off offset:128
	global_load_dwordx4 v[152:155], v[84:85], off offset:128
	global_load_dwordx4 v[156:159], v[86:87], off offset:128
	global_load_dwordx4 v[160:163], v[88:89], off offset:128
	global_load_dwordx4 v[164:167], v[78:79], off offset:128
	global_load_dwordx4 v[168:171], v[80:81], off offset:128
	global_load_dwordx4 v[172:175], v[82:83], off offset:128
	global_load_dwordx4 v[176:179], v[90:91], off offset:128
	s_waitcnt vmcnt(12)
	ds_write_b128 v1, v[14:17] offset:36864
	s_waitcnt vmcnt(11)
	ds_write_b128 v1, v[18:21] offset:41472
	s_waitcnt vmcnt(10)
	ds_write_b128 v1, v[22:25] offset:46080
	s_waitcnt vmcnt(9)
	ds_write_b128 v1, v[26:29] offset:50688
	ds_write_b128 v1, v[2:5]
	ds_write_b128 v1, v[6:9] offset:4608
	ds_write_b128 v1, v[10:13] offset:9216
	s_waitcnt vmcnt(8)
	ds_write_b128 v1, v[30:33] offset:13824
	s_waitcnt lgkmcnt(0)
	s_barrier
	global_load_dwordx4 v[180:183], v[80:81], off offset:256
	global_load_dwordx4 v[184:187], v[82:83], off offset:256
	global_load_dwordx4 v[188:191], v[78:79], off offset:256
	global_load_dwordx4 v[192:195], v[76:77], off offset:256
	global_load_dwordx4 v[196:199], v[90:91], off offset:256
	global_load_dwordx4 v[200:203], v[84:85], off offset:256
	global_load_dwordx4 v[204:207], v[86:87], off offset:256
	global_load_dwordx4 v[208:211], v[88:89], off offset:256
	ds_read_b128 v[18:21], v66
	ds_read_b128 v[34:37], v67 offset:36864
	ds_read_b128 v[212:215], v66 offset:32
	ds_read_b128 v[216:219], v67 offset:36896
	ds_read_b128 v[50:53], v67 offset:41472
	ds_read_b128 v[220:223], v67 offset:41504
	ds_read_b128 v[54:57], v66 offset:4608
	ds_read_b128 v[224:227], v66 offset:4640
	s_waitcnt lgkmcnt(6)
	v_mfma_f32_32x32x16_bf16 v[2:17], v[18:21], v[34:37], 0
	s_waitcnt lgkmcnt(3)
	v_mfma_f32_32x32x16_bf16 v[18:33], v[18:21], v[50:53], 0
	s_waitcnt lgkmcnt(1)
	v_mfma_f32_32x32x16_bf16 v[34:49], v[54:57], v[34:37], 0
	v_mfma_f32_32x32x16_bf16 v[50:65], v[54:57], v[50:53], 0
	v_mfma_f32_32x32x16_bf16 v[2:17], v[212:215], v[216:219], v[2:17]
	v_mfma_f32_32x32x16_bf16 v[18:33], v[212:215], v[220:223], v[18:33]
	s_waitcnt lgkmcnt(0)
	v_mfma_f32_32x32x16_bf16 v[34:49], v[224:227], v[216:219], v[34:49]
	v_mfma_f32_32x32x16_bf16 v[50:65], v[224:227], v[220:223], v[50:65]
	ds_read_b128 v[212:215], v66 offset:64
	ds_read_b128 v[216:219], v67 offset:36928
	ds_read_b128 v[220:223], v66 offset:96
	ds_read_b128 v[224:227], v67 offset:36960
	ds_read_b128 v[228:231], v67 offset:41536
	ds_read_b128 v[232:235], v67 offset:41568
	s_waitcnt lgkmcnt(4)
	v_mfma_f32_32x32x16_bf16 v[2:17], v[212:215], v[216:219], v[2:17]
	s_waitcnt lgkmcnt(1)
	v_mfma_f32_32x32x16_bf16 v[18:33], v[212:215], v[228:231], v[18:33]
	ds_read_b128 v[212:215], v66 offset:4672
	ds_read_b128 v[236:239], v66 offset:4704
	s_waitcnt vmcnt(11)
	ds_write_b128 v1, v[164:167] offset:18432
	s_waitcnt vmcnt(10)
	ds_write_b128 v1, v[168:171] offset:23040
	s_waitcnt vmcnt(9)
	ds_write_b128 v1, v[172:175] offset:27648
	s_waitcnt vmcnt(8)
	ds_write_b128 v1, v[176:179] offset:32256
	ds_write_b128 v1, v[148:151] offset:55296
	ds_write_b128 v1, v[152:155] offset:59904
	ds_write_b128 v1, v[156:159] offset:64512
	ds_write_b128 v92, v[160:163] offset:32256
	s_waitcnt lgkmcnt(0)
	s_barrier
	global_load_dwordx4 v[148:151], v[80:81], off offset:384
	global_load_dwordx4 v[152:155], v[82:83], off offset:384
	global_load_dwordx4 v[156:159], v[78:79], off offset:384
	global_load_dwordx4 v[160:163], v[76:77], off offset:384
	global_load_dwordx4 v[164:167], v[90:91], off offset:384
	global_load_dwordx4 v[168:171], v[84:85], off offset:384
	global_load_dwordx4 v[172:175], v[86:87], off offset:384
	global_load_dwordx4 v[176:179], v[88:89], off offset:384
	v_mfma_f32_32x32x16_bf16 v[34:49], v[212:215], v[216:219], v[34:49]
	v_mfma_f32_32x32x16_bf16 v[50:65], v[212:215], v[228:231], v[50:65]
	v_mfma_f32_32x32x16_bf16 v[2:17], v[220:223], v[224:227], v[2:17]
	v_mfma_f32_32x32x16_bf16 v[18:33], v[220:223], v[232:235], v[18:33]
	v_mfma_f32_32x32x16_bf16 v[34:49], v[236:239], v[224:227], v[34:49]
	v_mfma_f32_32x32x16_bf16 v[50:65], v[236:239], v[232:235], v[50:65]
	ds_read_b128 v[212:215], v66 offset:18432
	ds_read_b128 v[216:219], v67 offset:55296
	ds_read_b128 v[220:223], v66 offset:18464
	ds_read_b128 v[224:227], v67 offset:55328
	ds_read_b128 v[228:231], v67 offset:59904
	ds_read_b128 v[232:235], v67 offset:59936
	s_waitcnt lgkmcnt(4)
	v_mfma_f32_32x32x16_bf16 v[2:17], v[212:215], v[216:219], v[2:17]
	s_waitcnt lgkmcnt(1)
	v_mfma_f32_32x32x16_bf16 v[18:33], v[212:215], v[228:231], v[18:33]
	ds_read_b128 v[212:215], v66 offset:23040
	ds_read_b128 v[236:239], v66 offset:23072
	s_waitcnt lgkmcnt(1)
	v_mfma_f32_32x32x16_bf16 v[34:49], v[212:215], v[216:219], v[34:49]
	v_mfma_f32_32x32x16_bf16 v[50:65], v[212:215], v[228:231], v[50:65]
	v_mfma_f32_32x32x16_bf16 v[2:17], v[220:223], v[224:227], v[2:17]
	v_mfma_f32_32x32x16_bf16 v[18:33], v[220:223], v[232:235], v[18:33]
	s_waitcnt lgkmcnt(0)
	v_mfma_f32_32x32x16_bf16 v[34:49], v[236:239], v[224:227], v[34:49]
	ds_read_b128 v[212:215], v66 offset:18496
	ds_read_b128 v[216:219], v67 offset:55360
	ds_read_b128 v[220:223], v66 offset:18528
	ds_read_b128 v[224:227], v67 offset:55392
	v_mfma_f32_32x32x16_bf16 v[50:65], v[236:239], v[232:235], v[50:65]
	ds_read_b128 v[228:231], v67 offset:59968
	ds_read_b128 v[232:235], v67 offset:60000
	s_waitcnt lgkmcnt(4)
	v_mfma_f32_32x32x16_bf16 v[2:17], v[212:215], v[216:219], v[2:17]
	s_waitcnt lgkmcnt(1)
	v_mfma_f32_32x32x16_bf16 v[18:33], v[212:215], v[228:231], v[18:33]
	ds_read_b128 v[212:215], v66 offset:23104
	ds_read_b128 v[236:239], v66 offset:23136
	s_waitcnt vmcnt(13)
	ds_write_b128 v1, v[188:191]
	ds_write_b128 v1, v[180:183] offset:4608
	ds_write_b128 v1, v[184:187] offset:9216
	s_waitcnt vmcnt(11)
	ds_write_b128 v1, v[196:199] offset:13824
	ds_write_b128 v1, v[192:195] offset:36864
	s_waitcnt vmcnt(10)
	ds_write_b128 v1, v[200:203] offset:41472
	s_waitcnt vmcnt(9)
	ds_write_b128 v1, v[204:207] offset:46080
	s_waitcnt vmcnt(8)
	ds_write_b128 v1, v[208:211] offset:50688
	s_waitcnt lgkmcnt(0)
	s_barrier
	global_load_dwordx4 v[180:183], v[80:81], off offset:512
	global_load_dwordx4 v[184:187], v[82:83], off offset:512
	global_load_dwordx4 v[188:191], v[78:79], off offset:512
	global_load_dwordx4 v[192:195], v[76:77], off offset:512
	global_load_dwordx4 v[196:199], v[90:91], off offset:512
	global_load_dwordx4 v[200:203], v[84:85], off offset:512
	global_load_dwordx4 v[204:207], v[86:87], off offset:512
	global_load_dwordx4 v[208:211], v[88:89], off offset:512
	v_mfma_f32_32x32x16_bf16 v[34:49], v[212:215], v[216:219], v[34:49]
	v_mfma_f32_32x32x16_bf16 v[50:65], v[212:215], v[228:231], v[50:65]
	v_mfma_f32_32x32x16_bf16 v[2:17], v[220:223], v[224:227], v[2:17]
	v_mfma_f32_32x32x16_bf16 v[18:33], v[220:223], v[232:235], v[18:33]
	v_mfma_f32_32x32x16_bf16 v[34:49], v[236:239], v[224:227], v[34:49]
	v_mfma_f32_32x32x16_bf16 v[50:65], v[236:239], v[232:235], v[50:65]
	ds_read_b128 v[212:215], v66
	ds_read_b128 v[216:219], v67 offset:36864
	ds_read_b128 v[220:223], v66 offset:32
	ds_read_b128 v[224:227], v67 offset:36896
	ds_read_b128 v[228:231], v67 offset:41472
	ds_read_b128 v[232:235], v67 offset:41504
	s_waitcnt lgkmcnt(4)
	v_mfma_f32_32x32x16_bf16 v[2:17], v[212:215], v[216:219], v[2:17]
	s_waitcnt lgkmcnt(1)
	v_mfma_f32_32x32x16_bf16 v[18:33], v[212:215], v[228:231], v[18:33]
	ds_read_b128 v[212:215], v66 offset:4608
	ds_read_b128 v[236:239], v66 offset:4640
	s_waitcnt lgkmcnt(1)
	v_mfma_f32_32x32x16_bf16 v[34:49], v[212:215], v[216:219], v[34:49]
	v_mfma_f32_32x32x16_bf16 v[50:65], v[212:215], v[228:231], v[50:65]
	v_mfma_f32_32x32x16_bf16 v[2:17], v[220:223], v[224:227], v[2:17]
	v_mfma_f32_32x32x16_bf16 v[18:33], v[220:223], v[232:235], v[18:33]
	s_waitcnt lgkmcnt(0)
	v_mfma_f32_32x32x16_bf16 v[34:49], v[236:239], v[224:227], v[34:49]
	ds_read_b128 v[212:215], v66 offset:64
	ds_read_b128 v[216:219], v67 offset:36928
	ds_read_b128 v[220:223], v66 offset:96
	ds_read_b128 v[224:227], v67 offset:36960
	v_mfma_f32_32x32x16_bf16 v[50:65], v[236:239], v[232:235], v[50:65]
	ds_read_b128 v[228:231], v67 offset:41536
	ds_read_b128 v[232:235], v67 offset:41568
	s_waitcnt lgkmcnt(4)
	v_mfma_f32_32x32x16_bf16 v[2:17], v[212:215], v[216:219], v[2:17]
	s_waitcnt lgkmcnt(1)
	v_mfma_f32_32x32x16_bf16 v[18:33], v[212:215], v[228:231], v[18:33]
	ds_read_b128 v[212:215], v66 offset:4672
	ds_read_b128 v[236:239], v66 offset:4704
	s_waitcnt vmcnt(13)
	ds_write_b128 v1, v[156:159] offset:18432
	ds_write_b128 v1, v[148:151] offset:23040
	ds_write_b128 v1, v[152:155] offset:27648
	s_waitcnt vmcnt(11)
	ds_write_b128 v1, v[164:167] offset:32256
	ds_write_b128 v1, v[160:163] offset:55296
	s_waitcnt vmcnt(10)
	ds_write_b128 v1, v[168:171] offset:59904
	s_waitcnt vmcnt(9)
	ds_write_b128 v1, v[172:175] offset:64512
	s_waitcnt vmcnt(8)
	ds_write_b128 v92, v[176:179] offset:32256
	s_waitcnt lgkmcnt(0)
	s_barrier
	global_load_dwordx4 v[148:151], v[80:81], off offset:640
	global_load_dwordx4 v[152:155], v[82:83], off offset:640
	global_load_dwordx4 v[156:159], v[78:79], off offset:640
	global_load_dwordx4 v[160:163], v[76:77], off offset:640
	global_load_dwordx4 v[164:167], v[90:91], off offset:640
	global_load_dwordx4 v[168:171], v[84:85], off offset:640
	global_load_dwordx4 v[172:175], v[86:87], off offset:640
	global_load_dwordx4 v[176:179], v[88:89], off offset:640
	v_mfma_f32_32x32x16_bf16 v[34:49], v[212:215], v[216:219], v[34:49]
	v_mfma_f32_32x32x16_bf16 v[50:65], v[212:215], v[228:231], v[50:65]
	v_mfma_f32_32x32x16_bf16 v[2:17], v[220:223], v[224:227], v[2:17]
	v_mfma_f32_32x32x16_bf16 v[18:33], v[220:223], v[232:235], v[18:33]
	v_mfma_f32_32x32x16_bf16 v[34:49], v[236:239], v[224:227], v[34:49]
	v_mfma_f32_32x32x16_bf16 v[50:65], v[236:239], v[232:235], v[50:65]
	ds_read_b128 v[212:215], v66 offset:18432
	ds_read_b128 v[216:219], v67 offset:55296
	ds_read_b128 v[220:223], v66 offset:18464
	ds_read_b128 v[224:227], v67 offset:55328
	ds_read_b128 v[228:231], v67 offset:59904
	ds_read_b128 v[232:235], v67 offset:59936
	s_waitcnt lgkmcnt(4)
	v_mfma_f32_32x32x16_bf16 v[2:17], v[212:215], v[216:219], v[2:17]
	s_waitcnt lgkmcnt(1)
	v_mfma_f32_32x32x16_bf16 v[18:33], v[212:215], v[228:231], v[18:33]
	ds_read_b128 v[212:215], v66 offset:23040
	ds_read_b128 v[236:239], v66 offset:23072
	s_waitcnt lgkmcnt(1)
	v_mfma_f32_32x32x16_bf16 v[34:49], v[212:215], v[216:219], v[34:49]
	v_mfma_f32_32x32x16_bf16 v[50:65], v[212:215], v[228:231], v[50:65]
	v_mfma_f32_32x32x16_bf16 v[2:17], v[220:223], v[224:227], v[2:17]
	v_mfma_f32_32x32x16_bf16 v[18:33], v[220:223], v[232:235], v[18:33]
	s_waitcnt lgkmcnt(0)
	v_mfma_f32_32x32x16_bf16 v[34:49], v[236:239], v[224:227], v[34:49]
	ds_read_b128 v[212:215], v66 offset:18496
	ds_read_b128 v[216:219], v67 offset:55360
	ds_read_b128 v[220:223], v66 offset:18528
	ds_read_b128 v[224:227], v67 offset:55392
	v_mfma_f32_32x32x16_bf16 v[50:65], v[236:239], v[232:235], v[50:65]
	ds_read_b128 v[228:231], v67 offset:59968
	ds_read_b128 v[232:235], v67 offset:60000
	s_waitcnt lgkmcnt(4)
	v_mfma_f32_32x32x16_bf16 v[2:17], v[212:215], v[216:219], v[2:17]
	s_waitcnt lgkmcnt(1)
	v_mfma_f32_32x32x16_bf16 v[18:33], v[212:215], v[228:231], v[18:33]
	ds_read_b128 v[212:215], v66 offset:23104
	ds_read_b128 v[236:239], v66 offset:23136
	s_waitcnt vmcnt(13)
	ds_write_b128 v1, v[188:191]
	ds_write_b128 v1, v[180:183] offset:4608
	ds_write_b128 v1, v[184:187] offset:9216
	s_waitcnt vmcnt(11)
	ds_write_b128 v1, v[196:199] offset:13824
	ds_write_b128 v1, v[192:195] offset:36864
	s_waitcnt vmcnt(10)
	ds_write_b128 v1, v[200:203] offset:41472
	s_waitcnt vmcnt(9)
	ds_write_b128 v1, v[204:207] offset:46080
	s_waitcnt vmcnt(8)
	ds_write_b128 v1, v[208:211] offset:50688
	s_waitcnt lgkmcnt(0)
	s_barrier
	global_load_dwordx4 v[180:183], v[80:81], off offset:768
	global_load_dwordx4 v[184:187], v[82:83], off offset:768
	global_load_dwordx4 v[188:191], v[78:79], off offset:768
	global_load_dwordx4 v[192:195], v[76:77], off offset:768
	global_load_dwordx4 v[196:199], v[90:91], off offset:768
	global_load_dwordx4 v[200:203], v[84:85], off offset:768
	global_load_dwordx4 v[204:207], v[86:87], off offset:768
	global_load_dwordx4 v[208:211], v[88:89], off offset:768
	v_mfma_f32_32x32x16_bf16 v[34:49], v[212:215], v[216:219], v[34:49]
	v_mfma_f32_32x32x16_bf16 v[50:65], v[212:215], v[228:231], v[50:65]
	v_mfma_f32_32x32x16_bf16 v[2:17], v[220:223], v[224:227], v[2:17]
	v_mfma_f32_32x32x16_bf16 v[18:33], v[220:223], v[232:235], v[18:33]
	v_mfma_f32_32x32x16_bf16 v[34:49], v[236:239], v[224:227], v[34:49]
	v_mfma_f32_32x32x16_bf16 v[50:65], v[236:239], v[232:235], v[50:65]
	ds_read_b128 v[212:215], v66
	ds_read_b128 v[216:219], v67 offset:36864
	ds_read_b128 v[220:223], v66 offset:32
	ds_read_b128 v[224:227], v67 offset:36896
	ds_read_b128 v[228:231], v67 offset:41472
	ds_read_b128 v[232:235], v67 offset:41504
	s_waitcnt lgkmcnt(4)
	v_mfma_f32_32x32x16_bf16 v[2:17], v[212:215], v[216:219], v[2:17]
	s_waitcnt lgkmcnt(1)
	v_mfma_f32_32x32x16_bf16 v[18:33], v[212:215], v[228:231], v[18:33]
	ds_read_b128 v[212:215], v66 offset:4608
	ds_read_b128 v[236:239], v66 offset:4640
	s_waitcnt lgkmcnt(1)
	v_mfma_f32_32x32x16_bf16 v[34:49], v[212:215], v[216:219], v[34:49]
	v_mfma_f32_32x32x16_bf16 v[50:65], v[212:215], v[228:231], v[50:65]
	v_mfma_f32_32x32x16_bf16 v[2:17], v[220:223], v[224:227], v[2:17]
	v_mfma_f32_32x32x16_bf16 v[18:33], v[220:223], v[232:235], v[18:33]
	s_waitcnt lgkmcnt(0)
	v_mfma_f32_32x32x16_bf16 v[34:49], v[236:239], v[224:227], v[34:49]
	ds_read_b128 v[212:215], v66 offset:64
	ds_read_b128 v[216:219], v67 offset:36928
	ds_read_b128 v[220:223], v66 offset:96
	ds_read_b128 v[224:227], v67 offset:36960
	v_mfma_f32_32x32x16_bf16 v[50:65], v[236:239], v[232:235], v[50:65]
	ds_read_b128 v[228:231], v67 offset:41536
	ds_read_b128 v[232:235], v67 offset:41568
	s_waitcnt lgkmcnt(4)
	v_mfma_f32_32x32x16_bf16 v[2:17], v[212:215], v[216:219], v[2:17]
	s_waitcnt lgkmcnt(1)
	v_mfma_f32_32x32x16_bf16 v[18:33], v[212:215], v[228:231], v[18:33]
	ds_read_b128 v[212:215], v66 offset:4672
	ds_read_b128 v[236:239], v66 offset:4704
	s_waitcnt vmcnt(13)
	ds_write_b128 v1, v[156:159] offset:18432
	ds_write_b128 v1, v[148:151] offset:23040
	ds_write_b128 v1, v[152:155] offset:27648
	s_waitcnt vmcnt(11)
	ds_write_b128 v1, v[164:167] offset:32256
	ds_write_b128 v1, v[160:163] offset:55296
	s_waitcnt vmcnt(10)
	ds_write_b128 v1, v[168:171] offset:59904
	s_waitcnt vmcnt(9)
	ds_write_b128 v1, v[172:175] offset:64512
	s_waitcnt vmcnt(8)
	ds_write_b128 v92, v[176:179] offset:32256
	s_waitcnt lgkmcnt(0)
	s_barrier
	global_load_dwordx4 v[148:151], v[80:81], off offset:896
	global_load_dwordx4 v[152:155], v[82:83], off offset:896
	global_load_dwordx4 v[156:159], v[78:79], off offset:896
	global_load_dwordx4 v[160:163], v[76:77], off offset:896
	global_load_dwordx4 v[164:167], v[90:91], off offset:896
	global_load_dwordx4 v[168:171], v[84:85], off offset:896
	global_load_dwordx4 v[172:175], v[86:87], off offset:896
	global_load_dwordx4 v[176:179], v[88:89], off offset:896
	v_mfma_f32_32x32x16_bf16 v[34:49], v[212:215], v[216:219], v[34:49]
	v_mfma_f32_32x32x16_bf16 v[50:65], v[212:215], v[228:231], v[50:65]
	v_mfma_f32_32x32x16_bf16 v[2:17], v[220:223], v[224:227], v[2:17]
	v_mfma_f32_32x32x16_bf16 v[18:33], v[220:223], v[232:235], v[18:33]
	v_mfma_f32_32x32x16_bf16 v[34:49], v[236:239], v[224:227], v[34:49]
	v_mfma_f32_32x32x16_bf16 v[50:65], v[236:239], v[232:235], v[50:65]
	ds_read_b128 v[212:215], v66 offset:18432
	ds_read_b128 v[216:219], v67 offset:55296
	ds_read_b128 v[220:223], v66 offset:18464
	ds_read_b128 v[224:227], v67 offset:55328
	ds_read_b128 v[228:231], v67 offset:59904
	ds_read_b128 v[232:235], v67 offset:59936
	s_waitcnt lgkmcnt(4)
	v_mfma_f32_32x32x16_bf16 v[2:17], v[212:215], v[216:219], v[2:17]
	s_waitcnt lgkmcnt(1)
	v_mfma_f32_32x32x16_bf16 v[18:33], v[212:215], v[228:231], v[18:33]
	ds_read_b128 v[212:215], v66 offset:23040
	ds_read_b128 v[236:239], v66 offset:23072
	s_waitcnt lgkmcnt(1)
	v_mfma_f32_32x32x16_bf16 v[34:49], v[212:215], v[216:219], v[34:49]
	v_mfma_f32_32x32x16_bf16 v[50:65], v[212:215], v[228:231], v[50:65]
	v_mfma_f32_32x32x16_bf16 v[2:17], v[220:223], v[224:227], v[2:17]
	v_mfma_f32_32x32x16_bf16 v[18:33], v[220:223], v[232:235], v[18:33]
	s_waitcnt lgkmcnt(0)
	v_mfma_f32_32x32x16_bf16 v[34:49], v[236:239], v[224:227], v[34:49]
	ds_read_b128 v[212:215], v66 offset:18496
	ds_read_b128 v[216:219], v67 offset:55360
	ds_read_b128 v[220:223], v66 offset:18528
	ds_read_b128 v[224:227], v67 offset:55392
	v_mfma_f32_32x32x16_bf16 v[50:65], v[236:239], v[232:235], v[50:65]
	ds_read_b128 v[228:231], v67 offset:59968
	ds_read_b128 v[232:235], v67 offset:60000
	s_waitcnt lgkmcnt(4)
	v_mfma_f32_32x32x16_bf16 v[2:17], v[212:215], v[216:219], v[2:17]
	s_waitcnt lgkmcnt(1)
	v_mfma_f32_32x32x16_bf16 v[18:33], v[212:215], v[228:231], v[18:33]
	ds_read_b128 v[212:215], v66 offset:23104
	ds_read_b128 v[236:239], v66 offset:23136
	s_waitcnt vmcnt(13)
	ds_write_b128 v1, v[188:191]
	ds_write_b128 v1, v[180:183] offset:4608
	ds_write_b128 v1, v[184:187] offset:9216
	s_waitcnt vmcnt(11)
	ds_write_b128 v1, v[196:199] offset:13824
	ds_write_b128 v1, v[192:195] offset:36864
	s_waitcnt vmcnt(10)
	ds_write_b128 v1, v[200:203] offset:41472
	s_waitcnt vmcnt(9)
	ds_write_b128 v1, v[204:207] offset:46080
	s_waitcnt vmcnt(8)
	ds_write_b128 v1, v[208:211] offset:50688
	s_waitcnt lgkmcnt(0)
	s_barrier
	global_load_dwordx4 v[180:183], v[80:81], off offset:1024
	global_load_dwordx4 v[184:187], v[82:83], off offset:1024
	global_load_dwordx4 v[188:191], v[78:79], off offset:1024
	global_load_dwordx4 v[192:195], v[76:77], off offset:1024
	global_load_dwordx4 v[196:199], v[90:91], off offset:1024
	global_load_dwordx4 v[200:203], v[84:85], off offset:1024
	global_load_dwordx4 v[204:207], v[86:87], off offset:1024
	global_load_dwordx4 v[208:211], v[88:89], off offset:1024
	v_mfma_f32_32x32x16_bf16 v[34:49], v[212:215], v[216:219], v[34:49]
	v_mfma_f32_32x32x16_bf16 v[50:65], v[212:215], v[228:231], v[50:65]
	v_mfma_f32_32x32x16_bf16 v[2:17], v[220:223], v[224:227], v[2:17]
	v_mfma_f32_32x32x16_bf16 v[18:33], v[220:223], v[232:235], v[18:33]
	v_mfma_f32_32x32x16_bf16 v[34:49], v[236:239], v[224:227], v[34:49]
	v_mfma_f32_32x32x16_bf16 v[50:65], v[236:239], v[232:235], v[50:65]
	ds_read_b128 v[212:215], v66
	ds_read_b128 v[216:219], v67 offset:36864
	ds_read_b128 v[220:223], v66 offset:32
	ds_read_b128 v[224:227], v67 offset:36896
	ds_read_b128 v[228:231], v67 offset:41472
	ds_read_b128 v[232:235], v67 offset:41504
	s_waitcnt lgkmcnt(4)
	v_mfma_f32_32x32x16_bf16 v[2:17], v[212:215], v[216:219], v[2:17]
	s_waitcnt lgkmcnt(1)
	v_mfma_f32_32x32x16_bf16 v[18:33], v[212:215], v[228:231], v[18:33]
	ds_read_b128 v[212:215], v66 offset:4608
	ds_read_b128 v[236:239], v66 offset:4640
	s_waitcnt lgkmcnt(1)
	v_mfma_f32_32x32x16_bf16 v[34:49], v[212:215], v[216:219], v[34:49]
	v_mfma_f32_32x32x16_bf16 v[50:65], v[212:215], v[228:231], v[50:65]
	v_mfma_f32_32x32x16_bf16 v[2:17], v[220:223], v[224:227], v[2:17]
	v_mfma_f32_32x32x16_bf16 v[18:33], v[220:223], v[232:235], v[18:33]
	s_waitcnt lgkmcnt(0)
	v_mfma_f32_32x32x16_bf16 v[34:49], v[236:239], v[224:227], v[34:49]
	ds_read_b128 v[212:215], v66 offset:64
	ds_read_b128 v[216:219], v67 offset:36928
	ds_read_b128 v[220:223], v66 offset:96
	ds_read_b128 v[224:227], v67 offset:36960
	v_mfma_f32_32x32x16_bf16 v[50:65], v[236:239], v[232:235], v[50:65]
	ds_read_b128 v[228:231], v67 offset:41536
	ds_read_b128 v[232:235], v67 offset:41568
	s_waitcnt lgkmcnt(4)
	v_mfma_f32_32x32x16_bf16 v[2:17], v[212:215], v[216:219], v[2:17]
	s_waitcnt lgkmcnt(1)
	v_mfma_f32_32x32x16_bf16 v[18:33], v[212:215], v[228:231], v[18:33]
	ds_read_b128 v[212:215], v66 offset:4672
	ds_read_b128 v[236:239], v66 offset:4704
	s_waitcnt vmcnt(13)
	ds_write_b128 v1, v[156:159] offset:18432
	ds_write_b128 v1, v[148:151] offset:23040
	ds_write_b128 v1, v[152:155] offset:27648
	s_waitcnt vmcnt(11)
	ds_write_b128 v1, v[164:167] offset:32256
	ds_write_b128 v1, v[160:163] offset:55296
	s_waitcnt vmcnt(10)
	ds_write_b128 v1, v[168:171] offset:59904
	s_waitcnt vmcnt(9)
	ds_write_b128 v1, v[172:175] offset:64512
	s_waitcnt vmcnt(8)
	ds_write_b128 v92, v[176:179] offset:32256
	s_waitcnt lgkmcnt(0)
	s_barrier
	global_load_dwordx4 v[148:151], v[80:81], off offset:1152
	global_load_dwordx4 v[152:155], v[82:83], off offset:1152
	global_load_dwordx4 v[156:159], v[78:79], off offset:1152
	global_load_dwordx4 v[160:163], v[76:77], off offset:1152
	global_load_dwordx4 v[164:167], v[90:91], off offset:1152
	global_load_dwordx4 v[168:171], v[84:85], off offset:1152
	global_load_dwordx4 v[172:175], v[86:87], off offset:1152
	global_load_dwordx4 v[176:179], v[88:89], off offset:1152
	v_mfma_f32_32x32x16_bf16 v[34:49], v[212:215], v[216:219], v[34:49]
	v_mfma_f32_32x32x16_bf16 v[50:65], v[212:215], v[228:231], v[50:65]
	v_mfma_f32_32x32x16_bf16 v[2:17], v[220:223], v[224:227], v[2:17]
	v_mfma_f32_32x32x16_bf16 v[18:33], v[220:223], v[232:235], v[18:33]
	v_mfma_f32_32x32x16_bf16 v[34:49], v[236:239], v[224:227], v[34:49]
	v_mfma_f32_32x32x16_bf16 v[50:65], v[236:239], v[232:235], v[50:65]
	ds_read_b128 v[212:215], v66 offset:18432
	ds_read_b128 v[216:219], v67 offset:55296
	ds_read_b128 v[220:223], v66 offset:18464
	ds_read_b128 v[224:227], v67 offset:55328
	ds_read_b128 v[228:231], v67 offset:59904
	ds_read_b128 v[232:235], v67 offset:59936
	s_waitcnt lgkmcnt(4)
	v_mfma_f32_32x32x16_bf16 v[2:17], v[212:215], v[216:219], v[2:17]
	s_waitcnt lgkmcnt(1)
	v_mfma_f32_32x32x16_bf16 v[18:33], v[212:215], v[228:231], v[18:33]
	ds_read_b128 v[212:215], v66 offset:23040
	ds_read_b128 v[236:239], v66 offset:23072
	s_waitcnt lgkmcnt(1)
	v_mfma_f32_32x32x16_bf16 v[34:49], v[212:215], v[216:219], v[34:49]
	v_mfma_f32_32x32x16_bf16 v[50:65], v[212:215], v[228:231], v[50:65]
	v_mfma_f32_32x32x16_bf16 v[2:17], v[220:223], v[224:227], v[2:17]
	v_mfma_f32_32x32x16_bf16 v[18:33], v[220:223], v[232:235], v[18:33]
	s_waitcnt lgkmcnt(0)
	v_mfma_f32_32x32x16_bf16 v[34:49], v[236:239], v[224:227], v[34:49]
	ds_read_b128 v[212:215], v66 offset:18496
	ds_read_b128 v[216:219], v67 offset:55360
	ds_read_b128 v[220:223], v66 offset:18528
	ds_read_b128 v[224:227], v67 offset:55392
	v_mfma_f32_32x32x16_bf16 v[50:65], v[236:239], v[232:235], v[50:65]
	ds_read_b128 v[228:231], v67 offset:59968
	ds_read_b128 v[232:235], v67 offset:60000
	s_waitcnt lgkmcnt(4)
	v_mfma_f32_32x32x16_bf16 v[2:17], v[212:215], v[216:219], v[2:17]
	s_waitcnt lgkmcnt(1)
	v_mfma_f32_32x32x16_bf16 v[18:33], v[212:215], v[228:231], v[18:33]
	ds_read_b128 v[212:215], v66 offset:23104
	ds_read_b128 v[236:239], v66 offset:23136
	s_waitcnt vmcnt(13)
	ds_write_b128 v1, v[188:191]
	ds_write_b128 v1, v[180:183] offset:4608
	ds_write_b128 v1, v[184:187] offset:9216
	s_waitcnt vmcnt(11)
	ds_write_b128 v1, v[196:199] offset:13824
	ds_write_b128 v1, v[192:195] offset:36864
	s_waitcnt vmcnt(10)
	ds_write_b128 v1, v[200:203] offset:41472
	s_waitcnt vmcnt(9)
	ds_write_b128 v1, v[204:207] offset:46080
	s_waitcnt vmcnt(8)
	ds_write_b128 v1, v[208:211] offset:50688
	s_waitcnt lgkmcnt(0)
	s_barrier
	global_load_dwordx4 v[180:183], v[80:81], off offset:1280
	global_load_dwordx4 v[184:187], v[82:83], off offset:1280
	global_load_dwordx4 v[188:191], v[78:79], off offset:1280
	global_load_dwordx4 v[192:195], v[76:77], off offset:1280
	global_load_dwordx4 v[196:199], v[90:91], off offset:1280
	global_load_dwordx4 v[200:203], v[84:85], off offset:1280
	global_load_dwordx4 v[204:207], v[86:87], off offset:1280
	global_load_dwordx4 v[208:211], v[88:89], off offset:1280
	v_mfma_f32_32x32x16_bf16 v[34:49], v[212:215], v[216:219], v[34:49]
	v_mfma_f32_32x32x16_bf16 v[50:65], v[212:215], v[228:231], v[50:65]
	v_mfma_f32_32x32x16_bf16 v[2:17], v[220:223], v[224:227], v[2:17]
	v_mfma_f32_32x32x16_bf16 v[18:33], v[220:223], v[232:235], v[18:33]
	v_mfma_f32_32x32x16_bf16 v[34:49], v[236:239], v[224:227], v[34:49]
	v_mfma_f32_32x32x16_bf16 v[50:65], v[236:239], v[232:235], v[50:65]
	ds_read_b128 v[212:215], v66
	ds_read_b128 v[216:219], v67 offset:36864
	ds_read_b128 v[220:223], v66 offset:32
	ds_read_b128 v[224:227], v67 offset:36896
	ds_read_b128 v[228:231], v67 offset:41472
	ds_read_b128 v[232:235], v67 offset:41504
	s_waitcnt lgkmcnt(4)
	v_mfma_f32_32x32x16_bf16 v[2:17], v[212:215], v[216:219], v[2:17]
	s_waitcnt lgkmcnt(1)
	v_mfma_f32_32x32x16_bf16 v[18:33], v[212:215], v[228:231], v[18:33]
	ds_read_b128 v[212:215], v66 offset:4608
	ds_read_b128 v[236:239], v66 offset:4640
	s_waitcnt lgkmcnt(1)
	v_mfma_f32_32x32x16_bf16 v[34:49], v[212:215], v[216:219], v[34:49]
	v_mfma_f32_32x32x16_bf16 v[50:65], v[212:215], v[228:231], v[50:65]
	v_mfma_f32_32x32x16_bf16 v[2:17], v[220:223], v[224:227], v[2:17]
	v_mfma_f32_32x32x16_bf16 v[18:33], v[220:223], v[232:235], v[18:33]
	s_waitcnt lgkmcnt(0)
	v_mfma_f32_32x32x16_bf16 v[34:49], v[236:239], v[224:227], v[34:49]
	ds_read_b128 v[212:215], v66 offset:64
	ds_read_b128 v[216:219], v67 offset:36928
	ds_read_b128 v[220:223], v66 offset:96
	ds_read_b128 v[224:227], v67 offset:36960
	v_mfma_f32_32x32x16_bf16 v[50:65], v[236:239], v[232:235], v[50:65]
	ds_read_b128 v[228:231], v67 offset:41536
	ds_read_b128 v[232:235], v67 offset:41568
	s_waitcnt lgkmcnt(4)
	v_mfma_f32_32x32x16_bf16 v[2:17], v[212:215], v[216:219], v[2:17]
	s_waitcnt lgkmcnt(1)
	v_mfma_f32_32x32x16_bf16 v[18:33], v[212:215], v[228:231], v[18:33]
	ds_read_b128 v[212:215], v66 offset:4672
	ds_read_b128 v[236:239], v66 offset:4704
	s_waitcnt vmcnt(13)
	ds_write_b128 v1, v[156:159] offset:18432
	ds_write_b128 v1, v[148:151] offset:23040
	ds_write_b128 v1, v[152:155] offset:27648
	s_waitcnt vmcnt(11)
	ds_write_b128 v1, v[164:167] offset:32256
	ds_write_b128 v1, v[160:163] offset:55296
	s_waitcnt vmcnt(10)
	ds_write_b128 v1, v[168:171] offset:59904
	s_waitcnt vmcnt(9)
	ds_write_b128 v1, v[172:175] offset:64512
	s_waitcnt vmcnt(8)
	ds_write_b128 v92, v[176:179] offset:32256
	s_waitcnt lgkmcnt(0)
	s_barrier
	global_load_dwordx4 v[148:151], v[80:81], off offset:1408
	global_load_dwordx4 v[152:155], v[82:83], off offset:1408
	global_load_dwordx4 v[156:159], v[78:79], off offset:1408
	global_load_dwordx4 v[160:163], v[76:77], off offset:1408
	global_load_dwordx4 v[164:167], v[90:91], off offset:1408
	global_load_dwordx4 v[168:171], v[84:85], off offset:1408
	global_load_dwordx4 v[172:175], v[86:87], off offset:1408
	global_load_dwordx4 v[176:179], v[88:89], off offset:1408
	v_mfma_f32_32x32x16_bf16 v[34:49], v[212:215], v[216:219], v[34:49]
	v_mfma_f32_32x32x16_bf16 v[50:65], v[212:215], v[228:231], v[50:65]
	v_mfma_f32_32x32x16_bf16 v[2:17], v[220:223], v[224:227], v[2:17]
	v_mfma_f32_32x32x16_bf16 v[18:33], v[220:223], v[232:235], v[18:33]
	v_mfma_f32_32x32x16_bf16 v[34:49], v[236:239], v[224:227], v[34:49]
	v_mfma_f32_32x32x16_bf16 v[50:65], v[236:239], v[232:235], v[50:65]
	ds_read_b128 v[212:215], v66 offset:18432
	ds_read_b128 v[216:219], v67 offset:55296
	ds_read_b128 v[220:223], v66 offset:18464
	ds_read_b128 v[224:227], v67 offset:55328
	ds_read_b128 v[228:231], v67 offset:59904
	ds_read_b128 v[232:235], v67 offset:59936
	s_waitcnt lgkmcnt(4)
	v_mfma_f32_32x32x16_bf16 v[2:17], v[212:215], v[216:219], v[2:17]
	s_waitcnt lgkmcnt(1)
	v_mfma_f32_32x32x16_bf16 v[18:33], v[212:215], v[228:231], v[18:33]
	ds_read_b128 v[212:215], v66 offset:23040
	ds_read_b128 v[236:239], v66 offset:23072
	s_waitcnt lgkmcnt(1)
	v_mfma_f32_32x32x16_bf16 v[34:49], v[212:215], v[216:219], v[34:49]
	v_mfma_f32_32x32x16_bf16 v[50:65], v[212:215], v[228:231], v[50:65]
	v_mfma_f32_32x32x16_bf16 v[2:17], v[220:223], v[224:227], v[2:17]
	v_mfma_f32_32x32x16_bf16 v[18:33], v[220:223], v[232:235], v[18:33]
	s_waitcnt lgkmcnt(0)
	v_mfma_f32_32x32x16_bf16 v[34:49], v[236:239], v[224:227], v[34:49]
	ds_read_b128 v[212:215], v66 offset:18496
	ds_read_b128 v[216:219], v67 offset:55360
	ds_read_b128 v[220:223], v66 offset:18528
	ds_read_b128 v[224:227], v67 offset:55392
	v_mfma_f32_32x32x16_bf16 v[50:65], v[236:239], v[232:235], v[50:65]
	ds_read_b128 v[228:231], v67 offset:59968
	ds_read_b128 v[232:235], v67 offset:60000
	s_waitcnt lgkmcnt(4)
	v_mfma_f32_32x32x16_bf16 v[2:17], v[212:215], v[216:219], v[2:17]
	s_waitcnt lgkmcnt(1)
	v_mfma_f32_32x32x16_bf16 v[18:33], v[212:215], v[228:231], v[18:33]
	ds_read_b128 v[212:215], v66 offset:23104
	ds_read_b128 v[236:239], v66 offset:23136
	s_waitcnt vmcnt(13)
	ds_write_b128 v1, v[188:191]
	ds_write_b128 v1, v[180:183] offset:4608
	ds_write_b128 v1, v[184:187] offset:9216
	s_waitcnt vmcnt(11)
	ds_write_b128 v1, v[196:199] offset:13824
	ds_write_b128 v1, v[192:195] offset:36864
	s_waitcnt vmcnt(10)
	ds_write_b128 v1, v[200:203] offset:41472
	s_waitcnt vmcnt(9)
	ds_write_b128 v1, v[204:207] offset:46080
	s_waitcnt vmcnt(8)
	ds_write_b128 v1, v[208:211] offset:50688
	s_waitcnt lgkmcnt(0)
	s_barrier
	global_load_dwordx4 v[180:183], v[80:81], off offset:1536
	global_load_dwordx4 v[184:187], v[82:83], off offset:1536
	global_load_dwordx4 v[188:191], v[78:79], off offset:1536
	global_load_dwordx4 v[192:195], v[76:77], off offset:1536
	global_load_dwordx4 v[196:199], v[90:91], off offset:1536
	global_load_dwordx4 v[200:203], v[84:85], off offset:1536
	global_load_dwordx4 v[204:207], v[86:87], off offset:1536
	global_load_dwordx4 v[208:211], v[88:89], off offset:1536
	v_mfma_f32_32x32x16_bf16 v[34:49], v[212:215], v[216:219], v[34:49]
	v_mfma_f32_32x32x16_bf16 v[50:65], v[212:215], v[228:231], v[50:65]
	v_mfma_f32_32x32x16_bf16 v[2:17], v[220:223], v[224:227], v[2:17]
	v_mfma_f32_32x32x16_bf16 v[18:33], v[220:223], v[232:235], v[18:33]
	v_mfma_f32_32x32x16_bf16 v[34:49], v[236:239], v[224:227], v[34:49]
	v_mfma_f32_32x32x16_bf16 v[50:65], v[236:239], v[232:235], v[50:65]
	ds_read_b128 v[212:215], v66
	ds_read_b128 v[216:219], v67 offset:36864
	ds_read_b128 v[220:223], v66 offset:32
	ds_read_b128 v[224:227], v67 offset:36896
	ds_read_b128 v[228:231], v67 offset:41472
	ds_read_b128 v[232:235], v67 offset:41504
	s_waitcnt lgkmcnt(4)
	v_mfma_f32_32x32x16_bf16 v[2:17], v[212:215], v[216:219], v[2:17]
	s_waitcnt lgkmcnt(1)
	v_mfma_f32_32x32x16_bf16 v[18:33], v[212:215], v[228:231], v[18:33]
	ds_read_b128 v[212:215], v66 offset:4608
	ds_read_b128 v[236:239], v66 offset:4640
	s_waitcnt lgkmcnt(1)
	v_mfma_f32_32x32x16_bf16 v[34:49], v[212:215], v[216:219], v[34:49]
	v_mfma_f32_32x32x16_bf16 v[50:65], v[212:215], v[228:231], v[50:65]
	v_mfma_f32_32x32x16_bf16 v[2:17], v[220:223], v[224:227], v[2:17]
	v_mfma_f32_32x32x16_bf16 v[18:33], v[220:223], v[232:235], v[18:33]
	s_waitcnt lgkmcnt(0)
	v_mfma_f32_32x32x16_bf16 v[34:49], v[236:239], v[224:227], v[34:49]
	ds_read_b128 v[212:215], v66 offset:64
	ds_read_b128 v[216:219], v67 offset:36928
	ds_read_b128 v[220:223], v66 offset:96
	ds_read_b128 v[224:227], v67 offset:36960
	v_mfma_f32_32x32x16_bf16 v[50:65], v[236:239], v[232:235], v[50:65]
	ds_read_b128 v[228:231], v67 offset:41536
	ds_read_b128 v[232:235], v67 offset:41568
	s_waitcnt lgkmcnt(4)
	v_mfma_f32_32x32x16_bf16 v[2:17], v[212:215], v[216:219], v[2:17]
	s_waitcnt lgkmcnt(1)
	v_mfma_f32_32x32x16_bf16 v[18:33], v[212:215], v[228:231], v[18:33]
	ds_read_b128 v[212:215], v66 offset:4672
	ds_read_b128 v[236:239], v66 offset:4704
	s_waitcnt vmcnt(13)
	ds_write_b128 v1, v[156:159] offset:18432
	ds_write_b128 v1, v[148:151] offset:23040
	ds_write_b128 v1, v[152:155] offset:27648
	s_waitcnt vmcnt(11)
	ds_write_b128 v1, v[164:167] offset:32256
	ds_write_b128 v1, v[160:163] offset:55296
	s_waitcnt vmcnt(10)
	ds_write_b128 v1, v[168:171] offset:59904
	s_waitcnt vmcnt(9)
	ds_write_b128 v1, v[172:175] offset:64512
	s_waitcnt vmcnt(8)
	ds_write_b128 v92, v[176:179] offset:32256
	s_waitcnt lgkmcnt(0)
	s_barrier
	global_load_dwordx4 v[148:151], v[80:81], off offset:1664
	global_load_dwordx4 v[152:155], v[82:83], off offset:1664
	global_load_dwordx4 v[156:159], v[78:79], off offset:1664
	global_load_dwordx4 v[160:163], v[76:77], off offset:1664
	global_load_dwordx4 v[164:167], v[90:91], off offset:1664
	global_load_dwordx4 v[168:171], v[84:85], off offset:1664
	global_load_dwordx4 v[172:175], v[86:87], off offset:1664
	global_load_dwordx4 v[176:179], v[88:89], off offset:1664
	v_mfma_f32_32x32x16_bf16 v[34:49], v[212:215], v[216:219], v[34:49]
	v_mfma_f32_32x32x16_bf16 v[50:65], v[212:215], v[228:231], v[50:65]
	v_mfma_f32_32x32x16_bf16 v[2:17], v[220:223], v[224:227], v[2:17]
	v_mfma_f32_32x32x16_bf16 v[18:33], v[220:223], v[232:235], v[18:33]
	v_mfma_f32_32x32x16_bf16 v[34:49], v[236:239], v[224:227], v[34:49]
	v_mfma_f32_32x32x16_bf16 v[50:65], v[236:239], v[232:235], v[50:65]
	ds_read_b128 v[212:215], v66 offset:18432
	ds_read_b128 v[216:219], v67 offset:55296
	ds_read_b128 v[220:223], v66 offset:18464
	ds_read_b128 v[224:227], v67 offset:55328
	ds_read_b128 v[228:231], v67 offset:59904
	ds_read_b128 v[232:235], v67 offset:59936
	s_waitcnt lgkmcnt(4)
	v_mfma_f32_32x32x16_bf16 v[2:17], v[212:215], v[216:219], v[2:17]
	s_waitcnt lgkmcnt(1)
	v_mfma_f32_32x32x16_bf16 v[18:33], v[212:215], v[228:231], v[18:33]
	ds_read_b128 v[212:215], v66 offset:23040
	ds_read_b128 v[236:239], v66 offset:23072
	s_waitcnt lgkmcnt(1)
	v_mfma_f32_32x32x16_bf16 v[34:49], v[212:215], v[216:219], v[34:49]
	v_mfma_f32_32x32x16_bf16 v[50:65], v[212:215], v[228:231], v[50:65]
	v_mfma_f32_32x32x16_bf16 v[2:17], v[220:223], v[224:227], v[2:17]
	v_mfma_f32_32x32x16_bf16 v[18:33], v[220:223], v[232:235], v[18:33]
	s_waitcnt lgkmcnt(0)
	v_mfma_f32_32x32x16_bf16 v[34:49], v[236:239], v[224:227], v[34:49]
	ds_read_b128 v[212:215], v66 offset:18496
	ds_read_b128 v[216:219], v67 offset:55360
	ds_read_b128 v[220:223], v66 offset:18528
	ds_read_b128 v[224:227], v67 offset:55392
	v_mfma_f32_32x32x16_bf16 v[50:65], v[236:239], v[232:235], v[50:65]
	ds_read_b128 v[228:231], v67 offset:59968
	ds_read_b128 v[232:235], v67 offset:60000
	s_waitcnt lgkmcnt(4)
	v_mfma_f32_32x32x16_bf16 v[2:17], v[212:215], v[216:219], v[2:17]
	s_waitcnt lgkmcnt(1)
	v_mfma_f32_32x32x16_bf16 v[18:33], v[212:215], v[228:231], v[18:33]
	ds_read_b128 v[212:215], v66 offset:23104
	ds_read_b128 v[236:239], v66 offset:23136
	s_waitcnt vmcnt(13)
	ds_write_b128 v1, v[188:191]
	ds_write_b128 v1, v[180:183] offset:4608
	ds_write_b128 v1, v[184:187] offset:9216
	s_waitcnt vmcnt(11)
	ds_write_b128 v1, v[196:199] offset:13824
	ds_write_b128 v1, v[192:195] offset:36864
	s_waitcnt vmcnt(10)
	ds_write_b128 v1, v[200:203] offset:41472
	s_waitcnt vmcnt(9)
	ds_write_b128 v1, v[204:207] offset:46080
	s_waitcnt vmcnt(8)
	ds_write_b128 v1, v[208:211] offset:50688
	s_waitcnt lgkmcnt(0)
	s_barrier
	global_load_dwordx4 v[180:183], v[80:81], off offset:1792
	global_load_dwordx4 v[184:187], v[82:83], off offset:1792
	global_load_dwordx4 v[188:191], v[78:79], off offset:1792
	global_load_dwordx4 v[192:195], v[76:77], off offset:1792
	global_load_dwordx4 v[196:199], v[90:91], off offset:1792
	global_load_dwordx4 v[200:203], v[84:85], off offset:1792
	global_load_dwordx4 v[204:207], v[86:87], off offset:1792
	global_load_dwordx4 v[208:211], v[88:89], off offset:1792
	v_mfma_f32_32x32x16_bf16 v[34:49], v[212:215], v[216:219], v[34:49]
	v_mfma_f32_32x32x16_bf16 v[50:65], v[212:215], v[228:231], v[50:65]
	v_mfma_f32_32x32x16_bf16 v[2:17], v[220:223], v[224:227], v[2:17]
	v_mfma_f32_32x32x16_bf16 v[18:33], v[220:223], v[232:235], v[18:33]
	v_mfma_f32_32x32x16_bf16 v[34:49], v[236:239], v[224:227], v[34:49]
	v_mfma_f32_32x32x16_bf16 v[50:65], v[236:239], v[232:235], v[50:65]
	ds_read_b128 v[212:215], v66
	ds_read_b128 v[216:219], v67 offset:36864
	ds_read_b128 v[220:223], v66 offset:32
	ds_read_b128 v[224:227], v67 offset:36896
	ds_read_b128 v[228:231], v67 offset:41472
	ds_read_b128 v[232:235], v67 offset:41504
	s_waitcnt lgkmcnt(4)
	v_mfma_f32_32x32x16_bf16 v[2:17], v[212:215], v[216:219], v[2:17]
	s_waitcnt lgkmcnt(1)
	v_mfma_f32_32x32x16_bf16 v[18:33], v[212:215], v[228:231], v[18:33]
	ds_read_b128 v[212:215], v66 offset:4608
	ds_read_b128 v[236:239], v66 offset:4640
	s_waitcnt lgkmcnt(1)
	v_mfma_f32_32x32x16_bf16 v[34:49], v[212:215], v[216:219], v[34:49]
	v_mfma_f32_32x32x16_bf16 v[50:65], v[212:215], v[228:231], v[50:65]
	v_mfma_f32_32x32x16_bf16 v[2:17], v[220:223], v[224:227], v[2:17]
	v_mfma_f32_32x32x16_bf16 v[18:33], v[220:223], v[232:235], v[18:33]
	s_waitcnt lgkmcnt(0)
	v_mfma_f32_32x32x16_bf16 v[34:49], v[236:239], v[224:227], v[34:49]
	ds_read_b128 v[212:215], v66 offset:64
	ds_read_b128 v[216:219], v67 offset:36928
	ds_read_b128 v[220:223], v66 offset:96
	ds_read_b128 v[224:227], v67 offset:36960
	v_mfma_f32_32x32x16_bf16 v[50:65], v[236:239], v[232:235], v[50:65]
	ds_read_b128 v[228:231], v67 offset:41536
	ds_read_b128 v[232:235], v67 offset:41568
	s_waitcnt lgkmcnt(4)
	v_mfma_f32_32x32x16_bf16 v[2:17], v[212:215], v[216:219], v[2:17]
	s_waitcnt lgkmcnt(1)
	v_mfma_f32_32x32x16_bf16 v[18:33], v[212:215], v[228:231], v[18:33]
	ds_read_b128 v[212:215], v66 offset:4672
	ds_read_b128 v[236:239], v66 offset:4704
	s_waitcnt vmcnt(13)
	ds_write_b128 v1, v[156:159] offset:18432
	ds_write_b128 v1, v[148:151] offset:23040
	ds_write_b128 v1, v[152:155] offset:27648
	s_waitcnt vmcnt(11)
	ds_write_b128 v1, v[164:167] offset:32256
	ds_write_b128 v1, v[160:163] offset:55296
	s_waitcnt vmcnt(10)
	ds_write_b128 v1, v[168:171] offset:59904
	s_waitcnt vmcnt(9)
	ds_write_b128 v1, v[172:175] offset:64512
	s_waitcnt vmcnt(8)
	ds_write_b128 v92, v[176:179] offset:32256
	s_waitcnt lgkmcnt(0)
	s_barrier
	global_load_dwordx4 v[148:151], v[80:81], off offset:1920
	s_nop 0
	global_load_dwordx4 v[80:83], v[82:83], off offset:1920
	s_nop 0
	global_load_dwordx4 v[152:155], v[78:79], off offset:1920
	s_nop 0
	global_load_dwordx4 v[76:79], v[76:77], off offset:1920
	s_nop 0
	global_load_dwordx4 v[156:159], v[90:91], off offset:1920
	global_load_dwordx4 v[160:163], v[84:85], off offset:1920
	s_nop 0
	global_load_dwordx4 v[84:87], v[86:87], off offset:1920
	s_nop 0
	global_load_dwordx4 v[88:91], v[88:89], off offset:1920
	v_mfma_f32_32x32x16_bf16 v[34:49], v[212:215], v[216:219], v[34:49]
	v_mfma_f32_32x32x16_bf16 v[50:65], v[212:215], v[228:231], v[50:65]
	v_mfma_f32_32x32x16_bf16 v[2:17], v[220:223], v[224:227], v[2:17]
	v_mfma_f32_32x32x16_bf16 v[18:33], v[220:223], v[232:235], v[18:33]
	v_mfma_f32_32x32x16_bf16 v[34:49], v[236:239], v[224:227], v[34:49]
	v_mfma_f32_32x32x16_bf16 v[50:65], v[236:239], v[232:235], v[50:65]
	ds_read_b128 v[164:167], v66 offset:18432
	ds_read_b128 v[168:171], v67 offset:55296
	ds_read_b128 v[172:175], v66 offset:18464
	ds_read_b128 v[176:179], v67 offset:55328
	ds_read_b128 v[212:215], v67 offset:59904
	ds_read_b128 v[216:219], v67 offset:59936
	s_waitcnt lgkmcnt(4)
	v_mfma_f32_32x32x16_bf16 v[2:17], v[164:167], v[168:171], v[2:17]
	s_waitcnt lgkmcnt(1)
	v_mfma_f32_32x32x16_bf16 v[18:33], v[164:167], v[212:215], v[18:33]
	ds_read_b128 v[164:167], v66 offset:23040
	ds_read_b128 v[220:223], v66 offset:23072
	s_waitcnt lgkmcnt(1)
	v_mfma_f32_32x32x16_bf16 v[34:49], v[164:167], v[168:171], v[34:49]
	v_mfma_f32_32x32x16_bf16 v[50:65], v[164:167], v[212:215], v[50:65]
	v_mfma_f32_32x32x16_bf16 v[2:17], v[172:175], v[176:179], v[2:17]
	v_mfma_f32_32x32x16_bf16 v[18:33], v[172:175], v[216:219], v[18:33]
	s_waitcnt lgkmcnt(0)
	v_mfma_f32_32x32x16_bf16 v[34:49], v[220:223], v[176:179], v[34:49]
	ds_read_b128 v[164:167], v66 offset:18496
	ds_read_b128 v[168:171], v67 offset:55360
	ds_read_b128 v[172:175], v66 offset:18528
	ds_read_b128 v[176:179], v67 offset:55392
	v_mfma_f32_32x32x16_bf16 v[50:65], v[220:223], v[216:219], v[50:65]
	ds_read_b128 v[212:215], v67 offset:59968
	ds_read_b128 v[216:219], v67 offset:60000
	s_waitcnt lgkmcnt(4)
	v_mfma_f32_32x32x16_bf16 v[2:17], v[164:167], v[168:171], v[2:17]
	s_waitcnt lgkmcnt(1)
	v_mfma_f32_32x32x16_bf16 v[18:33], v[164:167], v[212:215], v[18:33]
	ds_read_b128 v[164:167], v66 offset:23104
	ds_read_b128 v[220:223], v66 offset:23136
	s_waitcnt vmcnt(13)
	ds_write_b128 v1, v[188:191]
	ds_write_b128 v1, v[180:183] offset:4608
	ds_write_b128 v1, v[184:187] offset:9216
	s_waitcnt vmcnt(11)
	ds_write_b128 v1, v[196:199] offset:13824
	ds_write_b128 v1, v[192:195] offset:36864
	s_waitcnt vmcnt(10)
	ds_write_b128 v1, v[200:203] offset:41472
	s_waitcnt vmcnt(9)
	ds_write_b128 v1, v[204:207] offset:46080
	s_waitcnt vmcnt(8)
	ds_write_b128 v1, v[208:211] offset:50688
	s_waitcnt lgkmcnt(0)
	s_barrier
	v_mfma_f32_32x32x16_bf16 v[34:49], v[164:167], v[168:171], v[34:49]
	v_mfma_f32_32x32x16_bf16 v[50:65], v[164:167], v[212:215], v[50:65]
	v_mfma_f32_32x32x16_bf16 v[2:17], v[172:175], v[176:179], v[2:17]
	v_mfma_f32_32x32x16_bf16 v[18:33], v[172:175], v[216:219], v[18:33]
	v_mfma_f32_32x32x16_bf16 v[34:49], v[220:223], v[176:179], v[34:49]
	v_mfma_f32_32x32x16_bf16 v[50:65], v[220:223], v[216:219], v[50:65]
	ds_read_b128 v[164:167], v66
	ds_read_b128 v[168:171], v67 offset:36864
	ds_read_b128 v[172:175], v66 offset:32
	ds_read_b128 v[176:179], v67 offset:36896
	ds_read_b128 v[180:183], v67 offset:41472
	ds_read_b128 v[184:187], v67 offset:41504
	s_waitcnt lgkmcnt(4)
	v_mfma_f32_32x32x16_bf16 v[2:17], v[164:167], v[168:171], v[2:17]
	s_waitcnt lgkmcnt(1)
	v_mfma_f32_32x32x16_bf16 v[18:33], v[164:167], v[180:183], v[18:33]
	ds_read_b128 v[164:167], v66 offset:4608
	ds_read_b128 v[188:191], v66 offset:4640
	s_waitcnt lgkmcnt(1)
	v_mfma_f32_32x32x16_bf16 v[34:49], v[164:167], v[168:171], v[34:49]
	v_mfma_f32_32x32x16_bf16 v[50:65], v[164:167], v[180:183], v[50:65]
	v_mfma_f32_32x32x16_bf16 v[2:17], v[172:175], v[176:179], v[2:17]
	v_mfma_f32_32x32x16_bf16 v[18:33], v[172:175], v[184:187], v[18:33]
	s_waitcnt lgkmcnt(0)
	v_mfma_f32_32x32x16_bf16 v[34:49], v[188:191], v[176:179], v[34:49]
	ds_read_b128 v[164:167], v66 offset:64
	ds_read_b128 v[168:171], v67 offset:36928
	ds_read_b128 v[172:175], v66 offset:96
	ds_read_b128 v[176:179], v67 offset:36960
	v_mfma_f32_32x32x16_bf16 v[50:65], v[188:191], v[184:187], v[50:65]
	ds_read_b128 v[180:183], v67 offset:41536
	ds_read_b128 v[184:187], v67 offset:41568
	s_waitcnt lgkmcnt(4)
	v_mfma_f32_32x32x16_bf16 v[2:17], v[164:167], v[168:171], v[2:17]
	s_waitcnt lgkmcnt(1)
	v_mfma_f32_32x32x16_bf16 v[18:33], v[164:167], v[180:183], v[18:33]
	ds_read_b128 v[164:167], v66 offset:4672
	ds_read_b128 v[188:191], v66 offset:4704
	s_waitcnt vmcnt(5)
	ds_write_b128 v1, v[152:155] offset:18432
	ds_write_b128 v1, v[148:151] offset:23040
	ds_write_b128 v1, v[80:83] offset:27648
	s_waitcnt vmcnt(3)
	ds_write_b128 v1, v[156:159] offset:32256
	ds_write_b128 v1, v[76:79] offset:55296
	s_waitcnt vmcnt(2)
	ds_write_b128 v1, v[160:163] offset:59904
	s_waitcnt vmcnt(1)
	ds_write_b128 v1, v[84:87] offset:64512
	s_waitcnt vmcnt(0)
	ds_write_b128 v92, v[88:91] offset:32256
	s_waitcnt lgkmcnt(0)
	s_barrier
	v_mfma_f32_32x32x16_bf16 v[34:49], v[164:167], v[168:171], v[34:49]
	v_mfma_f32_32x32x16_bf16 v[50:65], v[164:167], v[180:183], v[50:65]
	v_mfma_f32_32x32x16_bf16 v[2:17], v[172:175], v[176:179], v[2:17]
	v_mfma_f32_32x32x16_bf16 v[18:33], v[172:175], v[184:187], v[18:33]
	v_mfma_f32_32x32x16_bf16 v[34:49], v[188:191], v[176:179], v[34:49]
	v_mfma_f32_32x32x16_bf16 v[50:65], v[188:191], v[184:187], v[50:65]
	ds_read_b128 v[76:79], v66 offset:18432
	ds_read_b128 v[80:83], v67 offset:55296
	ds_read_b128 v[84:87], v66 offset:18464
	ds_read_b128 v[88:91], v67 offset:55328
	ds_read_b128 v[148:151], v67 offset:59904
	ds_read_b128 v[152:155], v67 offset:59936
	v_or_b32_e32 v68, s8, v94
	s_waitcnt lgkmcnt(4)
	v_mfma_f32_32x32x16_bf16 v[2:17], v[76:79], v[80:83], v[2:17]
	s_lshl_b32 s10, s10, 1
	s_mov_b32 s11, s9
	s_add_i32 s12, s12, s13
	s_add_i32 s14, s14, s15
	s_add_i32 s16, s16, s17
	s_cmpk_lt_u32 s12, 0x400
	s_waitcnt lgkmcnt(1)
	v_mfma_f32_32x32x16_bf16 v[18:33], v[76:79], v[148:151], v[18:33]
	ds_read_b128 v[76:79], v66 offset:23040
	ds_read_b128 v[156:159], v66 offset:23072
	s_waitcnt lgkmcnt(1)
	v_mfma_f32_32x32x16_bf16 v[34:49], v[76:79], v[80:83], v[34:49]
	v_mfma_f32_32x32x16_bf16 v[50:65], v[76:79], v[148:151], v[50:65]
	v_mfma_f32_32x32x16_bf16 v[2:17], v[84:87], v[88:91], v[2:17]
	v_mfma_f32_32x32x16_bf16 v[18:33], v[84:87], v[152:155], v[18:33]
	s_waitcnt lgkmcnt(0)
	v_mfma_f32_32x32x16_bf16 v[34:49], v[156:159], v[88:91], v[34:49]
	ds_read_b128 v[76:79], v66 offset:18496
	ds_read_b128 v[80:83], v67 offset:55360
	ds_read_b128 v[84:87], v66 offset:18528
	ds_read_b128 v[88:91], v67 offset:55392
	v_mfma_f32_32x32x16_bf16 v[50:65], v[156:159], v[152:155], v[50:65]
	ds_read_b128 v[148:151], v67 offset:59968
	ds_read_b128 v[152:155], v67 offset:60000
	s_waitcnt lgkmcnt(4)
	v_mfma_f32_32x32x16_bf16 v[2:17], v[76:79], v[80:83], v[2:17]
	s_waitcnt lgkmcnt(1)
	v_mfma_f32_32x32x16_bf16 v[18:33], v[76:79], v[148:151], v[18:33]
	ds_read_b128 v[76:79], v66 offset:23104
	ds_read_b128 v[156:159], v66 offset:23136
	s_waitcnt lgkmcnt(0)
	s_barrier
	v_mfma_f32_32x32x16_bf16 v[34:49], v[76:79], v[80:83], v[34:49]
	v_mfma_f32_32x32x16_bf16 v[50:65], v[76:79], v[148:151], v[50:65]
	v_mfma_f32_32x32x16_bf16 v[2:17], v[84:87], v[88:91], v[2:17]
	v_mfma_f32_32x32x16_bf16 v[18:33], v[84:87], v[152:155], v[18:33]
	v_mfma_f32_32x32x16_bf16 v[34:49], v[156:159], v[88:91], v[34:49]
	s_nop 10
	ds_write2_b32 v93, v2, v18 offset1:32
	v_mfma_f32_32x32x16_bf16 v[50:65], v[156:159], v[152:155], v[50:65]
	s_nop 11
	ds_write2_b32 v132, v34, v50 offset0:32 offset1:64
	ds_write2_b32 v93, v3, v19 offset0:129 offset1:161
	ds_write2_b32 v132, v35, v51 offset0:161 offset1:193
	ds_write2_b32 v133, v4, v20 offset0:2 offset1:34
	ds_write2_b32 v134, v36, v52 offset0:34 offset1:66
	ds_write2_b32 v133, v5, v21 offset0:131 offset1:163
	ds_write2_b32 v134, v37, v53 offset0:163 offset1:195
	ds_write2_b32 v135, v6, v22 offset0:8 offset1:40
	ds_write2_b32 v136, v38, v54 offset0:40 offset1:72
	ds_write2_b32 v135, v7, v23 offset0:137 offset1:169
	ds_write2_b32 v136, v39, v55 offset0:169 offset1:201
	ds_write2_b32 v137, v8, v24 offset0:10 offset1:42
	ds_write2_b32 v138, v40, v56 offset0:42 offset1:74
	ds_write2_b32 v137, v9, v25 offset0:139 offset1:171
	ds_write2_b32 v138, v41, v57 offset0:171 offset1:203
	ds_write2_b32 v139, v10, v26 offset0:16 offset1:48
	ds_write2_b32 v140, v42, v58 offset0:48 offset1:80
	ds_write2_b32 v139, v11, v27 offset0:145 offset1:177
	ds_write2_b32 v140, v43, v59 offset0:177 offset1:209
	ds_write2_b32 v141, v12, v28 offset0:18 offset1:50
	ds_write2_b32 v142, v44, v60 offset0:50 offset1:82
	ds_write2_b32 v141, v13, v29 offset0:147 offset1:179
	ds_write2_b32 v142, v45, v61 offset0:179 offset1:211
	ds_write2_b32 v143, v14, v30 offset0:24 offset1:56
	ds_write2_b32 v144, v46, v62 offset0:56 offset1:88
	ds_write2_b32 v143, v15, v31 offset0:153 offset1:185
	ds_write2_b32 v144, v47, v63 offset0:185 offset1:217
	ds_write2_b32 v145, v16, v32 offset0:26 offset1:58
	ds_write2_b32 v146, v48, v64 offset0:58 offset1:90
	ds_write2_b32 v145, v17, v33 offset0:155 offset1:187
	ds_write2_b32 v146, v49, v65 offset0:187 offset1:219
	v_lshl_add_u64 v[2:3], v[68:69], 2, s[6:7]
	s_waitcnt lgkmcnt(0)
	s_barrier
	v_mov_b32_e32 v2, v68
	v_lshlrev_b32_e32 v3, 2, v2
	global_load_dword v5, v3, s[6:7]
	global_load_dword v6, v3, s[6:7] offset:64
	global_load_dword v7, v3, s[6:7] offset:128
	global_load_dword v8, v3, s[6:7] offset:192
	global_load_dword v9, v3, s[6:7] offset:256
	global_load_dword v10, v3, s[6:7] offset:320
	global_load_dword v11, v3, s[6:7] offset:384
	global_load_dword v12, v3, s[6:7] offset:448
	v_lshlrev_b32_e32 v4, 13, v2
	v_add3_u32 v4, v4, v74, s10
	s_movk_i32 s24, 0x7fff
	v_mov_b32_e32 v59, 1
	v_mov_b32_e32 v13, 0x358637bd
	ds_read2_b32 v[14:15], v103 offset0:0 offset1:1
	ds_read2_b32 v[16:17], v103 offset0:2 offset1:3
	ds_read2_b32 v[18:19], v103 offset0:4 offset1:5
	ds_read2_b32 v[20:21], v103 offset0:6 offset1:7
	v_add_u32_e32 v56, 0x2040, v103
	ds_read2_b32 v[22:23], v56 offset0:0 offset1:1
	ds_read2_b32 v[24:25], v56 offset0:2 offset1:3
	ds_read2_b32 v[26:27], v56 offset0:4 offset1:5
	ds_read2_b32 v[28:29], v56 offset0:6 offset1:7
	s_waitcnt vmcnt(7) lgkmcnt(4)
	v_fmamk_f32 v54, v5, 0x3a800000, v13
	v_rsq_f32_e32 v54, v54
	s_nop 0
	v_mul_f32_e32 v14, v14, v54
	v_mul_f32_e32 v15, v15, v54
	v_mul_f32_e32 v16, v16, v54
	v_mul_f32_e32 v17, v17, v54
	v_mul_f32_e32 v18, v18, v54
	v_mul_f32_e32 v19, v19, v54
	v_mul_f32_e32 v20, v20, v54
	v_mul_f32_e32 v21, v21, v54
	v_max_f32_e32 v14, 0, v14
	v_max_f32_e32 v15, 0, v15
	v_max_f32_e32 v16, 0, v16
	v_max_f32_e32 v17, 0, v17
	v_max_f32_e32 v18, 0, v18
	v_max_f32_e32 v19, 0, v19
	v_max_f32_e32 v20, 0, v20
	v_max_f32_e32 v21, 0, v21
	v_pk_mul_f32 v[14:15], v[14:15], v[14:15]
	v_pk_mul_f32 v[16:17], v[16:17], v[16:17]
	v_pk_mul_f32 v[18:19], v[18:19], v[18:19]
	v_pk_mul_f32 v[20:21], v[20:21], v[20:21]
	v_and_b32_sdwa v46, v14, v59 dst_sel:DWORD dst_unused:UNUSED_PAD src0_sel:WORD_1 src1_sel:DWORD
	v_and_b32_sdwa v47, v15, v59 dst_sel:DWORD dst_unused:UNUSED_PAD src0_sel:WORD_1 src1_sel:DWORD
	v_and_b32_sdwa v48, v16, v59 dst_sel:DWORD dst_unused:UNUSED_PAD src0_sel:WORD_1 src1_sel:DWORD
	v_and_b32_sdwa v49, v17, v59 dst_sel:DWORD dst_unused:UNUSED_PAD src0_sel:WORD_1 src1_sel:DWORD
	v_and_b32_sdwa v50, v18, v59 dst_sel:DWORD dst_unused:UNUSED_PAD src0_sel:WORD_1 src1_sel:DWORD
	v_and_b32_sdwa v51, v19, v59 dst_sel:DWORD dst_unused:UNUSED_PAD src0_sel:WORD_1 src1_sel:DWORD
	v_and_b32_sdwa v52, v20, v59 dst_sel:DWORD dst_unused:UNUSED_PAD src0_sel:WORD_1 src1_sel:DWORD
	v_and_b32_sdwa v53, v21, v59 dst_sel:DWORD dst_unused:UNUSED_PAD src0_sel:WORD_1 src1_sel:DWORD
	v_add3_u32 v14, v14, v46, s24
	v_add3_u32 v15, v15, v47, s24
	v_add3_u32 v16, v16, v48, s24
	v_add3_u32 v17, v17, v49, s24
	v_add3_u32 v18, v18, v50, s24
	v_add3_u32 v19, v19, v51, s24
	v_add3_u32 v20, v20, v52, s24
	v_add3_u32 v21, v21, v53, s24
	v_and_b32_e32 v15, 0xffff0000, v15
	v_and_b32_e32 v17, 0xffff0000, v17
	v_and_b32_e32 v19, 0xffff0000, v19
	v_and_b32_e32 v21, 0xffff0000, v21
	v_or_b32_sdwa v60, v15, v14 dst_sel:DWORD dst_unused:UNUSED_PAD src0_sel:DWORD src1_sel:WORD_1
	v_or_b32_sdwa v61, v17, v16 dst_sel:DWORD dst_unused:UNUSED_PAD src0_sel:DWORD src1_sel:WORD_1
	v_or_b32_sdwa v62, v19, v18 dst_sel:DWORD dst_unused:UNUSED_PAD src0_sel:DWORD src1_sel:WORD_1
	v_or_b32_sdwa v63, v21, v20 dst_sel:DWORD dst_unused:UNUSED_PAD src0_sel:DWORD src1_sel:WORD_1
	global_store_dwordx4 v4, v[60:63], s[56:57]
	v_add_u32_e32 v55, 0x4080, v103
	ds_read2_b32 v[30:31], v55 offset0:0 offset1:1
	ds_read2_b32 v[32:33], v55 offset0:2 offset1:3
	ds_read2_b32 v[34:35], v55 offset0:4 offset1:5
	ds_read2_b32 v[36:37], v55 offset0:6 offset1:7
	v_add_u32_e32 v56, 0x60c0, v103
	ds_read2_b32 v[38:39], v56 offset0:0 offset1:1
	ds_read2_b32 v[40:41], v56 offset0:2 offset1:3
	ds_read2_b32 v[42:43], v56 offset0:4 offset1:5
	ds_read2_b32 v[44:45], v56 offset0:6 offset1:7
	s_waitcnt vmcnt(7) lgkmcnt(8)
	v_fmamk_f32 v54, v6, 0x3a800000, v13
	v_rsq_f32_e32 v54, v54
	v_add_u32_e32 v58, 0x20000, v4
	v_mul_f32_e32 v22, v22, v54
	v_mul_f32_e32 v23, v23, v54
	v_mul_f32_e32 v24, v24, v54
	v_mul_f32_e32 v25, v25, v54
	v_mul_f32_e32 v26, v26, v54
	v_mul_f32_e32 v27, v27, v54
	v_mul_f32_e32 v28, v28, v54
	v_mul_f32_e32 v29, v29, v54
	v_max_f32_e32 v22, 0, v22
	v_max_f32_e32 v23, 0, v23
	v_max_f32_e32 v24, 0, v24
	v_max_f32_e32 v25, 0, v25
	v_max_f32_e32 v26, 0, v26
	v_max_f32_e32 v27, 0, v27
	v_max_f32_e32 v28, 0, v28
	v_max_f32_e32 v29, 0, v29
	v_pk_mul_f32 v[22:23], v[22:23], v[22:23]
	v_pk_mul_f32 v[24:25], v[24:25], v[24:25]
	v_pk_mul_f32 v[26:27], v[26:27], v[26:27]
	v_pk_mul_f32 v[28:29], v[28:29], v[28:29]
	v_and_b32_sdwa v46, v22, v59 dst_sel:DWORD dst_unused:UNUSED_PAD src0_sel:WORD_1 src1_sel:DWORD
	v_and_b32_sdwa v47, v23, v59 dst_sel:DWORD dst_unused:UNUSED_PAD src0_sel:WORD_1 src1_sel:DWORD
	v_and_b32_sdwa v48, v24, v59 dst_sel:DWORD dst_unused:UNUSED_PAD src0_sel:WORD_1 src1_sel:DWORD
	v_and_b32_sdwa v49, v25, v59 dst_sel:DWORD dst_unused:UNUSED_PAD src0_sel:WORD_1 src1_sel:DWORD
	v_and_b32_sdwa v50, v26, v59 dst_sel:DWORD dst_unused:UNUSED_PAD src0_sel:WORD_1 src1_sel:DWORD
	v_and_b32_sdwa v51, v27, v59 dst_sel:DWORD dst_unused:UNUSED_PAD src0_sel:WORD_1 src1_sel:DWORD
	v_and_b32_sdwa v52, v28, v59 dst_sel:DWORD dst_unused:UNUSED_PAD src0_sel:WORD_1 src1_sel:DWORD
	v_and_b32_sdwa v53, v29, v59 dst_sel:DWORD dst_unused:UNUSED_PAD src0_sel:WORD_1 src1_sel:DWORD
	v_add3_u32 v22, v22, v46, s24
	v_add3_u32 v23, v23, v47, s24
	v_add3_u32 v24, v24, v48, s24
	v_add3_u32 v25, v25, v49, s24
	v_add3_u32 v26, v26, v50, s24
	v_add3_u32 v27, v27, v51, s24
	v_add3_u32 v28, v28, v52, s24
	v_add3_u32 v29, v29, v53, s24
	v_and_b32_e32 v23, 0xffff0000, v23
	v_and_b32_e32 v25, 0xffff0000, v25
	v_and_b32_e32 v27, 0xffff0000, v27
	v_and_b32_e32 v29, 0xffff0000, v29
	v_or_b32_sdwa v76, v23, v22 dst_sel:DWORD dst_unused:UNUSED_PAD src0_sel:DWORD src1_sel:WORD_1
	v_or_b32_sdwa v77, v25, v24 dst_sel:DWORD dst_unused:UNUSED_PAD src0_sel:DWORD src1_sel:WORD_1
	v_or_b32_sdwa v78, v27, v26 dst_sel:DWORD dst_unused:UNUSED_PAD src0_sel:DWORD src1_sel:WORD_1
	v_or_b32_sdwa v79, v29, v28 dst_sel:DWORD dst_unused:UNUSED_PAD src0_sel:DWORD src1_sel:WORD_1
	global_store_dwordx4 v58, v[76:79], s[56:57]
	s_waitcnt vmcnt(7) lgkmcnt(4)
	v_fmamk_f32 v54, v7, 0x3a800000, v13
	v_rsq_f32_e32 v54, v54
	v_add_u32_e32 v57, 0x40000, v4
	v_mul_f32_e32 v30, v30, v54
	v_mul_f32_e32 v31, v31, v54
	v_mul_f32_e32 v32, v32, v54
	v_mul_f32_e32 v33, v33, v54
	v_mul_f32_e32 v34, v34, v54
	v_mul_f32_e32 v35, v35, v54
	v_mul_f32_e32 v36, v36, v54
	v_mul_f32_e32 v37, v37, v54
	v_max_f32_e32 v30, 0, v30
	v_max_f32_e32 v31, 0, v31
	v_max_f32_e32 v32, 0, v32
	v_max_f32_e32 v33, 0, v33
	v_max_f32_e32 v34, 0, v34
	v_max_f32_e32 v35, 0, v35
	v_max_f32_e32 v36, 0, v36
	v_max_f32_e32 v37, 0, v37
	v_pk_mul_f32 v[30:31], v[30:31], v[30:31]
	v_pk_mul_f32 v[32:33], v[32:33], v[32:33]
	v_pk_mul_f32 v[34:35], v[34:35], v[34:35]
	v_pk_mul_f32 v[36:37], v[36:37], v[36:37]
	v_and_b32_sdwa v46, v30, v59 dst_sel:DWORD dst_unused:UNUSED_PAD src0_sel:WORD_1 src1_sel:DWORD
	v_and_b32_sdwa v47, v31, v59 dst_sel:DWORD dst_unused:UNUSED_PAD src0_sel:WORD_1 src1_sel:DWORD
	v_and_b32_sdwa v48, v32, v59 dst_sel:DWORD dst_unused:UNUSED_PAD src0_sel:WORD_1 src1_sel:DWORD
	v_and_b32_sdwa v49, v33, v59 dst_sel:DWORD dst_unused:UNUSED_PAD src0_sel:WORD_1 src1_sel:DWORD
	v_and_b32_sdwa v50, v34, v59 dst_sel:DWORD dst_unused:UNUSED_PAD src0_sel:WORD_1 src1_sel:DWORD
	v_and_b32_sdwa v51, v35, v59 dst_sel:DWORD dst_unused:UNUSED_PAD src0_sel:WORD_1 src1_sel:DWORD
	v_and_b32_sdwa v52, v36, v59 dst_sel:DWORD dst_unused:UNUSED_PAD src0_sel:WORD_1 src1_sel:DWORD
	v_and_b32_sdwa v53, v37, v59 dst_sel:DWORD dst_unused:UNUSED_PAD src0_sel:WORD_1 src1_sel:DWORD
	v_add3_u32 v30, v30, v46, s24
	v_add3_u32 v31, v31, v47, s24
	v_add3_u32 v32, v32, v48, s24
	v_add3_u32 v33, v33, v49, s24
	v_add3_u32 v34, v34, v50, s24
	v_add3_u32 v35, v35, v51, s24
	v_add3_u32 v36, v36, v52, s24
	v_add3_u32 v37, v37, v53, s24
	v_and_b32_e32 v31, 0xffff0000, v31
	v_and_b32_e32 v33, 0xffff0000, v33
	v_and_b32_e32 v35, 0xffff0000, v35
	v_and_b32_e32 v37, 0xffff0000, v37
	v_or_b32_sdwa v60, v31, v30 dst_sel:DWORD dst_unused:UNUSED_PAD src0_sel:DWORD src1_sel:WORD_1
	v_or_b32_sdwa v61, v33, v32 dst_sel:DWORD dst_unused:UNUSED_PAD src0_sel:DWORD src1_sel:WORD_1
	v_or_b32_sdwa v62, v35, v34 dst_sel:DWORD dst_unused:UNUSED_PAD src0_sel:DWORD src1_sel:WORD_1
	v_or_b32_sdwa v63, v37, v36 dst_sel:DWORD dst_unused:UNUSED_PAD src0_sel:DWORD src1_sel:WORD_1
	global_store_dwordx4 v57, v[60:63], s[56:57]
	v_add_u32_e32 v55, 0x8100, v103
	ds_read2_b32 v[14:15], v55 offset0:0 offset1:1
	ds_read2_b32 v[16:17], v55 offset0:2 offset1:3
	ds_read2_b32 v[18:19], v55 offset0:4 offset1:5
	ds_read2_b32 v[20:21], v55 offset0:6 offset1:7
	v_add_u32_e32 v56, 0xa140, v103
	ds_read2_b32 v[22:23], v56 offset0:0 offset1:1
	ds_read2_b32 v[24:25], v56 offset0:2 offset1:3
	ds_read2_b32 v[26:27], v56 offset0:4 offset1:5
	ds_read2_b32 v[28:29], v56 offset0:6 offset1:7
	s_waitcnt vmcnt(7) lgkmcnt(8)
	v_fmamk_f32 v54, v8, 0x3a800000, v13
	v_rsq_f32_e32 v54, v54
	v_add_u32_e32 v58, 0x60000, v4
	v_mul_f32_e32 v38, v38, v54
	v_mul_f32_e32 v39, v39, v54
	v_mul_f32_e32 v40, v40, v54
	v_mul_f32_e32 v41, v41, v54
	v_mul_f32_e32 v42, v42, v54
	v_mul_f32_e32 v43, v43, v54
	v_mul_f32_e32 v44, v44, v54
	v_mul_f32_e32 v45, v45, v54
	v_max_f32_e32 v38, 0, v38
	v_max_f32_e32 v39, 0, v39
	v_max_f32_e32 v40, 0, v40
	v_max_f32_e32 v41, 0, v41
	v_max_f32_e32 v42, 0, v42
	v_max_f32_e32 v43, 0, v43
	v_max_f32_e32 v44, 0, v44
	v_max_f32_e32 v45, 0, v45
	v_pk_mul_f32 v[38:39], v[38:39], v[38:39]
	v_pk_mul_f32 v[40:41], v[40:41], v[40:41]
	v_pk_mul_f32 v[42:43], v[42:43], v[42:43]
	v_pk_mul_f32 v[44:45], v[44:45], v[44:45]
	v_and_b32_sdwa v46, v38, v59 dst_sel:DWORD dst_unused:UNUSED_PAD src0_sel:WORD_1 src1_sel:DWORD
	v_and_b32_sdwa v47, v39, v59 dst_sel:DWORD dst_unused:UNUSED_PAD src0_sel:WORD_1 src1_sel:DWORD
	v_and_b32_sdwa v48, v40, v59 dst_sel:DWORD dst_unused:UNUSED_PAD src0_sel:WORD_1 src1_sel:DWORD
	v_and_b32_sdwa v49, v41, v59 dst_sel:DWORD dst_unused:UNUSED_PAD src0_sel:WORD_1 src1_sel:DWORD
	v_and_b32_sdwa v50, v42, v59 dst_sel:DWORD dst_unused:UNUSED_PAD src0_sel:WORD_1 src1_sel:DWORD
	v_and_b32_sdwa v51, v43, v59 dst_sel:DWORD dst_unused:UNUSED_PAD src0_sel:WORD_1 src1_sel:DWORD
	v_and_b32_sdwa v52, v44, v59 dst_sel:DWORD dst_unused:UNUSED_PAD src0_sel:WORD_1 src1_sel:DWORD
	v_and_b32_sdwa v53, v45, v59 dst_sel:DWORD dst_unused:UNUSED_PAD src0_sel:WORD_1 src1_sel:DWORD
	v_add3_u32 v38, v38, v46, s24
	v_add3_u32 v39, v39, v47, s24
	v_add3_u32 v40, v40, v48, s24
	v_add3_u32 v41, v41, v49, s24
	v_add3_u32 v42, v42, v50, s24
	v_add3_u32 v43, v43, v51, s24
	v_add3_u32 v44, v44, v52, s24
	v_add3_u32 v45, v45, v53, s24
	v_and_b32_e32 v39, 0xffff0000, v39
	v_and_b32_e32 v41, 0xffff0000, v41
	v_and_b32_e32 v43, 0xffff0000, v43
	v_and_b32_e32 v45, 0xffff0000, v45
	v_or_b32_sdwa v76, v39, v38 dst_sel:DWORD dst_unused:UNUSED_PAD src0_sel:DWORD src1_sel:WORD_1
	v_or_b32_sdwa v77, v41, v40 dst_sel:DWORD dst_unused:UNUSED_PAD src0_sel:DWORD src1_sel:WORD_1
	v_or_b32_sdwa v78, v43, v42 dst_sel:DWORD dst_unused:UNUSED_PAD src0_sel:DWORD src1_sel:WORD_1
	v_or_b32_sdwa v79, v45, v44 dst_sel:DWORD dst_unused:UNUSED_PAD src0_sel:DWORD src1_sel:WORD_1
	global_store_dwordx4 v58, v[76:79], s[56:57]
	s_waitcnt vmcnt(7) lgkmcnt(4)
	v_fmamk_f32 v54, v9, 0x3a800000, v13
	v_rsq_f32_e32 v54, v54
	v_add_u32_e32 v57, 0x80000, v4
	v_mul_f32_e32 v14, v14, v54
	v_mul_f32_e32 v15, v15, v54
	v_mul_f32_e32 v16, v16, v54
	v_mul_f32_e32 v17, v17, v54
	v_mul_f32_e32 v18, v18, v54
	v_mul_f32_e32 v19, v19, v54
	v_mul_f32_e32 v20, v20, v54
	v_mul_f32_e32 v21, v21, v54
	v_max_f32_e32 v14, 0, v14
	v_max_f32_e32 v15, 0, v15
	v_max_f32_e32 v16, 0, v16
	v_max_f32_e32 v17, 0, v17
	v_max_f32_e32 v18, 0, v18
	v_max_f32_e32 v19, 0, v19
	v_max_f32_e32 v20, 0, v20
	v_max_f32_e32 v21, 0, v21
	v_pk_mul_f32 v[14:15], v[14:15], v[14:15]
	v_pk_mul_f32 v[16:17], v[16:17], v[16:17]
	v_pk_mul_f32 v[18:19], v[18:19], v[18:19]
	v_pk_mul_f32 v[20:21], v[20:21], v[20:21]
	v_and_b32_sdwa v46, v14, v59 dst_sel:DWORD dst_unused:UNUSED_PAD src0_sel:WORD_1 src1_sel:DWORD
	v_and_b32_sdwa v47, v15, v59 dst_sel:DWORD dst_unused:UNUSED_PAD src0_sel:WORD_1 src1_sel:DWORD
	v_and_b32_sdwa v48, v16, v59 dst_sel:DWORD dst_unused:UNUSED_PAD src0_sel:WORD_1 src1_sel:DWORD
	v_and_b32_sdwa v49, v17, v59 dst_sel:DWORD dst_unused:UNUSED_PAD src0_sel:WORD_1 src1_sel:DWORD
	v_and_b32_sdwa v50, v18, v59 dst_sel:DWORD dst_unused:UNUSED_PAD src0_sel:WORD_1 src1_sel:DWORD
	v_and_b32_sdwa v51, v19, v59 dst_sel:DWORD dst_unused:UNUSED_PAD src0_sel:WORD_1 src1_sel:DWORD
	v_and_b32_sdwa v52, v20, v59 dst_sel:DWORD dst_unused:UNUSED_PAD src0_sel:WORD_1 src1_sel:DWORD
	v_and_b32_sdwa v53, v21, v59 dst_sel:DWORD dst_unused:UNUSED_PAD src0_sel:WORD_1 src1_sel:DWORD
	v_add3_u32 v14, v14, v46, s24
	v_add3_u32 v15, v15, v47, s24
	v_add3_u32 v16, v16, v48, s24
	v_add3_u32 v17, v17, v49, s24
	v_add3_u32 v18, v18, v50, s24
	v_add3_u32 v19, v19, v51, s24
	v_add3_u32 v20, v20, v52, s24
	v_add3_u32 v21, v21, v53, s24
	v_and_b32_e32 v15, 0xffff0000, v15
	v_and_b32_e32 v17, 0xffff0000, v17
	v_and_b32_e32 v19, 0xffff0000, v19
	v_and_b32_e32 v21, 0xffff0000, v21
	v_or_b32_sdwa v60, v15, v14 dst_sel:DWORD dst_unused:UNUSED_PAD src0_sel:DWORD src1_sel:WORD_1
	v_or_b32_sdwa v61, v17, v16 dst_sel:DWORD dst_unused:UNUSED_PAD src0_sel:DWORD src1_sel:WORD_1
	v_or_b32_sdwa v62, v19, v18 dst_sel:DWORD dst_unused:UNUSED_PAD src0_sel:DWORD src1_sel:WORD_1
	v_or_b32_sdwa v63, v21, v20 dst_sel:DWORD dst_unused:UNUSED_PAD src0_sel:DWORD src1_sel:WORD_1
	global_store_dwordx4 v57, v[60:63], s[56:57]
	v_add_u32_e32 v55, 0xc180, v103
	ds_read2_b32 v[30:31], v55 offset0:0 offset1:1
	ds_read2_b32 v[32:33], v55 offset0:2 offset1:3
	ds_read2_b32 v[34:35], v55 offset0:4 offset1:5
	ds_read2_b32 v[36:37], v55 offset0:6 offset1:7
	v_add_u32_e32 v56, 0xe1c0, v103
	ds_read2_b32 v[38:39], v56 offset0:0 offset1:1
	ds_read2_b32 v[40:41], v56 offset0:2 offset1:3
	ds_read2_b32 v[42:43], v56 offset0:4 offset1:5
	ds_read2_b32 v[44:45], v56 offset0:6 offset1:7
	s_waitcnt vmcnt(7) lgkmcnt(8)
	v_fmamk_f32 v54, v10, 0x3a800000, v13
	v_rsq_f32_e32 v54, v54
	v_add_u32_e32 v58, 0xa0000, v4
	v_mul_f32_e32 v22, v22, v54
	v_mul_f32_e32 v23, v23, v54
	v_mul_f32_e32 v24, v24, v54
	v_mul_f32_e32 v25, v25, v54
	v_mul_f32_e32 v26, v26, v54
	v_mul_f32_e32 v27, v27, v54
	v_mul_f32_e32 v28, v28, v54
	v_mul_f32_e32 v29, v29, v54
	v_max_f32_e32 v22, 0, v22
	v_max_f32_e32 v23, 0, v23
	v_max_f32_e32 v24, 0, v24
	v_max_f32_e32 v25, 0, v25
	v_max_f32_e32 v26, 0, v26
	v_max_f32_e32 v27, 0, v27
	v_max_f32_e32 v28, 0, v28
	v_max_f32_e32 v29, 0, v29
	v_pk_mul_f32 v[22:23], v[22:23], v[22:23]
	v_pk_mul_f32 v[24:25], v[24:25], v[24:25]
	v_pk_mul_f32 v[26:27], v[26:27], v[26:27]
	v_pk_mul_f32 v[28:29], v[28:29], v[28:29]
	v_and_b32_sdwa v46, v22, v59 dst_sel:DWORD dst_unused:UNUSED_PAD src0_sel:WORD_1 src1_sel:DWORD
	v_and_b32_sdwa v47, v23, v59 dst_sel:DWORD dst_unused:UNUSED_PAD src0_sel:WORD_1 src1_sel:DWORD
	v_and_b32_sdwa v48, v24, v59 dst_sel:DWORD dst_unused:UNUSED_PAD src0_sel:WORD_1 src1_sel:DWORD
	v_and_b32_sdwa v49, v25, v59 dst_sel:DWORD dst_unused:UNUSED_PAD src0_sel:WORD_1 src1_sel:DWORD
	v_and_b32_sdwa v50, v26, v59 dst_sel:DWORD dst_unused:UNUSED_PAD src0_sel:WORD_1 src1_sel:DWORD
	v_and_b32_sdwa v51, v27, v59 dst_sel:DWORD dst_unused:UNUSED_PAD src0_sel:WORD_1 src1_sel:DWORD
	v_and_b32_sdwa v52, v28, v59 dst_sel:DWORD dst_unused:UNUSED_PAD src0_sel:WORD_1 src1_sel:DWORD
	v_and_b32_sdwa v53, v29, v59 dst_sel:DWORD dst_unused:UNUSED_PAD src0_sel:WORD_1 src1_sel:DWORD
	v_add3_u32 v22, v22, v46, s24
	v_add3_u32 v23, v23, v47, s24
	v_add3_u32 v24, v24, v48, s24
	v_add3_u32 v25, v25, v49, s24
	v_add3_u32 v26, v26, v50, s24
	v_add3_u32 v27, v27, v51, s24
	v_add3_u32 v28, v28, v52, s24
	v_add3_u32 v29, v29, v53, s24
	v_and_b32_e32 v23, 0xffff0000, v23
	v_and_b32_e32 v25, 0xffff0000, v25
	v_and_b32_e32 v27, 0xffff0000, v27
	v_and_b32_e32 v29, 0xffff0000, v29
	v_or_b32_sdwa v76, v23, v22 dst_sel:DWORD dst_unused:UNUSED_PAD src0_sel:DWORD src1_sel:WORD_1
	v_or_b32_sdwa v77, v25, v24 dst_sel:DWORD dst_unused:UNUSED_PAD src0_sel:DWORD src1_sel:WORD_1
	v_or_b32_sdwa v78, v27, v26 dst_sel:DWORD dst_unused:UNUSED_PAD src0_sel:DWORD src1_sel:WORD_1
	v_or_b32_sdwa v79, v29, v28 dst_sel:DWORD dst_unused:UNUSED_PAD src0_sel:DWORD src1_sel:WORD_1
	global_store_dwordx4 v58, v[76:79], s[56:57]
	s_waitcnt vmcnt(7) lgkmcnt(4)
	v_fmamk_f32 v54, v11, 0x3a800000, v13
	v_rsq_f32_e32 v54, v54
	v_add_u32_e32 v57, 0xc0000, v4
	v_mul_f32_e32 v30, v30, v54
	v_mul_f32_e32 v31, v31, v54
	v_mul_f32_e32 v32, v32, v54
	v_mul_f32_e32 v33, v33, v54
	v_mul_f32_e32 v34, v34, v54
	v_mul_f32_e32 v35, v35, v54
	v_mul_f32_e32 v36, v36, v54
	v_mul_f32_e32 v37, v37, v54
	v_max_f32_e32 v30, 0, v30
	v_max_f32_e32 v31, 0, v31
	v_max_f32_e32 v32, 0, v32
	v_max_f32_e32 v33, 0, v33
	v_max_f32_e32 v34, 0, v34
	v_max_f32_e32 v35, 0, v35
	v_max_f32_e32 v36, 0, v36
	v_max_f32_e32 v37, 0, v37
	v_pk_mul_f32 v[30:31], v[30:31], v[30:31]
	v_pk_mul_f32 v[32:33], v[32:33], v[32:33]
	v_pk_mul_f32 v[34:35], v[34:35], v[34:35]
	v_pk_mul_f32 v[36:37], v[36:37], v[36:37]
	v_and_b32_sdwa v46, v30, v59 dst_sel:DWORD dst_unused:UNUSED_PAD src0_sel:WORD_1 src1_sel:DWORD
	v_and_b32_sdwa v47, v31, v59 dst_sel:DWORD dst_unused:UNUSED_PAD src0_sel:WORD_1 src1_sel:DWORD
	v_and_b32_sdwa v48, v32, v59 dst_sel:DWORD dst_unused:UNUSED_PAD src0_sel:WORD_1 src1_sel:DWORD
	v_and_b32_sdwa v49, v33, v59 dst_sel:DWORD dst_unused:UNUSED_PAD src0_sel:WORD_1 src1_sel:DWORD
	v_and_b32_sdwa v50, v34, v59 dst_sel:DWORD dst_unused:UNUSED_PAD src0_sel:WORD_1 src1_sel:DWORD
	v_and_b32_sdwa v51, v35, v59 dst_sel:DWORD dst_unused:UNUSED_PAD src0_sel:WORD_1 src1_sel:DWORD
	v_and_b32_sdwa v52, v36, v59 dst_sel:DWORD dst_unused:UNUSED_PAD src0_sel:WORD_1 src1_sel:DWORD
	v_and_b32_sdwa v53, v37, v59 dst_sel:DWORD dst_unused:UNUSED_PAD src0_sel:WORD_1 src1_sel:DWORD
	v_add3_u32 v30, v30, v46, s24
	v_add3_u32 v31, v31, v47, s24
	v_add3_u32 v32, v32, v48, s24
	v_add3_u32 v33, v33, v49, s24
	v_add3_u32 v34, v34, v50, s24
	v_add3_u32 v35, v35, v51, s24
	v_add3_u32 v36, v36, v52, s24
	v_add3_u32 v37, v37, v53, s24
	v_and_b32_e32 v31, 0xffff0000, v31
	v_and_b32_e32 v33, 0xffff0000, v33
	v_and_b32_e32 v35, 0xffff0000, v35
	v_and_b32_e32 v37, 0xffff0000, v37
	v_or_b32_sdwa v60, v31, v30 dst_sel:DWORD dst_unused:UNUSED_PAD src0_sel:DWORD src1_sel:WORD_1
	v_or_b32_sdwa v61, v33, v32 dst_sel:DWORD dst_unused:UNUSED_PAD src0_sel:DWORD src1_sel:WORD_1
	v_or_b32_sdwa v62, v35, v34 dst_sel:DWORD dst_unused:UNUSED_PAD src0_sel:DWORD src1_sel:WORD_1
	v_or_b32_sdwa v63, v37, v36 dst_sel:DWORD dst_unused:UNUSED_PAD src0_sel:DWORD src1_sel:WORD_1
	global_store_dwordx4 v57, v[60:63], s[56:57]
	s_waitcnt vmcnt(7) lgkmcnt(0)
	v_fmamk_f32 v54, v12, 0x3a800000, v13
	v_rsq_f32_e32 v54, v54
	v_add_u32_e32 v58, 0xe0000, v4
	v_mul_f32_e32 v38, v38, v54
	v_mul_f32_e32 v39, v39, v54
	v_mul_f32_e32 v40, v40, v54
	v_mul_f32_e32 v41, v41, v54
	v_mul_f32_e32 v42, v42, v54
	v_mul_f32_e32 v43, v43, v54
	v_mul_f32_e32 v44, v44, v54
	v_mul_f32_e32 v45, v45, v54
	v_max_f32_e32 v38, 0, v38
	v_max_f32_e32 v39, 0, v39
	v_max_f32_e32 v40, 0, v40
	v_max_f32_e32 v41, 0, v41
	v_max_f32_e32 v42, 0, v42
	v_max_f32_e32 v43, 0, v43
	v_max_f32_e32 v44, 0, v44
	v_max_f32_e32 v45, 0, v45
	v_pk_mul_f32 v[38:39], v[38:39], v[38:39]
	v_pk_mul_f32 v[40:41], v[40:41], v[40:41]
	v_pk_mul_f32 v[42:43], v[42:43], v[42:43]
	v_pk_mul_f32 v[44:45], v[44:45], v[44:45]
	v_and_b32_sdwa v46, v38, v59 dst_sel:DWORD dst_unused:UNUSED_PAD src0_sel:WORD_1 src1_sel:DWORD
	v_and_b32_sdwa v47, v39, v59 dst_sel:DWORD dst_unused:UNUSED_PAD src0_sel:WORD_1 src1_sel:DWORD
	v_and_b32_sdwa v48, v40, v59 dst_sel:DWORD dst_unused:UNUSED_PAD src0_sel:WORD_1 src1_sel:DWORD
	v_and_b32_sdwa v49, v41, v59 dst_sel:DWORD dst_unused:UNUSED_PAD src0_sel:WORD_1 src1_sel:DWORD
	v_and_b32_sdwa v50, v42, v59 dst_sel:DWORD dst_unused:UNUSED_PAD src0_sel:WORD_1 src1_sel:DWORD
	v_and_b32_sdwa v51, v43, v59 dst_sel:DWORD dst_unused:UNUSED_PAD src0_sel:WORD_1 src1_sel:DWORD
	v_and_b32_sdwa v52, v44, v59 dst_sel:DWORD dst_unused:UNUSED_PAD src0_sel:WORD_1 src1_sel:DWORD
	v_and_b32_sdwa v53, v45, v59 dst_sel:DWORD dst_unused:UNUSED_PAD src0_sel:WORD_1 src1_sel:DWORD
	v_add3_u32 v38, v38, v46, s24
	v_add3_u32 v39, v39, v47, s24
	v_add3_u32 v40, v40, v48, s24
	v_add3_u32 v41, v41, v49, s24
	v_add3_u32 v42, v42, v50, s24
	v_add3_u32 v43, v43, v51, s24
	v_add3_u32 v44, v44, v52, s24
	v_add3_u32 v45, v45, v53, s24
	v_and_b32_e32 v39, 0xffff0000, v39
	v_and_b32_e32 v41, 0xffff0000, v41
	v_and_b32_e32 v43, 0xffff0000, v43
	v_and_b32_e32 v45, 0xffff0000, v45
	v_or_b32_sdwa v76, v39, v38 dst_sel:DWORD dst_unused:UNUSED_PAD src0_sel:DWORD src1_sel:WORD_1
	v_or_b32_sdwa v77, v41, v40 dst_sel:DWORD dst_unused:UNUSED_PAD src0_sel:DWORD src1_sel:WORD_1
	v_or_b32_sdwa v78, v43, v42 dst_sel:DWORD dst_unused:UNUSED_PAD src0_sel:DWORD src1_sel:WORD_1
	v_or_b32_sdwa v79, v45, v44 dst_sel:DWORD dst_unused:UNUSED_PAD src0_sel:DWORD src1_sel:WORD_1
	global_store_dwordx4 v58, v[76:79], s[56:57]
	s_cmpk_lt_u32 s12, 0x400
	s_barrier
	s_cbranch_scc1 .LBB0_590
